# v23: v16 with s_setprio 0 kept in front of each load segment so the 8-byte ds_reads start 8-byte aligned
# speedup vs baseline: 1.0032x; 1.0032x over previous
; #define PG8_STAGE(bufoff, gbase, voff) do { _Pragma("unroll") for (int _i = 0; _i < 2; ++_i) \
;         __builtin_amdgcn_global_load_lds((const unsigned*)((const char*)(gbase) + (voff)[_i]), (PG8_LAS unsigned*)(lds + (bufoff) + ldsw + _i * 8192), 16, 0, 0); } while (0)
; #define PG8_LDA(dst, b, h) do { _Pragma("unroll") for (int m = 0; m < 4; ++m) _Pragma("unroll") for (int k = 0; k < 2; ++k) dst[m][k] = *(const PG8_LAS bf16x8*)(lds + PG8_SA(b, h) + aoff + m * 2048 + k * 1024); } while (0)
; #define PG8_LDB(dst, b, h) do { _Pragma("unroll") for (int n = 0; n < 2; ++n) _Pragma("unroll") for (int k = 0; k < 2; ++k) dst[n][k] = *(const PG8_LAS bf16x8*)(lds + PG8_SB(b, h) + boff + n * 2048 + k * 1024); } while (0)
; #define PG8_MMA(ai, bj, At, Bt) do { __builtin_amdgcn_s_setprio(1); _Pragma("unroll") for (int m = 0; m < 4; ++m) _Pragma("unroll") for (int n = 0; n < 2; ++n) _Pragma("unroll") for (int k = 0; k < 2; ++k) \
;         acc[ai][bj][m][n] = __builtin_amdgcn_mfma_f32_16x16x32_bf16(Bt[n][k], At[m][k], acc[ai][bj][m][n], 0, 0, 0); __builtin_amdgcn_s_setprio(0); } while (0)
; #define PG8_WAIT_V(n) asm volatile("s_waitcnt vmcnt(" #n ")" ::: "memory")
; #define PG8_WAIT_L(n) asm volatile("s_waitcnt lgkmcnt(" #n ")" ::: "memory")
; #define PG8_BAR __builtin_amdgcn_s_barrier()
; #define PG8_SCHED __builtin_amdgcn_sched_barrier(0)
; template <class Epi, class Sched, bool ALIGN_EPI = false, bool SP2 = false>
; __device__ __forceinline__ void gemm_phase(PG8_LAS unsigned char* lds, const Gemm g, const Sched& S, const Epi& E) {
;     ...
;             PG8_LDB(B0, 0, 0); PG8_LDB(B1, 0, 1); PG8_SCHED; PG8_LDA(At, 0, 0); PG8_STAGE(PG8_SA(1, 1), a1 + hstep, voffA);
;             PG8_WAIT_V(8); PG8_WAIT_L(0); PG8_BAR; PG8_MMA(0, 0, At, B0); PG8_MMA(0, 1, At, B1); PG8_BAR; PG8_SCHED;
;             PG8_LDA(At, 0, 1); PG8_STAGE(PG8_SB(0, 0), b2, voffB); PG8_STAGE(PG8_SB(0, 1), b2 + hstep, voffB); PG8_STAGE(PG8_SA(0, 0), a2, voffA);
;             PG8_WAIT_V(8); PG8_WAIT_L(0); PG8_BAR; PG8_MMA(1, 0, At, B0); PG8_MMA(1, 1, At, B1); PG8_BAR; PG8_SCHED;
.LBB0_816:
	s_setprio 0
	ds_read_b128 v[142:145], v198
	ds_read_b128 v[146:149], v198 offset:1024
	ds_read_b128 v[154:157], v198 offset:2048
	ds_read_b128 v[158:161], v198 offset:3072
	ds_read_b128 v[162:165], v198 offset:16384
	ds_read_b128 v[166:169], v198 offset:17408
	ds_read_b128 v[170:173], v198 offset:18432
	ds_read_b128 v[174:177], v198 offset:19456
	ds_read_b128 v[178:181], v153
	ds_read_b128 v[182:185], v153 offset:1024
	ds_read_b128 v[186:189], v153 offset:2048
	ds_read_b128 v[190:193], v153 offset:3072
	ds_read_b128 v[194:197], v153 offset:4096
	ds_read_b128 v[214:217], v153 offset:5120
	ds_read_b128 v[218:221], v153 offset:6144
	ds_read_b128 v[234:237], v153 offset:7168
	s_add_u32 s0, s50, 0xfff00080
	s_addc_u32 s1, s51, -1
	s_add_i32 s61, 0, 0x10000
	s_cmp_eq_u32 s60, 60
	s_cselect_b32 s27, s47, s1
	s_cselect_b32 s26, s46, s0
	s_cselect_b32 s1, s49, s45
	s_cselect_b32 s0, s48, s43
	s_add_i32 s64, 0, 0x14000
	s_add_u32 s100, s50, 0xfff00000
	s_addc_u32 s101, s51, -1
	s_mov_b32 m0, s54
	s_nop 0
	global_load_lds_dwordx4 v136, s[100:101]
	s_mov_b32 m0, s55
	s_nop 0
	global_load_lds_dwordx4 v134, s[100:101]
	s_add_i32 m0, s9, 0xc000
	s_nop 0
	global_load_lds_dwordx4 v138, s[50:51]
	s_add_i32 m0, s9, 0xe000
	s_nop 0
	global_load_lds_dwordx4 v140, s[50:51]
	s_nop 0
	s_setprio 1
	s_waitcnt vmcnt(8)
	s_waitcnt lgkmcnt(0)
	s_barrier
	v_mfma_f32_16x16x32_bf16 v[128:131], v[142:145], v[178:181], v[128:131]
	v_mfma_f32_16x16x32_bf16 v[128:131], v[146:149], v[182:185], v[128:131]
	v_mfma_f32_16x16x32_bf16 v[124:127], v[154:157], v[178:181], v[124:127]
	v_mfma_f32_16x16x32_bf16 v[124:127], v[158:161], v[182:185], v[124:127]
	v_mfma_f32_16x16x32_bf16 v[108:111], v[154:157], v[186:189], v[108:111]
	v_mfma_f32_16x16x32_bf16 v[108:111], v[158:161], v[190:193], v[108:111]
	v_mfma_f32_16x16x32_bf16 v[116:119], v[142:145], v[186:189], v[116:119]
	v_mfma_f32_16x16x32_bf16 v[116:119], v[146:149], v[190:193], v[116:119]
	v_mfma_f32_16x16x32_bf16 v[100:103], v[142:145], v[194:197], v[100:103]
	v_mfma_f32_16x16x32_bf16 v[100:103], v[146:149], v[214:217], v[100:103]
	v_mfma_f32_16x16x32_bf16 v[92:95], v[154:157], v[194:197], v[92:95]
	v_mfma_f32_16x16x32_bf16 v[92:95], v[158:161], v[214:217], v[92:95]
	v_mfma_f32_16x16x32_bf16 v[76:79], v[154:157], v[218:221], v[76:79]
	v_mfma_f32_16x16x32_bf16 v[76:79], v[158:161], v[234:237], v[76:79]
	v_mfma_f32_16x16x32_bf16 v[84:87], v[142:145], v[218:221], v[84:87]
	v_mfma_f32_16x16x32_bf16 v[84:87], v[146:149], v[234:237], v[84:87]
	s_setprio 0
	s_setprio 1
	v_mfma_f32_16x16x32_bf16 v[120:123], v[162:165], v[178:181], v[120:123]
	v_mfma_f32_16x16x32_bf16 v[120:123], v[166:169], v[182:185], v[120:123]
	v_mfma_f32_16x16x32_bf16 v[112:115], v[170:173], v[178:181], v[112:115]
	v_mfma_f32_16x16x32_bf16 v[112:115], v[174:177], v[182:185], v[112:115]
	v_mfma_f32_16x16x32_bf16 v[96:99], v[170:173], v[186:189], v[96:99]
	v_mfma_f32_16x16x32_bf16 v[96:99], v[174:177], v[190:193], v[96:99]
	v_mfma_f32_16x16x32_bf16 v[104:107], v[162:165], v[186:189], v[104:107]
	v_mfma_f32_16x16x32_bf16 v[104:107], v[166:169], v[190:193], v[104:107]
	v_mfma_f32_16x16x32_bf16 v[88:91], v[162:165], v[194:197], v[88:91]
	v_mfma_f32_16x16x32_bf16 v[88:91], v[166:169], v[214:217], v[88:91]
	v_mfma_f32_16x16x32_bf16 v[80:83], v[170:173], v[194:197], v[80:83]
	v_mfma_f32_16x16x32_bf16 v[80:83], v[174:177], v[214:217], v[80:83]
	v_mfma_f32_16x16x32_bf16 v[68:71], v[170:173], v[218:221], v[68:71]
	v_mfma_f32_16x16x32_bf16 v[68:71], v[174:177], v[234:237], v[68:71]
	v_mfma_f32_16x16x32_bf16 v[72:75], v[162:165], v[218:221], v[72:75]
	v_mfma_f32_16x16x32_bf16 v[72:75], v[166:169], v[234:237], v[72:75]
	s_barrier
	s_setprio 0
	ds_read_b128 v[178:181], v153 offset:16384
	ds_read_b128 v[182:185], v153 offset:17408
	ds_read_b128 v[186:189], v153 offset:18432
	ds_read_b128 v[190:193], v153 offset:19456
	ds_read_b128 v[194:197], v153 offset:20480
	ds_read_b128 v[214:217], v153 offset:21504
	ds_read_b128 v[218:221], v153 offset:22528
	ds_read_b128 v[234:237], v153 offset:23552
	s_add_i32 s61, s61, s8
	s_mov_b32 m0, s61
	s_nop 0
	global_load_lds_dwordx4 v2, s[0:1]
	s_add_i32 m0, s61, 0x2000
	s_add_u32 s62, s0, 0x100000
	s_addc_u32 s63, s1, 0
	s_add_i32 s61, s64, s8
	global_load_lds_dwordx4 v132, s[0:1]
	s_mov_b32 m0, s61
	s_nop 0
	global_load_lds_dwordx4 v2, s[62:63]
	s_add_i32 m0, s61, 0x2000
	s_nop 0
	global_load_lds_dwordx4 v132, s[62:63]
	s_setprio 1
	s_waitcnt vmcnt(6)
	s_waitcnt lgkmcnt(0)
	s_barrier
	v_mfma_f32_16x16x32_bf16 v[64:67], v[142:145], v[178:181], v[64:67]
	v_mfma_f32_16x16x32_bf16 v[64:67], v[146:149], v[182:185], v[64:67]
	v_mfma_f32_16x16x32_bf16 v[60:63], v[154:157], v[178:181], v[60:63]
	v_mfma_f32_16x16x32_bf16 v[60:63], v[158:161], v[182:185], v[60:63]
	v_mfma_f32_16x16x32_bf16 v[44:47], v[154:157], v[186:189], v[44:47]
	v_mfma_f32_16x16x32_bf16 v[44:47], v[158:161], v[190:193], v[44:47]
	v_mfma_f32_16x16x32_bf16 v[52:55], v[142:145], v[186:189], v[52:55]
	v_mfma_f32_16x16x32_bf16 v[52:55], v[146:149], v[190:193], v[52:55]
	v_mfma_f32_16x16x32_bf16 v[36:39], v[142:145], v[194:197], v[36:39]
	v_mfma_f32_16x16x32_bf16 v[36:39], v[146:149], v[214:217], v[36:39]
	v_mfma_f32_16x16x32_bf16 v[28:31], v[154:157], v[194:197], v[28:31]
	v_mfma_f32_16x16x32_bf16 v[28:31], v[158:161], v[214:217], v[28:31]
	v_mfma_f32_16x16x32_bf16 v[12:15], v[154:157], v[218:221], v[12:15]
	v_mfma_f32_16x16x32_bf16 v[12:15], v[158:161], v[234:237], v[12:15]
	v_mfma_f32_16x16x32_bf16 v[16:19], v[142:145], v[218:221], v[16:19]
	v_mfma_f32_16x16x32_bf16 v[16:19], v[146:149], v[234:237], v[16:19]
	s_setprio 0
	s_setprio 1
	v_mfma_f32_16x16x32_bf16 v[56:59], v[162:165], v[178:181], v[56:59]
	v_mfma_f32_16x16x32_bf16 v[56:59], v[166:169], v[182:185], v[56:59]
	v_mfma_f32_16x16x32_bf16 v[48:51], v[170:173], v[178:181], v[48:51]
	v_mfma_f32_16x16x32_bf16 v[48:51], v[174:177], v[182:185], v[48:51]
	v_mfma_f32_16x16x32_bf16 v[32:35], v[170:173], v[186:189], v[32:35]
	v_mfma_f32_16x16x32_bf16 v[32:35], v[174:177], v[190:193], v[32:35]
	v_mfma_f32_16x16x32_bf16 v[40:43], v[162:165], v[186:189], v[40:43]
	v_mfma_f32_16x16x32_bf16 v[40:43], v[166:169], v[190:193], v[40:43]
	v_mfma_f32_16x16x32_bf16 v[24:27], v[162:165], v[194:197], v[24:27]
	v_mfma_f32_16x16x32_bf16 v[24:27], v[166:169], v[214:217], v[24:27]
	v_mfma_f32_16x16x32_bf16 v[20:23], v[170:173], v[194:197], v[20:23]
	v_mfma_f32_16x16x32_bf16 v[20:23], v[174:177], v[214:217], v[20:23]
	v_mfma_f32_16x16x32_bf16 v[4:7], v[170:173], v[218:221], v[4:7]
	v_mfma_f32_16x16x32_bf16 v[4:7], v[174:177], v[234:237], v[4:7]
	v_mfma_f32_16x16x32_bf16 v[8:11], v[162:165], v[218:221], v[8:11]
	v_mfma_f32_16x16x32_bf16 v[8:11], v[166:169], v[234:237], v[8:11]
	s_barrier
; #define PG8_STAGE(bufoff, gbase, voff) do { _Pragma("unroll") for (int _i = 0; _i < 2; ++_i) \
;         __builtin_amdgcn_global_load_lds((const unsigned*)((const char*)(gbase) + (voff)[_i]), (PG8_LAS unsigned*)(lds + (bufoff) + ldsw + _i * 8192), 16, 0, 0); } while (0)
; #define PG8_LDA(dst, b, h) do { _Pragma("unroll") for (int m = 0; m < 4; ++m) _Pragma("unroll") for (int k = 0; k < 2; ++k) dst[m][k] = *(const PG8_LAS bf16x8*)(lds + PG8_SA(b, h) + aoff + m * 2048 + k * 1024); } while (0)
; #define PG8_LDB(dst, b, h) do { _Pragma("unroll") for (int n = 0; n < 2; ++n) _Pragma("unroll") for (int k = 0; k < 2; ++k) dst[n][k] = *(const PG8_LAS bf16x8*)(lds + PG8_SB(b, h) + boff + n * 2048 + k * 1024); } while (0)
; #define PG8_MMA(ai, bj, At, Bt) do { __builtin_amdgcn_s_setprio(1); _Pragma("unroll") for (int m = 0; m < 4; ++m) _Pragma("unroll") for (int n = 0; n < 2; ++n) _Pragma("unroll") for (int k = 0; k < 2; ++k) \
;         acc[ai][bj][m][n] = __builtin_amdgcn_mfma_f32_16x16x32_bf16(Bt[n][k], At[m][k], acc[ai][bj][m][n], 0, 0, 0); __builtin_amdgcn_s_setprio(0); } while (0)
; #define PG8_WAIT_V(n) asm volatile("s_waitcnt vmcnt(" #n ")" ::: "memory")
; #define PG8_WAIT_L(n) asm volatile("s_waitcnt lgkmcnt(" #n ")" ::: "memory")
; #define PG8_BAR __builtin_amdgcn_s_barrier()
; #define PG8_SCHED __builtin_amdgcn_sched_barrier(0)
; template <class Epi, class Sched, bool ALIGN_EPI = false, bool SP2 = false>
; __device__ __forceinline__ void gemm_phase(PG8_LAS unsigned char* lds, const Gemm g, const Sched& S, const Epi& E) {
;     ...
;             PG8_LDB(B0, 1, 0); PG8_LDB(B1, 1, 1); PG8_SCHED; PG8_LDA(At, 1, 0); PG8_STAGE(PG8_SA(0, 1), a2 + hstep, voffA);
;             PG8_WAIT_V(8); PG8_WAIT_L(0); PG8_BAR; PG8_MMA(0, 0, At, B0); PG8_MMA(0, 1, At, B1); PG8_BAR; PG8_SCHED;
;             PG8_LDA(At, 1, 1); PG8_STAGE(PG8_SB(1, 0), b3, voffB); PG8_STAGE(PG8_SB(1, 1), b3 + hstep, voffB); PG8_STAGE(PG8_SA(1, 0), a3, voffA);
;             PG8_WAIT_V(8); PG8_WAIT_L(0); PG8_BAR; PG8_MMA(1, 0, At, B0); PG8_MMA(1, 1, At, B1); PG8_BAR; PG8_SCHED;
	s_setprio 0
	ds_read_b128 v[142:145], v198 offset:32768
	ds_read_b128 v[146:149], v198 offset:33792
	ds_read_b128 v[154:157], v198 offset:34816
	ds_read_b128 v[158:161], v198 offset:35840
	ds_read_b128 v[162:165], v198 offset:49152
	ds_read_b128 v[166:169], v198 offset:50176
	ds_read_b128 v[170:173], v198 offset:51200
	ds_read_b128 v[174:177], v198 offset:52224
	ds_read_b128 v[178:181], v153 offset:32768
	ds_read_b128 v[182:185], v153 offset:33792
	ds_read_b128 v[186:189], v153 offset:34816
	ds_read_b128 v[190:193], v153 offset:35840
	ds_read_b128 v[194:197], v153 offset:36864
	ds_read_b128 v[214:217], v153 offset:37888
	ds_read_b128 v[218:221], v153 offset:38912
	ds_read_b128 v[234:237], v153 offset:39936
	s_add_i32 s61, 0, 0x18000
	s_add_i32 s62, 0, 0x1c000
	s_mov_b32 m0, s9
	s_nop 0
	global_load_lds_dwordx4 v136, s[26:27]
	s_mov_b32 m0, s10
	s_nop 0
	global_load_lds_dwordx4 v134, s[26:27]
	s_add_u32 s26, s26, 0x100000
	s_addc_u32 s27, s27, 0
	s_mov_b32 m0, s11
	s_nop 0
	global_load_lds_dwordx4 v136, s[26:27]
	s_mov_b32 m0, s52
	s_nop 0
	global_load_lds_dwordx4 v134, s[26:27]
	s_nop 0
	s_setprio 1
	s_waitcnt vmcnt(8)
	s_waitcnt lgkmcnt(0)
	s_barrier
	v_mfma_f32_16x16x32_bf16 v[128:131], v[142:145], v[178:181], v[128:131]
	v_mfma_f32_16x16x32_bf16 v[128:131], v[146:149], v[182:185], v[128:131]
	v_mfma_f32_16x16x32_bf16 v[124:127], v[154:157], v[178:181], v[124:127]
	v_mfma_f32_16x16x32_bf16 v[124:127], v[158:161], v[182:185], v[124:127]
	v_mfma_f32_16x16x32_bf16 v[108:111], v[154:157], v[186:189], v[108:111]
	v_mfma_f32_16x16x32_bf16 v[108:111], v[158:161], v[190:193], v[108:111]
	v_mfma_f32_16x16x32_bf16 v[116:119], v[142:145], v[186:189], v[116:119]
	v_mfma_f32_16x16x32_bf16 v[116:119], v[146:149], v[190:193], v[116:119]
	v_mfma_f32_16x16x32_bf16 v[100:103], v[142:145], v[194:197], v[100:103]
	v_mfma_f32_16x16x32_bf16 v[100:103], v[146:149], v[214:217], v[100:103]
	v_mfma_f32_16x16x32_bf16 v[92:95], v[154:157], v[194:197], v[92:95]
	v_mfma_f32_16x16x32_bf16 v[92:95], v[158:161], v[214:217], v[92:95]
	v_mfma_f32_16x16x32_bf16 v[76:79], v[154:157], v[218:221], v[76:79]
	v_mfma_f32_16x16x32_bf16 v[76:79], v[158:161], v[234:237], v[76:79]
	v_mfma_f32_16x16x32_bf16 v[84:87], v[142:145], v[218:221], v[84:87]
	v_mfma_f32_16x16x32_bf16 v[84:87], v[146:149], v[234:237], v[84:87]
	s_setprio 0
	s_setprio 1
	v_mfma_f32_16x16x32_bf16 v[120:123], v[162:165], v[178:181], v[120:123]
	v_mfma_f32_16x16x32_bf16 v[120:123], v[166:169], v[182:185], v[120:123]
	v_mfma_f32_16x16x32_bf16 v[112:115], v[170:173], v[178:181], v[112:115]
	v_mfma_f32_16x16x32_bf16 v[112:115], v[174:177], v[182:185], v[112:115]
	v_mfma_f32_16x16x32_bf16 v[96:99], v[170:173], v[186:189], v[96:99]
	v_mfma_f32_16x16x32_bf16 v[96:99], v[174:177], v[190:193], v[96:99]
	v_mfma_f32_16x16x32_bf16 v[104:107], v[162:165], v[186:189], v[104:107]
	v_mfma_f32_16x16x32_bf16 v[104:107], v[166:169], v[190:193], v[104:107]
	v_mfma_f32_16x16x32_bf16 v[88:91], v[162:165], v[194:197], v[88:91]
	v_mfma_f32_16x16x32_bf16 v[88:91], v[166:169], v[214:217], v[88:91]
	v_mfma_f32_16x16x32_bf16 v[80:83], v[170:173], v[194:197], v[80:83]
	v_mfma_f32_16x16x32_bf16 v[80:83], v[174:177], v[214:217], v[80:83]
	v_mfma_f32_16x16x32_bf16 v[68:71], v[170:173], v[218:221], v[68:71]
	v_mfma_f32_16x16x32_bf16 v[68:71], v[174:177], v[234:237], v[68:71]
	v_mfma_f32_16x16x32_bf16 v[72:75], v[162:165], v[218:221], v[72:75]
	v_mfma_f32_16x16x32_bf16 v[72:75], v[166:169], v[234:237], v[72:75]
	s_barrier
	s_setprio 0
	ds_read_b128 v[178:181], v153 offset:49152
	ds_read_b128 v[182:185], v153 offset:50176
	ds_read_b128 v[186:189], v153 offset:51200
	ds_read_b128 v[190:193], v153 offset:52224
	ds_read_b128 v[194:197], v153 offset:53248
	ds_read_b128 v[214:217], v153 offset:54272
	ds_read_b128 v[218:221], v153 offset:55296
	ds_read_b128 v[234:237], v153 offset:56320
	s_add_i32 s26, s61, s8
	s_mov_b32 m0, s26
	s_add_u32 s0, s0, 0x80
	s_addc_u32 s1, s1, 0
	global_load_lds_dwordx4 v2, s[0:1]
	s_add_i32 m0, s26, 0x2000
	s_add_i32 s26, s62, s8
	global_load_lds_dwordx4 v132, s[0:1]
	s_add_u32 s0, s0, 0x100000
	s_addc_u32 s1, s1, 0
	s_mov_b32 m0, s26
	s_nop 0
	global_load_lds_dwordx4 v2, s[0:1]
	s_add_i32 m0, s26, 0x2000
	s_nop 0
	global_load_lds_dwordx4 v132, s[0:1]
	s_setprio 1
	s_waitcnt vmcnt(6)
	s_waitcnt lgkmcnt(0)
	s_barrier
	v_mfma_f32_16x16x32_bf16 v[64:67], v[142:145], v[178:181], v[64:67]
	v_mfma_f32_16x16x32_bf16 v[64:67], v[146:149], v[182:185], v[64:67]
	v_mfma_f32_16x16x32_bf16 v[60:63], v[154:157], v[178:181], v[60:63]
	v_mfma_f32_16x16x32_bf16 v[60:63], v[158:161], v[182:185], v[60:63]
	v_mfma_f32_16x16x32_bf16 v[44:47], v[154:157], v[186:189], v[44:47]
	v_mfma_f32_16x16x32_bf16 v[44:47], v[158:161], v[190:193], v[44:47]
	v_mfma_f32_16x16x32_bf16 v[52:55], v[142:145], v[186:189], v[52:55]
	v_mfma_f32_16x16x32_bf16 v[52:55], v[146:149], v[190:193], v[52:55]
	v_mfma_f32_16x16x32_bf16 v[36:39], v[142:145], v[194:197], v[36:39]
	v_mfma_f32_16x16x32_bf16 v[36:39], v[146:149], v[214:217], v[36:39]
	v_mfma_f32_16x16x32_bf16 v[28:31], v[154:157], v[194:197], v[28:31]
	v_mfma_f32_16x16x32_bf16 v[28:31], v[158:161], v[214:217], v[28:31]
	v_mfma_f32_16x16x32_bf16 v[12:15], v[154:157], v[218:221], v[12:15]
	v_mfma_f32_16x16x32_bf16 v[12:15], v[158:161], v[234:237], v[12:15]
	v_mfma_f32_16x16x32_bf16 v[16:19], v[142:145], v[218:221], v[16:19]
	v_mfma_f32_16x16x32_bf16 v[16:19], v[146:149], v[234:237], v[16:19]
	s_setprio 0
	s_setprio 1
	s_add_i32 s60, s60, 2
	s_add_u32 s50, s50, 0x100
	s_addc_u32 s51, s51, 0
	s_add_u32 s43, s43, 0x100
	s_addc_u32 s45, s45, 0
	s_nop 0
	v_mfma_f32_16x16x32_bf16 v[56:59], v[162:165], v[178:181], v[56:59]
	v_mfma_f32_16x16x32_bf16 v[56:59], v[166:169], v[182:185], v[56:59]
	v_mfma_f32_16x16x32_bf16 v[48:51], v[170:173], v[178:181], v[48:51]
	v_mfma_f32_16x16x32_bf16 v[48:51], v[174:177], v[182:185], v[48:51]
	v_mfma_f32_16x16x32_bf16 v[32:35], v[170:173], v[186:189], v[32:35]
	v_mfma_f32_16x16x32_bf16 v[32:35], v[174:177], v[190:193], v[32:35]
	v_mfma_f32_16x16x32_bf16 v[40:43], v[162:165], v[186:189], v[40:43]
	v_mfma_f32_16x16x32_bf16 v[40:43], v[166:169], v[190:193], v[40:43]
	v_mfma_f32_16x16x32_bf16 v[24:27], v[162:165], v[194:197], v[24:27]
	v_mfma_f32_16x16x32_bf16 v[24:27], v[166:169], v[214:217], v[24:27]
	v_mfma_f32_16x16x32_bf16 v[20:23], v[170:173], v[194:197], v[20:23]
	v_mfma_f32_16x16x32_bf16 v[20:23], v[174:177], v[214:217], v[20:23]
	v_mfma_f32_16x16x32_bf16 v[4:7], v[170:173], v[218:221], v[4:7]
	v_mfma_f32_16x16x32_bf16 v[4:7], v[174:177], v[234:237], v[4:7]
	v_mfma_f32_16x16x32_bf16 v[8:11], v[162:165], v[218:221], v[8:11]
	v_mfma_f32_16x16x32_bf16 v[8:11], v[166:169], v[234:237], v[8:11]
	s_barrier
	s_cmp_gt_u32 s60, 61
	s_cbranch_scc0 .LBB0_816
	s_setprio 0
	s_and_b64 vcc, exec, s[40:41]
	s_cbranch_vccz .LBB0_819
	s_barrier

; #define PG8_STAGE(bufoff, gbase, voff) do { _Pragma("unroll") for (int _i = 0; _i < 2; ++_i) \
;         __builtin_amdgcn_global_load_lds((const unsigned*)((const char*)(gbase) + (voff)[_i]), (PG8_LAS unsigned*)(lds + (bufoff) + ldsw + _i * 8192), 16, 0, 0); } while (0)
; #define PG8_LDA(dst, b, h) do { _Pragma("unroll") for (int m = 0; m < 4; ++m) _Pragma("unroll") for (int k = 0; k < 2; ++k) dst[m][k] = *(const PG8_LAS bf16x8*)(lds + PG8_SA(b, h) + aoff + m * 2048 + k * 1024); } while (0)
; #define PG8_LDB(dst, b, h) do { _Pragma("unroll") for (int n = 0; n < 2; ++n) _Pragma("unroll") for (int k = 0; k < 2; ++k) dst[n][k] = *(const PG8_LAS bf16x8*)(lds + PG8_SB(b, h) + boff + n * 2048 + k * 1024); } while (0)
; #define PG8_MMA(ai, bj, At, Bt) do { __builtin_amdgcn_s_setprio(1); _Pragma("unroll") for (int m = 0; m < 4; ++m) _Pragma("unroll") for (int n = 0; n < 2; ++n) _Pragma("unroll") for (int k = 0; k < 2; ++k) \
;         acc[ai][bj][m][n] = __builtin_amdgcn_mfma_f32_16x16x32_bf16(Bt[n][k], At[m][k], acc[ai][bj][m][n], 0, 0, 0); __builtin_amdgcn_s_setprio(0); } while (0)
; #define PG8_WAIT_V(n) asm volatile("s_waitcnt vmcnt(" #n ")" ::: "memory")
; #define PG8_WAIT_L(n) asm volatile("s_waitcnt lgkmcnt(" #n ")" ::: "memory")
; #define PG8_BAR __builtin_amdgcn_s_barrier()
; #define PG8_SCHED __builtin_amdgcn_sched_barrier(0)
; template <class Epi, class Sched, bool ALIGN_EPI = false, bool SP2 = false>
; __device__ __forceinline__ void gemm_phase(PG8_LAS unsigned char* lds, const Gemm g, const Sched& S, const Epi& E) {
;     ...
;             PG8_LDB(B0, 0, 0); PG8_LDB(B1, 0, 1); PG8_SCHED; PG8_LDA(At, 0, 0); PG8_STAGE(PG8_SA(1, 1), a1 + hstep, voffA);
;             PG8_WAIT_V(8); PG8_WAIT_L(0); PG8_BAR; PG8_MMA(0, 0, At, B0); PG8_MMA(0, 1, At, B1); PG8_BAR; PG8_SCHED;
;             PG8_LDA(At, 0, 1); PG8_STAGE(PG8_SB(0, 0), b2, voffB); PG8_STAGE(PG8_SB(0, 1), b2 + hstep, voffB); PG8_STAGE(PG8_SA(0, 0), a2, voffA);
;             PG8_WAIT_V(8); PG8_WAIT_L(0); PG8_BAR; PG8_MMA(1, 0, At, B0); PG8_MMA(1, 1, At, B1); PG8_BAR; PG8_SCHED;
.LBB0_1032:
	s_setprio 0
	ds_read_b128 v[146:149], v198
	ds_read_b128 v[150:153], v198 offset:1024
	ds_read_b128 v[154:157], v198 offset:2048
	ds_read_b128 v[158:161], v198 offset:3072
	ds_read_b128 v[162:165], v198 offset:16384
	ds_read_b128 v[166:169], v198 offset:17408
	ds_read_b128 v[170:173], v198 offset:18432
	ds_read_b128 v[174:177], v198 offset:19456
	ds_read_b128 v[178:181], v145
	ds_read_b128 v[182:185], v145 offset:1024
	ds_read_b128 v[186:189], v145 offset:2048
	ds_read_b128 v[190:193], v145 offset:3072
	ds_read_b128 v[194:197], v145 offset:4096
	ds_read_b128 v[214:217], v145 offset:5120
	ds_read_b128 v[218:221], v145 offset:6144
	ds_read_b128 v[234:237], v145 offset:7168
	s_add_u32 s0, s50, 0xfffc0080
	s_addc_u32 s1, s51, -1
	s_add_i32 s53, 0, 0x10000
	s_cmp_eq_u32 s52, 12
	s_cselect_b32 s27, s47, s1
	s_cselect_b32 s26, s46, s0
	s_cselect_b32 s1, s49, s45
	s_cselect_b32 s0, s48, s43
	s_add_i32 s64, 0, 0x14000
	s_add_u32 s100, s50, 0xfffc0000
	s_addc_u32 s101, s51, -1
	s_mov_b32 m0, s57
	s_nop 0
	global_load_lds_dwordx4 v136, s[100:101]
	s_mov_b32 m0, s58
	s_nop 0
	global_load_lds_dwordx4 v134, s[100:101]
	s_add_i32 m0, s37, 0xc000
	s_nop 0
	global_load_lds_dwordx4 v138, s[50:51]
	s_add_i32 m0, s37, 0xe000
	s_nop 0
	global_load_lds_dwordx4 v140, s[50:51]
	s_setprio 1
	s_waitcnt vmcnt(8)
	s_waitcnt lgkmcnt(0)
	s_barrier
	v_mfma_f32_16x16x32_bf16 v[128:131], v[146:149], v[178:181], v[128:131]
	v_mfma_f32_16x16x32_bf16 v[128:131], v[150:153], v[182:185], v[128:131]
	v_mfma_f32_16x16x32_bf16 v[124:127], v[154:157], v[178:181], v[124:127]
	v_mfma_f32_16x16x32_bf16 v[124:127], v[158:161], v[182:185], v[124:127]
	v_mfma_f32_16x16x32_bf16 v[116:119], v[154:157], v[186:189], v[116:119]
	v_mfma_f32_16x16x32_bf16 v[116:119], v[158:161], v[190:193], v[116:119]
	v_mfma_f32_16x16x32_bf16 v[120:123], v[146:149], v[186:189], v[120:123]
	v_mfma_f32_16x16x32_bf16 v[120:123], v[150:153], v[190:193], v[120:123]
	v_mfma_f32_16x16x32_bf16 v[104:107], v[146:149], v[194:197], v[104:107]
	v_mfma_f32_16x16x32_bf16 v[104:107], v[150:153], v[214:217], v[104:107]
	v_mfma_f32_16x16x32_bf16 v[100:103], v[154:157], v[194:197], v[100:103]
	v_mfma_f32_16x16x32_bf16 v[100:103], v[158:161], v[214:217], v[100:103]
	v_mfma_f32_16x16x32_bf16 v[84:87], v[154:157], v[218:221], v[84:87]
	v_mfma_f32_16x16x32_bf16 v[84:87], v[158:161], v[234:237], v[84:87]
	v_mfma_f32_16x16x32_bf16 v[88:91], v[146:149], v[218:221], v[88:91]
	v_mfma_f32_16x16x32_bf16 v[88:91], v[150:153], v[234:237], v[88:91]
	s_setprio 0
	s_setprio 1
	v_mfma_f32_16x16x32_bf16 v[112:115], v[162:165], v[178:181], v[112:115]
	v_mfma_f32_16x16x32_bf16 v[112:115], v[166:169], v[182:185], v[112:115]
	v_mfma_f32_16x16x32_bf16 v[108:111], v[170:173], v[178:181], v[108:111]
	v_mfma_f32_16x16x32_bf16 v[108:111], v[174:177], v[182:185], v[108:111]
	v_mfma_f32_16x16x32_bf16 v[92:95], v[170:173], v[186:189], v[92:95]
	v_mfma_f32_16x16x32_bf16 v[92:95], v[174:177], v[190:193], v[92:95]
	v_mfma_f32_16x16x32_bf16 v[96:99], v[162:165], v[186:189], v[96:99]
	v_mfma_f32_16x16x32_bf16 v[96:99], v[166:169], v[190:193], v[96:99]
	v_mfma_f32_16x16x32_bf16 v[80:83], v[162:165], v[194:197], v[80:83]
	v_mfma_f32_16x16x32_bf16 v[80:83], v[166:169], v[214:217], v[80:83]
	v_mfma_f32_16x16x32_bf16 v[76:79], v[170:173], v[194:197], v[76:79]
	v_mfma_f32_16x16x32_bf16 v[76:79], v[174:177], v[214:217], v[76:79]
	v_mfma_f32_16x16x32_bf16 v[68:71], v[170:173], v[218:221], v[68:71]
	v_mfma_f32_16x16x32_bf16 v[68:71], v[174:177], v[234:237], v[68:71]
	v_mfma_f32_16x16x32_bf16 v[72:75], v[162:165], v[218:221], v[72:75]
	v_mfma_f32_16x16x32_bf16 v[72:75], v[166:169], v[234:237], v[72:75]
	s_barrier
	s_setprio 0
	ds_read_b128 v[178:181], v145 offset:16384
	ds_read_b128 v[182:185], v145 offset:17408
	ds_read_b128 v[186:189], v145 offset:18432
	ds_read_b128 v[190:193], v145 offset:19456
	ds_read_b128 v[194:197], v145 offset:20480
	ds_read_b128 v[214:217], v145 offset:21504
	ds_read_b128 v[218:221], v145 offset:22528
	ds_read_b128 v[234:237], v145 offset:23552
	s_add_i32 s53, s53, s10
	s_mov_b32 m0, s53
	s_nop 0
	global_load_lds_dwordx4 v2, s[0:1]
	s_add_i32 m0, s53, 0x2000
	s_add_u32 s62, s0, 0x40000
	s_addc_u32 s63, s1, 0
	s_add_i32 s53, s64, s10
	global_load_lds_dwordx4 v132, s[0:1]
	s_mov_b32 m0, s53
	s_nop 0
	global_load_lds_dwordx4 v2, s[62:63]
	s_add_i32 m0, s53, 0x2000
	s_nop 0
	global_load_lds_dwordx4 v132, s[62:63]
	s_setprio 1
	s_waitcnt vmcnt(6)
	s_waitcnt lgkmcnt(0)
	s_barrier
	v_mfma_f32_16x16x32_bf16 v[64:67], v[146:149], v[178:181], v[64:67]
	v_mfma_f32_16x16x32_bf16 v[64:67], v[150:153], v[182:185], v[64:67]
	v_mfma_f32_16x16x32_bf16 v[60:63], v[154:157], v[178:181], v[60:63]
	v_mfma_f32_16x16x32_bf16 v[60:63], v[158:161], v[182:185], v[60:63]
	v_mfma_f32_16x16x32_bf16 v[52:55], v[154:157], v[186:189], v[52:55]
	v_mfma_f32_16x16x32_bf16 v[52:55], v[158:161], v[190:193], v[52:55]
	v_mfma_f32_16x16x32_bf16 v[56:59], v[146:149], v[186:189], v[56:59]
	v_mfma_f32_16x16x32_bf16 v[56:59], v[150:153], v[190:193], v[56:59]
	v_mfma_f32_16x16x32_bf16 v[40:43], v[146:149], v[194:197], v[40:43]
	v_mfma_f32_16x16x32_bf16 v[40:43], v[150:153], v[214:217], v[40:43]
	v_mfma_f32_16x16x32_bf16 v[36:39], v[154:157], v[194:197], v[36:39]
	v_mfma_f32_16x16x32_bf16 v[36:39], v[158:161], v[214:217], v[36:39]
	v_mfma_f32_16x16x32_bf16 v[20:23], v[154:157], v[218:221], v[20:23]
	v_mfma_f32_16x16x32_bf16 v[20:23], v[158:161], v[234:237], v[20:23]
	v_mfma_f32_16x16x32_bf16 v[24:27], v[146:149], v[218:221], v[24:27]
	v_mfma_f32_16x16x32_bf16 v[24:27], v[150:153], v[234:237], v[24:27]
	s_setprio 0
	s_setprio 1
	v_mfma_f32_16x16x32_bf16 v[48:51], v[162:165], v[178:181], v[48:51]
	v_mfma_f32_16x16x32_bf16 v[48:51], v[166:169], v[182:185], v[48:51]
	v_mfma_f32_16x16x32_bf16 v[44:47], v[170:173], v[178:181], v[44:47]
	v_mfma_f32_16x16x32_bf16 v[44:47], v[174:177], v[182:185], v[44:47]
	v_mfma_f32_16x16x32_bf16 v[28:31], v[170:173], v[186:189], v[28:31]
	v_mfma_f32_16x16x32_bf16 v[28:31], v[174:177], v[190:193], v[28:31]
	v_mfma_f32_16x16x32_bf16 v[32:35], v[162:165], v[186:189], v[32:35]
	v_mfma_f32_16x16x32_bf16 v[32:35], v[166:169], v[190:193], v[32:35]
	v_mfma_f32_16x16x32_bf16 v[16:19], v[162:165], v[194:197], v[16:19]
	v_mfma_f32_16x16x32_bf16 v[16:19], v[166:169], v[214:217], v[16:19]
	v_mfma_f32_16x16x32_bf16 v[12:15], v[170:173], v[194:197], v[12:15]
	v_mfma_f32_16x16x32_bf16 v[12:15], v[174:177], v[214:217], v[12:15]
	v_mfma_f32_16x16x32_bf16 v[4:7], v[170:173], v[218:221], v[4:7]
	v_mfma_f32_16x16x32_bf16 v[4:7], v[174:177], v[234:237], v[4:7]
	v_mfma_f32_16x16x32_bf16 v[8:11], v[162:165], v[218:221], v[8:11]
	v_mfma_f32_16x16x32_bf16 v[8:11], v[166:169], v[234:237], v[8:11]
	s_barrier
; #define PG8_STAGE(bufoff, gbase, voff) do { _Pragma("unroll") for (int _i = 0; _i < 2; ++_i) \
;         __builtin_amdgcn_global_load_lds((const unsigned*)((const char*)(gbase) + (voff)[_i]), (PG8_LAS unsigned*)(lds + (bufoff) + ldsw + _i * 8192), 16, 0, 0); } while (0)
; #define PG8_LDA(dst, b, h) do { _Pragma("unroll") for (int m = 0; m < 4; ++m) _Pragma("unroll") for (int k = 0; k < 2; ++k) dst[m][k] = *(const PG8_LAS bf16x8*)(lds + PG8_SA(b, h) + aoff + m * 2048 + k * 1024); } while (0)
; #define PG8_LDB(dst, b, h) do { _Pragma("unroll") for (int n = 0; n < 2; ++n) _Pragma("unroll") for (int k = 0; k < 2; ++k) dst[n][k] = *(const PG8_LAS bf16x8*)(lds + PG8_SB(b, h) + boff + n * 2048 + k * 1024); } while (0)
; #define PG8_MMA(ai, bj, At, Bt) do { __builtin_amdgcn_s_setprio(1); _Pragma("unroll") for (int m = 0; m < 4; ++m) _Pragma("unroll") for (int n = 0; n < 2; ++n) _Pragma("unroll") for (int k = 0; k < 2; ++k) \
;         acc[ai][bj][m][n] = __builtin_amdgcn_mfma_f32_16x16x32_bf16(Bt[n][k], At[m][k], acc[ai][bj][m][n], 0, 0, 0); __builtin_amdgcn_s_setprio(0); } while (0)
; #define PG8_WAIT_V(n) asm volatile("s_waitcnt vmcnt(" #n ")" ::: "memory")
; #define PG8_WAIT_L(n) asm volatile("s_waitcnt lgkmcnt(" #n ")" ::: "memory")
; #define PG8_BAR __builtin_amdgcn_s_barrier()
; #define PG8_SCHED __builtin_amdgcn_sched_barrier(0)
; template <class Epi, class Sched, bool ALIGN_EPI = false, bool SP2 = false>
; __device__ __forceinline__ void gemm_phase(PG8_LAS unsigned char* lds, const Gemm g, const Sched& S, const Epi& E) {
;     ...
;             PG8_LDB(B0, 1, 0); PG8_LDB(B1, 1, 1); PG8_SCHED; PG8_LDA(At, 1, 0); PG8_STAGE(PG8_SA(0, 1), a2 + hstep, voffA);
;             PG8_WAIT_V(8); PG8_WAIT_L(0); PG8_BAR; PG8_MMA(0, 0, At, B0); PG8_MMA(0, 1, At, B1); PG8_BAR; PG8_SCHED;
;             PG8_LDA(At, 1, 1); PG8_STAGE(PG8_SB(1, 0), b3, voffB); PG8_STAGE(PG8_SB(1, 1), b3 + hstep, voffB); PG8_STAGE(PG8_SA(1, 0), a3, voffA);
;             PG8_WAIT_V(8); PG8_WAIT_L(0); PG8_BAR; PG8_MMA(1, 0, At, B0); PG8_MMA(1, 1, At, B1); PG8_BAR; PG8_SCHED;
	s_setprio 0
	ds_read_b128 v[146:149], v198 offset:32768
	ds_read_b128 v[150:153], v198 offset:33792
	ds_read_b128 v[154:157], v198 offset:34816
	ds_read_b128 v[158:161], v198 offset:35840
	ds_read_b128 v[162:165], v198 offset:49152
	ds_read_b128 v[166:169], v198 offset:50176
	ds_read_b128 v[170:173], v198 offset:51200
	ds_read_b128 v[174:177], v198 offset:52224
	ds_read_b128 v[178:181], v145 offset:32768
	ds_read_b128 v[182:185], v145 offset:33792
	ds_read_b128 v[186:189], v145 offset:34816
	ds_read_b128 v[190:193], v145 offset:35840
	ds_read_b128 v[194:197], v145 offset:36864
	ds_read_b128 v[214:217], v145 offset:37888
	ds_read_b128 v[218:221], v145 offset:38912
	ds_read_b128 v[234:237], v145 offset:39936
	s_add_i32 s53, 0, 0x18000
	s_add_i32 s62, 0, 0x1c000
	s_mov_b32 m0, s37
	s_nop 0
	global_load_lds_dwordx4 v136, s[26:27]
	s_mov_b32 m0, s54
	s_nop 0
	global_load_lds_dwordx4 v134, s[26:27]
	s_add_u32 s26, s26, 0x40000
	s_addc_u32 s27, s27, 0
	s_mov_b32 m0, s55
	s_nop 0
	global_load_lds_dwordx4 v136, s[26:27]
	s_mov_b32 m0, s56
	s_nop 0
	global_load_lds_dwordx4 v134, s[26:27]
	s_nop 0
	s_setprio 1
	s_waitcnt vmcnt(8)
	s_waitcnt lgkmcnt(0)
	s_barrier
	v_mfma_f32_16x16x32_bf16 v[128:131], v[146:149], v[178:181], v[128:131]
	v_mfma_f32_16x16x32_bf16 v[128:131], v[150:153], v[182:185], v[128:131]
	v_mfma_f32_16x16x32_bf16 v[124:127], v[154:157], v[178:181], v[124:127]
	v_mfma_f32_16x16x32_bf16 v[124:127], v[158:161], v[182:185], v[124:127]
	v_mfma_f32_16x16x32_bf16 v[116:119], v[154:157], v[186:189], v[116:119]
	v_mfma_f32_16x16x32_bf16 v[116:119], v[158:161], v[190:193], v[116:119]
	v_mfma_f32_16x16x32_bf16 v[120:123], v[146:149], v[186:189], v[120:123]
	v_mfma_f32_16x16x32_bf16 v[120:123], v[150:153], v[190:193], v[120:123]
	v_mfma_f32_16x16x32_bf16 v[104:107], v[146:149], v[194:197], v[104:107]
	v_mfma_f32_16x16x32_bf16 v[104:107], v[150:153], v[214:217], v[104:107]
	v_mfma_f32_16x16x32_bf16 v[100:103], v[154:157], v[194:197], v[100:103]
	v_mfma_f32_16x16x32_bf16 v[100:103], v[158:161], v[214:217], v[100:103]
	v_mfma_f32_16x16x32_bf16 v[84:87], v[154:157], v[218:221], v[84:87]
	v_mfma_f32_16x16x32_bf16 v[84:87], v[158:161], v[234:237], v[84:87]
	v_mfma_f32_16x16x32_bf16 v[88:91], v[146:149], v[218:221], v[88:91]
	v_mfma_f32_16x16x32_bf16 v[88:91], v[150:153], v[234:237], v[88:91]
	s_setprio 0
	s_setprio 1
	v_mfma_f32_16x16x32_bf16 v[112:115], v[162:165], v[178:181], v[112:115]
	v_mfma_f32_16x16x32_bf16 v[112:115], v[166:169], v[182:185], v[112:115]
	v_mfma_f32_16x16x32_bf16 v[108:111], v[170:173], v[178:181], v[108:111]
	v_mfma_f32_16x16x32_bf16 v[108:111], v[174:177], v[182:185], v[108:111]
	v_mfma_f32_16x16x32_bf16 v[92:95], v[170:173], v[186:189], v[92:95]
	v_mfma_f32_16x16x32_bf16 v[92:95], v[174:177], v[190:193], v[92:95]
	v_mfma_f32_16x16x32_bf16 v[96:99], v[162:165], v[186:189], v[96:99]
	v_mfma_f32_16x16x32_bf16 v[96:99], v[166:169], v[190:193], v[96:99]
	v_mfma_f32_16x16x32_bf16 v[80:83], v[162:165], v[194:197], v[80:83]
	v_mfma_f32_16x16x32_bf16 v[80:83], v[166:169], v[214:217], v[80:83]
	v_mfma_f32_16x16x32_bf16 v[76:79], v[170:173], v[194:197], v[76:79]
	v_mfma_f32_16x16x32_bf16 v[76:79], v[174:177], v[214:217], v[76:79]
	v_mfma_f32_16x16x32_bf16 v[68:71], v[170:173], v[218:221], v[68:71]
	v_mfma_f32_16x16x32_bf16 v[68:71], v[174:177], v[234:237], v[68:71]
	v_mfma_f32_16x16x32_bf16 v[72:75], v[162:165], v[218:221], v[72:75]
	v_mfma_f32_16x16x32_bf16 v[72:75], v[166:169], v[234:237], v[72:75]
	s_barrier
	s_setprio 0
	ds_read_b128 v[178:181], v145 offset:49152
	ds_read_b128 v[182:185], v145 offset:50176
	ds_read_b128 v[186:189], v145 offset:51200
	ds_read_b128 v[190:193], v145 offset:52224
	ds_read_b128 v[194:197], v145 offset:53248
	ds_read_b128 v[214:217], v145 offset:54272
	ds_read_b128 v[218:221], v145 offset:55296
	ds_read_b128 v[234:237], v145 offset:56320
	s_add_i32 s26, s53, s10
	s_mov_b32 m0, s26
	s_add_u32 s0, s0, 0x80
	s_addc_u32 s1, s1, 0
	global_load_lds_dwordx4 v2, s[0:1]
	s_add_i32 m0, s26, 0x2000
	s_add_i32 s26, s62, s10
	global_load_lds_dwordx4 v132, s[0:1]
	s_add_u32 s0, s0, 0x40000
	s_addc_u32 s1, s1, 0
	s_mov_b32 m0, s26
	s_nop 0
	global_load_lds_dwordx4 v2, s[0:1]
	s_add_i32 m0, s26, 0x2000
	s_nop 0
	global_load_lds_dwordx4 v132, s[0:1]
	s_setprio 1
	s_waitcnt vmcnt(6)
	s_waitcnt lgkmcnt(0)
	s_barrier
	v_mfma_f32_16x16x32_bf16 v[64:67], v[146:149], v[178:181], v[64:67]
	v_mfma_f32_16x16x32_bf16 v[64:67], v[150:153], v[182:185], v[64:67]
	v_mfma_f32_16x16x32_bf16 v[60:63], v[154:157], v[178:181], v[60:63]
	v_mfma_f32_16x16x32_bf16 v[60:63], v[158:161], v[182:185], v[60:63]
	v_mfma_f32_16x16x32_bf16 v[52:55], v[154:157], v[186:189], v[52:55]
	v_mfma_f32_16x16x32_bf16 v[52:55], v[158:161], v[190:193], v[52:55]
	v_mfma_f32_16x16x32_bf16 v[56:59], v[146:149], v[186:189], v[56:59]
	v_mfma_f32_16x16x32_bf16 v[56:59], v[150:153], v[190:193], v[56:59]
	v_mfma_f32_16x16x32_bf16 v[40:43], v[146:149], v[194:197], v[40:43]
	v_mfma_f32_16x16x32_bf16 v[40:43], v[150:153], v[214:217], v[40:43]
	v_mfma_f32_16x16x32_bf16 v[36:39], v[154:157], v[194:197], v[36:39]
	v_mfma_f32_16x16x32_bf16 v[36:39], v[158:161], v[214:217], v[36:39]
	v_mfma_f32_16x16x32_bf16 v[20:23], v[154:157], v[218:221], v[20:23]
	v_mfma_f32_16x16x32_bf16 v[20:23], v[158:161], v[234:237], v[20:23]
	v_mfma_f32_16x16x32_bf16 v[24:27], v[146:149], v[218:221], v[24:27]
	v_mfma_f32_16x16x32_bf16 v[24:27], v[150:153], v[234:237], v[24:27]
	s_setprio 0
	s_setprio 1
	s_add_i32 s52, s52, 2
	s_add_u32 s50, s50, 0x100
	s_addc_u32 s51, s51, 0
	s_add_u32 s43, s43, 0x100
	s_addc_u32 s45, s45, 0
	s_nop 0
	v_mfma_f32_16x16x32_bf16 v[48:51], v[162:165], v[178:181], v[48:51]
	v_mfma_f32_16x16x32_bf16 v[48:51], v[166:169], v[182:185], v[48:51]
	v_mfma_f32_16x16x32_bf16 v[44:47], v[170:173], v[178:181], v[44:47]
	v_mfma_f32_16x16x32_bf16 v[44:47], v[174:177], v[182:185], v[44:47]
	v_mfma_f32_16x16x32_bf16 v[28:31], v[170:173], v[186:189], v[28:31]
	v_mfma_f32_16x16x32_bf16 v[28:31], v[174:177], v[190:193], v[28:31]
	v_mfma_f32_16x16x32_bf16 v[32:35], v[162:165], v[186:189], v[32:35]
	v_mfma_f32_16x16x32_bf16 v[32:35], v[166:169], v[190:193], v[32:35]
	v_mfma_f32_16x16x32_bf16 v[16:19], v[162:165], v[194:197], v[16:19]
	v_mfma_f32_16x16x32_bf16 v[16:19], v[166:169], v[214:217], v[16:19]
	v_mfma_f32_16x16x32_bf16 v[12:15], v[170:173], v[194:197], v[12:15]
	v_mfma_f32_16x16x32_bf16 v[12:15], v[174:177], v[214:217], v[12:15]
	v_mfma_f32_16x16x32_bf16 v[4:7], v[170:173], v[218:221], v[4:7]
	v_mfma_f32_16x16x32_bf16 v[4:7], v[174:177], v[234:237], v[4:7]
	v_mfma_f32_16x16x32_bf16 v[8:11], v[162:165], v[218:221], v[8:11]
	v_mfma_f32_16x16x32_bf16 v[8:11], v[166:169], v[234:237], v[8:11]
	s_barrier
	s_cmp_gt_u32 s52, 13
	s_cbranch_scc0 .LBB0_1032
	s_setprio 0
	s_and_b64 vcc, exec, s[40:41]
	s_cbranch_vccz .LBB0_1035
	s_barrier

; #define PG8_STAGE(bufoff, gbase, voff) do { _Pragma("unroll") for (int _i = 0; _i < 2; ++_i) \
;         __builtin_amdgcn_global_load_lds((const unsigned*)((const char*)(gbase) + (voff)[_i]), (PG8_LAS unsigned*)(lds + (bufoff) + ldsw + _i * 8192), 16, 0, 0); } while (0)
; #define PG8_LDA(dst, b, h) do { _Pragma("unroll") for (int m = 0; m < 4; ++m) _Pragma("unroll") for (int k = 0; k < 2; ++k) dst[m][k] = *(const PG8_LAS bf16x8*)(lds + PG8_SA(b, h) + aoff + m * 2048 + k * 1024); } while (0)
; #define PG8_LDB(dst, b, h) do { _Pragma("unroll") for (int n = 0; n < 2; ++n) _Pragma("unroll") for (int k = 0; k < 2; ++k) dst[n][k] = *(const PG8_LAS bf16x8*)(lds + PG8_SB(b, h) + boff + n * 2048 + k * 1024); } while (0)
; #define PG8_MMA(ai, bj, At, Bt) do { __builtin_amdgcn_s_setprio(1); _Pragma("unroll") for (int m = 0; m < 4; ++m) _Pragma("unroll") for (int n = 0; n < 2; ++n) _Pragma("unroll") for (int k = 0; k < 2; ++k) \
;         acc[ai][bj][m][n] = __builtin_amdgcn_mfma_f32_16x16x32_bf16(Bt[n][k], At[m][k], acc[ai][bj][m][n], 0, 0, 0); __builtin_amdgcn_s_setprio(0); } while (0)
; #define PG8_WAIT_V(n) asm volatile("s_waitcnt vmcnt(" #n ")" ::: "memory")
; #define PG8_WAIT_L(n) asm volatile("s_waitcnt lgkmcnt(" #n ")" ::: "memory")
; #define PG8_BAR __builtin_amdgcn_s_barrier()
; #define PG8_SCHED __builtin_amdgcn_sched_barrier(0)
; template <class Epi, class Sched, bool ALIGN_EPI = false, bool SP2 = false>
; __device__ __forceinline__ void gemm_phase(PG8_LAS unsigned char* lds, const Gemm g, const Sched& S, const Epi& E) {
;     ...
;             PG8_LDB(B0, 0, 0); PG8_LDB(B1, 0, 1); PG8_SCHED; PG8_LDA(At, 0, 0); PG8_STAGE(PG8_SA(1, 1), a1 + hstep, voffA);
;             PG8_WAIT_V(8); PG8_WAIT_L(0); PG8_BAR; PG8_MMA(0, 0, At, B0); PG8_MMA(0, 1, At, B1); PG8_BAR; PG8_SCHED;
;             PG8_LDA(At, 0, 1); PG8_STAGE(PG8_SB(0, 0), b2, voffB); PG8_STAGE(PG8_SB(0, 1), b2 + hstep, voffB); PG8_STAGE(PG8_SA(0, 0), a2, voffA);
;             PG8_WAIT_V(8); PG8_WAIT_L(0); PG8_BAR; PG8_MMA(1, 0, At, B0); PG8_MMA(1, 1, At, B1); PG8_BAR; PG8_SCHED;
.LBB0_1051:
	s_setprio 0
	ds_read_b128 v[84:87], v154
	ds_read_b128 v[88:91], v154 offset:1024
	ds_read_b128 v[162:165], v154 offset:2048
	ds_read_b128 v[166:169], v154 offset:3072
	ds_read_b128 v[170:173], v154 offset:16384
	ds_read_b128 v[174:177], v154 offset:17408
	ds_read_b128 v[178:181], v154 offset:18432
	ds_read_b128 v[182:185], v154 offset:19456
	ds_read_b128 v[186:189], v160
	ds_read_b128 v[190:193], v160 offset:1024
	ds_read_b128 v[194:197], v160 offset:2048
	ds_read_b128 v[214:217], v160 offset:3072
	ds_read_b128 v[218:221], v160 offset:4096
	ds_read_b128 v[234:237], v160 offset:5120
	ds_read_b128 v[238:241], v160 offset:6144
	ds_read_b128 v[242:245], v160 offset:7168
	s_add_u32 s0, s52, 0xfffe0080
	s_addc_u32 s1, s53, -1
	s_add_i32 s63, 0, 0x10000
	s_cmp_eq_u32 s62, 4
	s_cselect_b32 s27, s45, s1
	s_cselect_b32 s26, s58, s0
	s_cselect_b32 s1, s43, s61
	s_cselect_b32 s0, s59, s60
	s_add_i32 s66, 0, 0x14000
	s_add_u32 s100, s52, 0xfffe0000
	s_addc_u32 s101, s53, -1
	s_mov_b32 m0, s54
	s_nop 0
	global_load_lds_dwordx4 v140, s[100:101]
	s_mov_b32 m0, s55
	s_nop 0
	global_load_lds_dwordx4 v142, s[100:101]
	s_add_i32 m0, s10, 0xc000
	s_nop 0
	global_load_lds_dwordx4 v150, s[52:53]
	s_add_i32 m0, s10, 0xe000
	s_nop 0
	global_load_lds_dwordx4 v152, s[52:53]
	s_setprio 1
	s_waitcnt vmcnt(8)
	s_waitcnt lgkmcnt(0)
	s_barrier
	v_mfma_f32_16x16x32_bf16 v[136:139], v[84:87], v[186:189], v[136:139]
	v_mfma_f32_16x16x32_bf16 v[136:139], v[88:91], v[190:193], v[136:139]
	v_mfma_f32_16x16x32_bf16 v[132:135], v[162:165], v[186:189], v[132:135]
	v_mfma_f32_16x16x32_bf16 v[132:135], v[166:169], v[190:193], v[132:135]
	v_mfma_f32_16x16x32_bf16 v[120:123], v[162:165], v[194:197], v[120:123]
	v_mfma_f32_16x16x32_bf16 v[120:123], v[166:169], v[214:217], v[120:123]
	v_mfma_f32_16x16x32_bf16 v[128:131], v[84:87], v[194:197], v[128:131]
	v_mfma_f32_16x16x32_bf16 v[128:131], v[88:91], v[214:217], v[128:131]
	v_mfma_f32_16x16x32_bf16 v[104:107], v[84:87], v[218:221], v[104:107]
	v_mfma_f32_16x16x32_bf16 v[104:107], v[88:91], v[234:237], v[104:107]
	v_mfma_f32_16x16x32_bf16 v[100:103], v[162:165], v[218:221], v[100:103]
	v_mfma_f32_16x16x32_bf16 v[100:103], v[166:169], v[234:237], v[100:103]
	v_mfma_f32_16x16x32_bf16 v[76:79], v[162:165], v[238:241], v[76:79]
	v_mfma_f32_16x16x32_bf16 v[76:79], v[166:169], v[242:245], v[76:79]
	v_mfma_f32_16x16x32_bf16 v[80:83], v[84:87], v[238:241], v[80:83]
	v_mfma_f32_16x16x32_bf16 v[80:83], v[88:91], v[242:245], v[80:83]
	s_setprio 0
	s_setprio 1
	v_mfma_f32_16x16x32_bf16 v[124:127], v[170:173], v[186:189], v[124:127]
	v_mfma_f32_16x16x32_bf16 v[124:127], v[174:177], v[190:193], v[124:127]
	v_mfma_f32_16x16x32_bf16 v[116:119], v[178:181], v[186:189], v[116:119]
	v_mfma_f32_16x16x32_bf16 v[116:119], v[182:185], v[190:193], v[116:119]
	v_mfma_f32_16x16x32_bf16 v[108:111], v[178:181], v[194:197], v[108:111]
	v_mfma_f32_16x16x32_bf16 v[108:111], v[182:185], v[214:217], v[108:111]
	v_mfma_f32_16x16x32_bf16 v[112:115], v[170:173], v[194:197], v[112:115]
	v_mfma_f32_16x16x32_bf16 v[112:115], v[174:177], v[214:217], v[112:115]
	v_mfma_f32_16x16x32_bf16 v[96:99], v[170:173], v[218:221], v[96:99]
	v_mfma_f32_16x16x32_bf16 v[96:99], v[174:177], v[234:237], v[96:99]
	v_mfma_f32_16x16x32_bf16 v[92:95], v[178:181], v[218:221], v[92:95]
	v_mfma_f32_16x16x32_bf16 v[92:95], v[182:185], v[234:237], v[92:95]
	v_mfma_f32_16x16x32_bf16 v[68:71], v[178:181], v[238:241], v[68:71]
	v_mfma_f32_16x16x32_bf16 v[68:71], v[182:185], v[242:245], v[68:71]
	v_mfma_f32_16x16x32_bf16 v[72:75], v[170:173], v[238:241], v[72:75]
	v_mfma_f32_16x16x32_bf16 v[72:75], v[174:177], v[242:245], v[72:75]
	s_barrier
	s_setprio 0
	ds_read_b128 v[186:189], v160 offset:16384
	ds_read_b128 v[190:193], v160 offset:17408
	ds_read_b128 v[194:197], v160 offset:18432
	ds_read_b128 v[214:217], v160 offset:19456
	ds_read_b128 v[218:221], v160 offset:20480
	ds_read_b128 v[234:237], v160 offset:21504
	ds_read_b128 v[238:241], v160 offset:22528
	ds_read_b128 v[242:245], v160 offset:23552
	s_add_i32 s63, s63, s9
	s_mov_b32 m0, s63
	s_nop 0
	global_load_lds_dwordx4 v2, s[0:1]
	s_add_i32 m0, s63, 0x2000
	s_add_u32 s64, s0, 0x20000
	s_addc_u32 s65, s1, 0
	s_add_i32 s63, s66, s9
	global_load_lds_dwordx4 v144, s[0:1]
	s_mov_b32 m0, s63
	s_nop 0
	global_load_lds_dwordx4 v2, s[64:65]
	s_add_i32 m0, s63, 0x2000
	s_nop 0
	global_load_lds_dwordx4 v144, s[64:65]
	s_setprio 1
	s_waitcnt vmcnt(6)
	s_waitcnt lgkmcnt(0)
	s_barrier
	v_mfma_f32_16x16x32_bf16 v[64:67], v[84:87], v[186:189], v[64:67]
	v_mfma_f32_16x16x32_bf16 v[64:67], v[88:91], v[190:193], v[64:67]
	v_mfma_f32_16x16x32_bf16 v[60:63], v[162:165], v[186:189], v[60:63]
	v_mfma_f32_16x16x32_bf16 v[60:63], v[166:169], v[190:193], v[60:63]
	v_mfma_f32_16x16x32_bf16 v[44:47], v[162:165], v[194:197], v[44:47]
	v_mfma_f32_16x16x32_bf16 v[44:47], v[166:169], v[214:217], v[44:47]
	v_mfma_f32_16x16x32_bf16 v[48:51], v[84:87], v[194:197], v[48:51]
	v_mfma_f32_16x16x32_bf16 v[48:51], v[88:91], v[214:217], v[48:51]
	v_mfma_f32_16x16x32_bf16 v[32:35], v[84:87], v[218:221], v[32:35]
	v_mfma_f32_16x16x32_bf16 v[32:35], v[88:91], v[234:237], v[32:35]
	v_mfma_f32_16x16x32_bf16 v[28:31], v[162:165], v[218:221], v[28:31]
	v_mfma_f32_16x16x32_bf16 v[28:31], v[166:169], v[234:237], v[28:31]
	v_mfma_f32_16x16x32_bf16 v[12:15], v[162:165], v[238:241], v[12:15]
	v_mfma_f32_16x16x32_bf16 v[12:15], v[166:169], v[242:245], v[12:15]
	v_mfma_f32_16x16x32_bf16 v[16:19], v[84:87], v[238:241], v[16:19]
	v_mfma_f32_16x16x32_bf16 v[16:19], v[88:91], v[242:245], v[16:19]
	s_setprio 0
	s_setprio 1
	v_mfma_f32_16x16x32_bf16 v[56:59], v[170:173], v[186:189], v[56:59]
	v_mfma_f32_16x16x32_bf16 v[56:59], v[174:177], v[190:193], v[56:59]
	v_mfma_f32_16x16x32_bf16 v[52:55], v[178:181], v[186:189], v[52:55]
	v_mfma_f32_16x16x32_bf16 v[52:55], v[182:185], v[190:193], v[52:55]
	v_mfma_f32_16x16x32_bf16 v[36:39], v[178:181], v[194:197], v[36:39]
	v_mfma_f32_16x16x32_bf16 v[36:39], v[182:185], v[214:217], v[36:39]
	v_mfma_f32_16x16x32_bf16 v[40:43], v[170:173], v[194:197], v[40:43]
	v_mfma_f32_16x16x32_bf16 v[40:43], v[174:177], v[214:217], v[40:43]
	v_mfma_f32_16x16x32_bf16 v[24:27], v[170:173], v[218:221], v[24:27]
	v_mfma_f32_16x16x32_bf16 v[24:27], v[174:177], v[234:237], v[24:27]
	v_mfma_f32_16x16x32_bf16 v[20:23], v[178:181], v[218:221], v[20:23]
	v_mfma_f32_16x16x32_bf16 v[20:23], v[182:185], v[234:237], v[20:23]
	v_mfma_f32_16x16x32_bf16 v[4:7], v[178:181], v[238:241], v[4:7]
	v_mfma_f32_16x16x32_bf16 v[4:7], v[182:185], v[242:245], v[4:7]
	v_mfma_f32_16x16x32_bf16 v[8:11], v[170:173], v[238:241], v[8:11]
	v_mfma_f32_16x16x32_bf16 v[8:11], v[174:177], v[242:245], v[8:11]
	s_barrier
; #define PG8_STAGE(bufoff, gbase, voff) do { _Pragma("unroll") for (int _i = 0; _i < 2; ++_i) \
;         __builtin_amdgcn_global_load_lds((const unsigned*)((const char*)(gbase) + (voff)[_i]), (PG8_LAS unsigned*)(lds + (bufoff) + ldsw + _i * 8192), 16, 0, 0); } while (0)
; #define PG8_LDA(dst, b, h) do { _Pragma("unroll") for (int m = 0; m < 4; ++m) _Pragma("unroll") for (int k = 0; k < 2; ++k) dst[m][k] = *(const PG8_LAS bf16x8*)(lds + PG8_SA(b, h) + aoff + m * 2048 + k * 1024); } while (0)
; #define PG8_LDB(dst, b, h) do { _Pragma("unroll") for (int n = 0; n < 2; ++n) _Pragma("unroll") for (int k = 0; k < 2; ++k) dst[n][k] = *(const PG8_LAS bf16x8*)(lds + PG8_SB(b, h) + boff + n * 2048 + k * 1024); } while (0)
; #define PG8_MMA(ai, bj, At, Bt) do { __builtin_amdgcn_s_setprio(1); _Pragma("unroll") for (int m = 0; m < 4; ++m) _Pragma("unroll") for (int n = 0; n < 2; ++n) _Pragma("unroll") for (int k = 0; k < 2; ++k) \
;         acc[ai][bj][m][n] = __builtin_amdgcn_mfma_f32_16x16x32_bf16(Bt[n][k], At[m][k], acc[ai][bj][m][n], 0, 0, 0); __builtin_amdgcn_s_setprio(0); } while (0)
; #define PG8_WAIT_V(n) asm volatile("s_waitcnt vmcnt(" #n ")" ::: "memory")
; #define PG8_WAIT_L(n) asm volatile("s_waitcnt lgkmcnt(" #n ")" ::: "memory")
; #define PG8_BAR __builtin_amdgcn_s_barrier()
; #define PG8_SCHED __builtin_amdgcn_sched_barrier(0)
; template <class Epi, class Sched, bool ALIGN_EPI = false, bool SP2 = false>
; __device__ __forceinline__ void gemm_phase(PG8_LAS unsigned char* lds, const Gemm g, const Sched& S, const Epi& E) {
;     ...
;             PG8_LDB(B0, 1, 0); PG8_LDB(B1, 1, 1); PG8_SCHED; PG8_LDA(At, 1, 0); PG8_STAGE(PG8_SA(0, 1), a2 + hstep, voffA);
;             PG8_WAIT_V(8); PG8_WAIT_L(0); PG8_BAR; PG8_MMA(0, 0, At, B0); PG8_MMA(0, 1, At, B1); PG8_BAR; PG8_SCHED;
;             PG8_LDA(At, 1, 1); PG8_STAGE(PG8_SB(1, 0), b3, voffB); PG8_STAGE(PG8_SB(1, 1), b3 + hstep, voffB); PG8_STAGE(PG8_SA(1, 0), a3, voffA);
;             PG8_WAIT_V(8); PG8_WAIT_L(0); PG8_BAR; PG8_MMA(1, 0, At, B0); PG8_MMA(1, 1, At, B1); PG8_BAR; PG8_SCHED;
	s_setprio 0
	ds_read_b128 v[84:87], v154 offset:32768
	ds_read_b128 v[88:91], v154 offset:33792
	ds_read_b128 v[162:165], v154 offset:34816
	ds_read_b128 v[166:169], v154 offset:35840
	ds_read_b128 v[170:173], v154 offset:49152
	ds_read_b128 v[174:177], v154 offset:50176
	ds_read_b128 v[178:181], v154 offset:51200
	ds_read_b128 v[182:185], v154 offset:52224
	ds_read_b128 v[186:189], v160 offset:32768
	ds_read_b128 v[190:193], v160 offset:33792
	ds_read_b128 v[194:197], v160 offset:34816
	ds_read_b128 v[214:217], v160 offset:35840
	ds_read_b128 v[218:221], v160 offset:36864
	ds_read_b128 v[234:237], v160 offset:37888
	ds_read_b128 v[238:241], v160 offset:38912
	ds_read_b128 v[242:245], v160 offset:39936
	s_add_i32 s63, 0, 0x18000
	s_add_i32 s64, 0, 0x1c000
	s_mov_b32 m0, s10
	s_nop 0
	global_load_lds_dwordx4 v140, s[26:27]
	s_mov_b32 m0, s11
	s_nop 0
	global_load_lds_dwordx4 v142, s[26:27]
	s_add_u32 s26, s26, 0x20000
	s_addc_u32 s27, s27, 0
	s_mov_b32 m0, s25
	s_nop 0
	global_load_lds_dwordx4 v140, s[26:27]
	s_mov_b32 m0, s51
	s_nop 0
	global_load_lds_dwordx4 v142, s[26:27]
	s_nop 0
	s_setprio 1
	s_waitcnt vmcnt(8)
	s_waitcnt lgkmcnt(0)
	s_barrier
	v_mfma_f32_16x16x32_bf16 v[136:139], v[84:87], v[186:189], v[136:139]
	v_mfma_f32_16x16x32_bf16 v[136:139], v[88:91], v[190:193], v[136:139]
	v_mfma_f32_16x16x32_bf16 v[132:135], v[162:165], v[186:189], v[132:135]
	v_mfma_f32_16x16x32_bf16 v[132:135], v[166:169], v[190:193], v[132:135]
	v_mfma_f32_16x16x32_bf16 v[120:123], v[162:165], v[194:197], v[120:123]
	v_mfma_f32_16x16x32_bf16 v[120:123], v[166:169], v[214:217], v[120:123]
	v_mfma_f32_16x16x32_bf16 v[128:131], v[84:87], v[194:197], v[128:131]
	v_mfma_f32_16x16x32_bf16 v[128:131], v[88:91], v[214:217], v[128:131]
	v_mfma_f32_16x16x32_bf16 v[104:107], v[84:87], v[218:221], v[104:107]
	v_mfma_f32_16x16x32_bf16 v[104:107], v[88:91], v[234:237], v[104:107]
	v_mfma_f32_16x16x32_bf16 v[100:103], v[162:165], v[218:221], v[100:103]
	v_mfma_f32_16x16x32_bf16 v[100:103], v[166:169], v[234:237], v[100:103]
	v_mfma_f32_16x16x32_bf16 v[76:79], v[162:165], v[238:241], v[76:79]
	v_mfma_f32_16x16x32_bf16 v[76:79], v[166:169], v[242:245], v[76:79]
	v_mfma_f32_16x16x32_bf16 v[80:83], v[84:87], v[238:241], v[80:83]
	v_mfma_f32_16x16x32_bf16 v[80:83], v[88:91], v[242:245], v[80:83]
	s_setprio 0
	s_setprio 1
	v_mfma_f32_16x16x32_bf16 v[124:127], v[170:173], v[186:189], v[124:127]
	v_mfma_f32_16x16x32_bf16 v[124:127], v[174:177], v[190:193], v[124:127]
	v_mfma_f32_16x16x32_bf16 v[116:119], v[178:181], v[186:189], v[116:119]
	v_mfma_f32_16x16x32_bf16 v[116:119], v[182:185], v[190:193], v[116:119]
	v_mfma_f32_16x16x32_bf16 v[108:111], v[178:181], v[194:197], v[108:111]
	v_mfma_f32_16x16x32_bf16 v[108:111], v[182:185], v[214:217], v[108:111]
	v_mfma_f32_16x16x32_bf16 v[112:115], v[170:173], v[194:197], v[112:115]
	v_mfma_f32_16x16x32_bf16 v[112:115], v[174:177], v[214:217], v[112:115]
	v_mfma_f32_16x16x32_bf16 v[96:99], v[170:173], v[218:221], v[96:99]
	v_mfma_f32_16x16x32_bf16 v[96:99], v[174:177], v[234:237], v[96:99]
	v_mfma_f32_16x16x32_bf16 v[92:95], v[178:181], v[218:221], v[92:95]
	v_mfma_f32_16x16x32_bf16 v[92:95], v[182:185], v[234:237], v[92:95]
	v_mfma_f32_16x16x32_bf16 v[68:71], v[178:181], v[238:241], v[68:71]
	v_mfma_f32_16x16x32_bf16 v[68:71], v[182:185], v[242:245], v[68:71]
	v_mfma_f32_16x16x32_bf16 v[72:75], v[170:173], v[238:241], v[72:75]
	v_mfma_f32_16x16x32_bf16 v[72:75], v[174:177], v[242:245], v[72:75]
	s_barrier
	s_setprio 0
	ds_read_b128 v[186:189], v160 offset:49152
	ds_read_b128 v[190:193], v160 offset:50176
	ds_read_b128 v[194:197], v160 offset:51200
	ds_read_b128 v[214:217], v160 offset:52224
	ds_read_b128 v[218:221], v160 offset:53248
	ds_read_b128 v[234:237], v160 offset:54272
	ds_read_b128 v[238:241], v160 offset:55296
	ds_read_b128 v[242:245], v160 offset:56320
	s_add_i32 s26, s63, s9
	s_mov_b32 m0, s26
	s_add_u32 s0, s0, 0x80
	s_addc_u32 s1, s1, 0
	global_load_lds_dwordx4 v2, s[0:1]
	s_add_i32 m0, s26, 0x2000
	s_add_i32 s26, s64, s9
	global_load_lds_dwordx4 v144, s[0:1]
	s_add_u32 s0, s0, 0x20000
	s_addc_u32 s1, s1, 0
	s_mov_b32 m0, s26
	s_nop 0
	global_load_lds_dwordx4 v2, s[0:1]
	s_add_i32 m0, s26, 0x2000
	s_nop 0
	global_load_lds_dwordx4 v144, s[0:1]
	s_setprio 1
	s_waitcnt vmcnt(6)
	s_waitcnt lgkmcnt(0)
	s_barrier
	v_mfma_f32_16x16x32_bf16 v[64:67], v[84:87], v[186:189], v[64:67]
	v_mfma_f32_16x16x32_bf16 v[64:67], v[88:91], v[190:193], v[64:67]
	v_mfma_f32_16x16x32_bf16 v[60:63], v[162:165], v[186:189], v[60:63]
	v_mfma_f32_16x16x32_bf16 v[60:63], v[166:169], v[190:193], v[60:63]
	v_mfma_f32_16x16x32_bf16 v[44:47], v[162:165], v[194:197], v[44:47]
	v_mfma_f32_16x16x32_bf16 v[44:47], v[166:169], v[214:217], v[44:47]
	v_mfma_f32_16x16x32_bf16 v[48:51], v[84:87], v[194:197], v[48:51]
	v_mfma_f32_16x16x32_bf16 v[48:51], v[88:91], v[214:217], v[48:51]
	v_mfma_f32_16x16x32_bf16 v[32:35], v[84:87], v[218:221], v[32:35]
	v_mfma_f32_16x16x32_bf16 v[32:35], v[88:91], v[234:237], v[32:35]
	v_mfma_f32_16x16x32_bf16 v[28:31], v[162:165], v[218:221], v[28:31]
	v_mfma_f32_16x16x32_bf16 v[28:31], v[166:169], v[234:237], v[28:31]
	v_mfma_f32_16x16x32_bf16 v[12:15], v[162:165], v[238:241], v[12:15]
	v_mfma_f32_16x16x32_bf16 v[12:15], v[166:169], v[242:245], v[12:15]
	v_mfma_f32_16x16x32_bf16 v[16:19], v[84:87], v[238:241], v[16:19]
	v_mfma_f32_16x16x32_bf16 v[16:19], v[88:91], v[242:245], v[16:19]
	s_setprio 0
	s_setprio 1
	s_add_i32 s62, s62, 2
	s_add_u32 s52, s52, 0x100
	s_addc_u32 s53, s53, 0
	s_add_u32 s60, s60, 0x100
	s_addc_u32 s61, s61, 0
	s_nop 0
	v_mfma_f32_16x16x32_bf16 v[56:59], v[170:173], v[186:189], v[56:59]
	v_mfma_f32_16x16x32_bf16 v[56:59], v[174:177], v[190:193], v[56:59]
	v_mfma_f32_16x16x32_bf16 v[52:55], v[178:181], v[186:189], v[52:55]
	v_mfma_f32_16x16x32_bf16 v[52:55], v[182:185], v[190:193], v[52:55]
	v_mfma_f32_16x16x32_bf16 v[36:39], v[178:181], v[194:197], v[36:39]
	v_mfma_f32_16x16x32_bf16 v[36:39], v[182:185], v[214:217], v[36:39]
	v_mfma_f32_16x16x32_bf16 v[40:43], v[170:173], v[194:197], v[40:43]
	v_mfma_f32_16x16x32_bf16 v[40:43], v[174:177], v[214:217], v[40:43]
	v_mfma_f32_16x16x32_bf16 v[24:27], v[170:173], v[218:221], v[24:27]
	v_mfma_f32_16x16x32_bf16 v[24:27], v[174:177], v[234:237], v[24:27]
	v_mfma_f32_16x16x32_bf16 v[20:23], v[178:181], v[218:221], v[20:23]
	v_mfma_f32_16x16x32_bf16 v[20:23], v[182:185], v[234:237], v[20:23]
	v_mfma_f32_16x16x32_bf16 v[4:7], v[178:181], v[238:241], v[4:7]
	v_mfma_f32_16x16x32_bf16 v[4:7], v[182:185], v[242:245], v[4:7]
	v_mfma_f32_16x16x32_bf16 v[8:11], v[170:173], v[238:241], v[8:11]
	v_mfma_f32_16x16x32_bf16 v[8:11], v[174:177], v[242:245], v[8:11]
	s_barrier
	s_cmp_gt_u32 s62, 5
	s_cbranch_scc0 .LBB0_1051
	s_setprio 0
	s_and_b64 vcc, exec, s[36:37]
	s_cbranch_vccz .LBB0_1054
	s_barrier

; #define PG8_STAGE(bufoff, gbase, voff) do { _Pragma("unroll") for (int _i = 0; _i < 2; ++_i) \
;         __builtin_amdgcn_global_load_lds((const unsigned*)((const char*)(gbase) + (voff)[_i]), (PG8_LAS unsigned*)(lds + (bufoff) + ldsw + _i * 8192), 16, 0, 0); } while (0)
; #define PG8_LDA(dst, b, h) do { _Pragma("unroll") for (int m = 0; m < 4; ++m) _Pragma("unroll") for (int k = 0; k < 2; ++k) dst[m][k] = *(const PG8_LAS bf16x8*)(lds + PG8_SA(b, h) + aoff + m * 2048 + k * 1024); } while (0)
; #define PG8_LDB(dst, b, h) do { _Pragma("unroll") for (int n = 0; n < 2; ++n) _Pragma("unroll") for (int k = 0; k < 2; ++k) dst[n][k] = *(const PG8_LAS bf16x8*)(lds + PG8_SB(b, h) + boff + n * 2048 + k * 1024); } while (0)
; #define PG8_MMA(ai, bj, At, Bt) do { __builtin_amdgcn_s_setprio(1); _Pragma("unroll") for (int m = 0; m < 4; ++m) _Pragma("unroll") for (int n = 0; n < 2; ++n) _Pragma("unroll") for (int k = 0; k < 2; ++k) \
;         acc[ai][bj][m][n] = __builtin_amdgcn_mfma_f32_16x16x32_bf16(Bt[n][k], At[m][k], acc[ai][bj][m][n], 0, 0, 0); __builtin_amdgcn_s_setprio(0); } while (0)
; #define PG8_WAIT_V(n) asm volatile("s_waitcnt vmcnt(" #n ")" ::: "memory")
; #define PG8_WAIT_L(n) asm volatile("s_waitcnt lgkmcnt(" #n ")" ::: "memory")
; #define PG8_BAR __builtin_amdgcn_s_barrier()
; #define PG8_SCHED __builtin_amdgcn_sched_barrier(0)
; template <class Epi, class Sched, bool ALIGN_EPI = false, bool SP2 = false>
; __device__ __forceinline__ void gemm_phase(PG8_LAS unsigned char* lds, const Gemm g, const Sched& S, const Epi& E) {
;     ...
;             PG8_LDB(B0, 0, 0); PG8_LDB(B1, 0, 1); PG8_SCHED; PG8_LDA(At, 0, 0); PG8_STAGE(PG8_SA(1, 1), a1 + hstep, voffA);
;             PG8_WAIT_V(8); PG8_WAIT_L(0); PG8_BAR; PG8_MMA(0, 0, At, B0); PG8_MMA(0, 1, At, B1); PG8_BAR; PG8_SCHED;
;             PG8_LDA(At, 0, 1); PG8_STAGE(PG8_SB(0, 0), b2, voffB); PG8_STAGE(PG8_SB(0, 1), b2 + hstep, voffB); PG8_STAGE(PG8_SA(0, 0), a2, voffA);
;             PG8_WAIT_V(8); PG8_WAIT_L(0); PG8_BAR; PG8_MMA(1, 0, At, B0); PG8_MMA(1, 1, At, B1); PG8_BAR; PG8_SCHED;
.LBB0_1624:
	s_setprio 0
	ds_read_b128 v[142:145], v210
	ds_read_b128 v[150:153], v210 offset:1024
	ds_read_b128 v[154:157], v210 offset:2048
	ds_read_b128 v[158:161], v210 offset:3072
	ds_read_b128 v[162:165], v210 offset:16384
	ds_read_b128 v[166:169], v210 offset:17408
	ds_read_b128 v[170:173], v210 offset:18432
	ds_read_b128 v[174:177], v210 offset:19456
	ds_read_b128 v[178:181], v149
	ds_read_b128 v[182:185], v149 offset:1024
	ds_read_b128 v[186:189], v149 offset:2048
	ds_read_b128 v[190:193], v149 offset:3072
	ds_read_b128 v[194:197], v149 offset:4096
	ds_read_b128 v[198:201], v149 offset:5120
	ds_read_b128 v[202:205], v149 offset:6144
	ds_read_b128 v[206:209], v149 offset:7168
	s_add_u32 s0, s56, 0xfff00080
	s_addc_u32 s1, s57, -1
	s_add_i32 s63, 0, 0x10000
	s_cmp_eq_u32 s62, 60
	s_cselect_b32 s27, s51, s1
	s_cselect_b32 s26, s50, s0
	s_cselect_b32 s1, s53, s49
	s_cselect_b32 s0, s52, s47
	s_add_i32 s66, 0, 0x14000
	s_add_u32 s100, s56, 0xfff00000
	s_addc_u32 s101, s57, -1
	s_mov_b32 m0, s58
	s_nop 0
	global_load_lds_dwordx4 v132, s[100:101]
	s_mov_b32 m0, s59
	s_nop 0
	global_load_lds_dwordx4 v134, s[100:101]
	s_add_i32 m0, s10, 0xc000
	s_nop 0
	global_load_lds_dwordx4 v138, s[56:57]
	s_add_i32 m0, s10, 0xe000
	s_nop 0
	global_load_lds_dwordx4 v140, s[56:57]
	s_nop 0
	s_setprio 1
	s_waitcnt vmcnt(8)
	s_waitcnt lgkmcnt(0)
	s_barrier
	v_mfma_f32_16x16x32_bf16 v[128:131], v[142:145], v[178:181], v[128:131]
	v_mfma_f32_16x16x32_bf16 v[128:131], v[150:153], v[182:185], v[128:131]
	v_mfma_f32_16x16x32_bf16 v[124:127], v[154:157], v[178:181], v[124:127]
	v_mfma_f32_16x16x32_bf16 v[124:127], v[158:161], v[182:185], v[124:127]
	v_mfma_f32_16x16x32_bf16 v[108:111], v[154:157], v[186:189], v[108:111]
	v_mfma_f32_16x16x32_bf16 v[108:111], v[158:161], v[190:193], v[108:111]
	v_mfma_f32_16x16x32_bf16 v[112:115], v[142:145], v[186:189], v[112:115]
	v_mfma_f32_16x16x32_bf16 v[112:115], v[150:153], v[190:193], v[112:115]
	v_mfma_f32_16x16x32_bf16 v[96:99], v[142:145], v[194:197], v[96:99]
	v_mfma_f32_16x16x32_bf16 v[96:99], v[150:153], v[198:201], v[96:99]
	v_mfma_f32_16x16x32_bf16 v[92:95], v[154:157], v[194:197], v[92:95]
	v_mfma_f32_16x16x32_bf16 v[92:95], v[158:161], v[198:201], v[92:95]
	v_mfma_f32_16x16x32_bf16 v[76:79], v[154:157], v[202:205], v[76:79]
	v_mfma_f32_16x16x32_bf16 v[76:79], v[158:161], v[206:209], v[76:79]
	v_mfma_f32_16x16x32_bf16 v[80:83], v[142:145], v[202:205], v[80:83]
	v_mfma_f32_16x16x32_bf16 v[80:83], v[150:153], v[206:209], v[80:83]
	s_setprio 0
	s_setprio 1
	v_mfma_f32_16x16x32_bf16 v[120:123], v[162:165], v[178:181], v[120:123]
	v_mfma_f32_16x16x32_bf16 v[120:123], v[166:169], v[182:185], v[120:123]
	v_mfma_f32_16x16x32_bf16 v[116:119], v[170:173], v[178:181], v[116:119]
	v_mfma_f32_16x16x32_bf16 v[116:119], v[174:177], v[182:185], v[116:119]
	v_mfma_f32_16x16x32_bf16 v[100:103], v[170:173], v[186:189], v[100:103]
	v_mfma_f32_16x16x32_bf16 v[100:103], v[174:177], v[190:193], v[100:103]
	v_mfma_f32_16x16x32_bf16 v[104:107], v[162:165], v[186:189], v[104:107]
	v_mfma_f32_16x16x32_bf16 v[104:107], v[166:169], v[190:193], v[104:107]
	v_mfma_f32_16x16x32_bf16 v[88:91], v[162:165], v[194:197], v[88:91]
	v_mfma_f32_16x16x32_bf16 v[88:91], v[166:169], v[198:201], v[88:91]
	v_mfma_f32_16x16x32_bf16 v[84:87], v[170:173], v[194:197], v[84:87]
	v_mfma_f32_16x16x32_bf16 v[84:87], v[174:177], v[198:201], v[84:87]
	v_mfma_f32_16x16x32_bf16 v[68:71], v[170:173], v[202:205], v[68:71]
	v_mfma_f32_16x16x32_bf16 v[68:71], v[174:177], v[206:209], v[68:71]
	v_mfma_f32_16x16x32_bf16 v[72:75], v[162:165], v[202:205], v[72:75]
	v_mfma_f32_16x16x32_bf16 v[72:75], v[166:169], v[206:209], v[72:75]
	s_barrier
	s_setprio 0
	ds_read_b128 v[178:181], v149 offset:16384
	ds_read_b128 v[182:185], v149 offset:17408
	ds_read_b128 v[186:189], v149 offset:18432
	ds_read_b128 v[190:193], v149 offset:19456
	ds_read_b128 v[194:197], v149 offset:20480
	ds_read_b128 v[198:201], v149 offset:21504
	ds_read_b128 v[202:205], v149 offset:22528
	ds_read_b128 v[206:209], v149 offset:23552
	s_add_i32 s63, s63, s9
	s_mov_b32 m0, s63
	s_nop 0
	global_load_lds_dwordx4 v2, s[0:1]
	s_add_i32 m0, s63, 0x2000
	s_add_u32 s64, s0, 0x100000
	s_addc_u32 s65, s1, 0
	s_add_i32 s63, s66, s9
	global_load_lds_dwordx4 v136, s[0:1]
	s_mov_b32 m0, s63
	s_nop 0
	global_load_lds_dwordx4 v2, s[64:65]
	s_add_i32 m0, s63, 0x2000
	s_nop 0
	global_load_lds_dwordx4 v136, s[64:65]
	s_setprio 1
	s_waitcnt vmcnt(6)
	s_waitcnt lgkmcnt(0)
	s_barrier
	v_mfma_f32_16x16x32_bf16 v[64:67], v[142:145], v[178:181], v[64:67]
	v_mfma_f32_16x16x32_bf16 v[64:67], v[150:153], v[182:185], v[64:67]
	v_mfma_f32_16x16x32_bf16 v[60:63], v[154:157], v[178:181], v[60:63]
	v_mfma_f32_16x16x32_bf16 v[60:63], v[158:161], v[182:185], v[60:63]
	v_mfma_f32_16x16x32_bf16 v[44:47], v[154:157], v[186:189], v[44:47]
	v_mfma_f32_16x16x32_bf16 v[44:47], v[158:161], v[190:193], v[44:47]
	v_mfma_f32_16x16x32_bf16 v[48:51], v[142:145], v[186:189], v[48:51]
	v_mfma_f32_16x16x32_bf16 v[48:51], v[150:153], v[190:193], v[48:51]
	v_mfma_f32_16x16x32_bf16 v[32:35], v[142:145], v[194:197], v[32:35]
	v_mfma_f32_16x16x32_bf16 v[32:35], v[150:153], v[198:201], v[32:35]
	v_mfma_f32_16x16x32_bf16 v[28:31], v[154:157], v[194:197], v[28:31]
	v_mfma_f32_16x16x32_bf16 v[28:31], v[158:161], v[198:201], v[28:31]
	v_mfma_f32_16x16x32_bf16 v[12:15], v[154:157], v[202:205], v[12:15]
	v_mfma_f32_16x16x32_bf16 v[12:15], v[158:161], v[206:209], v[12:15]
	v_mfma_f32_16x16x32_bf16 v[16:19], v[142:145], v[202:205], v[16:19]
	v_mfma_f32_16x16x32_bf16 v[16:19], v[150:153], v[206:209], v[16:19]
	s_setprio 0
	s_setprio 1
	v_mfma_f32_16x16x32_bf16 v[56:59], v[162:165], v[178:181], v[56:59]
	v_mfma_f32_16x16x32_bf16 v[56:59], v[166:169], v[182:185], v[56:59]
	v_mfma_f32_16x16x32_bf16 v[52:55], v[170:173], v[178:181], v[52:55]
	v_mfma_f32_16x16x32_bf16 v[52:55], v[174:177], v[182:185], v[52:55]
	v_mfma_f32_16x16x32_bf16 v[36:39], v[170:173], v[186:189], v[36:39]
	v_mfma_f32_16x16x32_bf16 v[36:39], v[174:177], v[190:193], v[36:39]
	v_mfma_f32_16x16x32_bf16 v[40:43], v[162:165], v[186:189], v[40:43]
	v_mfma_f32_16x16x32_bf16 v[40:43], v[166:169], v[190:193], v[40:43]
	v_mfma_f32_16x16x32_bf16 v[24:27], v[162:165], v[194:197], v[24:27]
	v_mfma_f32_16x16x32_bf16 v[24:27], v[166:169], v[198:201], v[24:27]
	v_mfma_f32_16x16x32_bf16 v[20:23], v[170:173], v[194:197], v[20:23]
	v_mfma_f32_16x16x32_bf16 v[20:23], v[174:177], v[198:201], v[20:23]
	v_mfma_f32_16x16x32_bf16 v[4:7], v[170:173], v[202:205], v[4:7]
	v_mfma_f32_16x16x32_bf16 v[4:7], v[174:177], v[206:209], v[4:7]
	v_mfma_f32_16x16x32_bf16 v[8:11], v[162:165], v[202:205], v[8:11]
	v_mfma_f32_16x16x32_bf16 v[8:11], v[166:169], v[206:209], v[8:11]
	s_barrier
; #define PG8_STAGE(bufoff, gbase, voff) do { _Pragma("unroll") for (int _i = 0; _i < 2; ++_i) \
;         __builtin_amdgcn_global_load_lds((const unsigned*)((const char*)(gbase) + (voff)[_i]), (PG8_LAS unsigned*)(lds + (bufoff) + ldsw + _i * 8192), 16, 0, 0); } while (0)
; #define PG8_LDA(dst, b, h) do { _Pragma("unroll") for (int m = 0; m < 4; ++m) _Pragma("unroll") for (int k = 0; k < 2; ++k) dst[m][k] = *(const PG8_LAS bf16x8*)(lds + PG8_SA(b, h) + aoff + m * 2048 + k * 1024); } while (0)
; #define PG8_LDB(dst, b, h) do { _Pragma("unroll") for (int n = 0; n < 2; ++n) _Pragma("unroll") for (int k = 0; k < 2; ++k) dst[n][k] = *(const PG8_LAS bf16x8*)(lds + PG8_SB(b, h) + boff + n * 2048 + k * 1024); } while (0)
; #define PG8_MMA(ai, bj, At, Bt) do { __builtin_amdgcn_s_setprio(1); _Pragma("unroll") for (int m = 0; m < 4; ++m) _Pragma("unroll") for (int n = 0; n < 2; ++n) _Pragma("unroll") for (int k = 0; k < 2; ++k) \
;         acc[ai][bj][m][n] = __builtin_amdgcn_mfma_f32_16x16x32_bf16(Bt[n][k], At[m][k], acc[ai][bj][m][n], 0, 0, 0); __builtin_amdgcn_s_setprio(0); } while (0)
; #define PG8_WAIT_V(n) asm volatile("s_waitcnt vmcnt(" #n ")" ::: "memory")
; #define PG8_WAIT_L(n) asm volatile("s_waitcnt lgkmcnt(" #n ")" ::: "memory")
; #define PG8_BAR __builtin_amdgcn_s_barrier()
; #define PG8_SCHED __builtin_amdgcn_sched_barrier(0)
; template <class Epi, class Sched, bool ALIGN_EPI = false, bool SP2 = false>
; __device__ __forceinline__ void gemm_phase(PG8_LAS unsigned char* lds, const Gemm g, const Sched& S, const Epi& E) {
;     ...
;             PG8_LDB(B0, 1, 0); PG8_LDB(B1, 1, 1); PG8_SCHED; PG8_LDA(At, 1, 0); PG8_STAGE(PG8_SA(0, 1), a2 + hstep, voffA);
;             PG8_WAIT_V(8); PG8_WAIT_L(0); PG8_BAR; PG8_MMA(0, 0, At, B0); PG8_MMA(0, 1, At, B1); PG8_BAR; PG8_SCHED;
;             PG8_LDA(At, 1, 1); PG8_STAGE(PG8_SB(1, 0), b3, voffB); PG8_STAGE(PG8_SB(1, 1), b3 + hstep, voffB); PG8_STAGE(PG8_SA(1, 0), a3, voffA);
;             PG8_WAIT_V(8); PG8_WAIT_L(0); PG8_BAR; PG8_MMA(1, 0, At, B0); PG8_MMA(1, 1, At, B1); PG8_BAR; PG8_SCHED;
	s_setprio 0
	ds_read_b128 v[142:145], v210 offset:32768
	ds_read_b128 v[150:153], v210 offset:33792
	ds_read_b128 v[154:157], v210 offset:34816
	ds_read_b128 v[158:161], v210 offset:35840
	ds_read_b128 v[162:165], v210 offset:49152
	ds_read_b128 v[166:169], v210 offset:50176
	ds_read_b128 v[170:173], v210 offset:51200
	ds_read_b128 v[174:177], v210 offset:52224
	ds_read_b128 v[178:181], v149 offset:32768
	ds_read_b128 v[182:185], v149 offset:33792
	ds_read_b128 v[186:189], v149 offset:34816
	ds_read_b128 v[190:193], v149 offset:35840
	ds_read_b128 v[194:197], v149 offset:36864
	ds_read_b128 v[198:201], v149 offset:37888
	ds_read_b128 v[202:205], v149 offset:38912
	ds_read_b128 v[206:209], v149 offset:39936
	s_add_i32 s63, 0, 0x18000
	s_add_i32 s64, 0, 0x1c000
	s_mov_b32 m0, s10
	s_nop 0
	global_load_lds_dwordx4 v132, s[26:27]
	s_mov_b32 m0, s11
	s_nop 0
	global_load_lds_dwordx4 v134, s[26:27]
	s_add_u32 s26, s26, 0x100000
	s_addc_u32 s27, s27, 0
	s_mov_b32 m0, s25
	s_nop 0
	global_load_lds_dwordx4 v132, s[26:27]
	s_mov_b32 m0, s55
	s_nop 0
	global_load_lds_dwordx4 v134, s[26:27]
	s_nop 0
	s_setprio 1
	s_waitcnt vmcnt(8)
	s_waitcnt lgkmcnt(0)
	s_barrier
	v_mfma_f32_16x16x32_bf16 v[128:131], v[142:145], v[178:181], v[128:131]
	v_mfma_f32_16x16x32_bf16 v[128:131], v[150:153], v[182:185], v[128:131]
	v_mfma_f32_16x16x32_bf16 v[124:127], v[154:157], v[178:181], v[124:127]
	v_mfma_f32_16x16x32_bf16 v[124:127], v[158:161], v[182:185], v[124:127]
	v_mfma_f32_16x16x32_bf16 v[108:111], v[154:157], v[186:189], v[108:111]
	v_mfma_f32_16x16x32_bf16 v[108:111], v[158:161], v[190:193], v[108:111]
	v_mfma_f32_16x16x32_bf16 v[112:115], v[142:145], v[186:189], v[112:115]
	v_mfma_f32_16x16x32_bf16 v[112:115], v[150:153], v[190:193], v[112:115]
	v_mfma_f32_16x16x32_bf16 v[96:99], v[142:145], v[194:197], v[96:99]
	v_mfma_f32_16x16x32_bf16 v[96:99], v[150:153], v[198:201], v[96:99]
	v_mfma_f32_16x16x32_bf16 v[92:95], v[154:157], v[194:197], v[92:95]
	v_mfma_f32_16x16x32_bf16 v[92:95], v[158:161], v[198:201], v[92:95]
	v_mfma_f32_16x16x32_bf16 v[76:79], v[154:157], v[202:205], v[76:79]
	v_mfma_f32_16x16x32_bf16 v[76:79], v[158:161], v[206:209], v[76:79]
	v_mfma_f32_16x16x32_bf16 v[80:83], v[142:145], v[202:205], v[80:83]
	v_mfma_f32_16x16x32_bf16 v[80:83], v[150:153], v[206:209], v[80:83]
	s_setprio 0
	s_setprio 1
	v_mfma_f32_16x16x32_bf16 v[120:123], v[162:165], v[178:181], v[120:123]
	v_mfma_f32_16x16x32_bf16 v[120:123], v[166:169], v[182:185], v[120:123]
	v_mfma_f32_16x16x32_bf16 v[116:119], v[170:173], v[178:181], v[116:119]
	v_mfma_f32_16x16x32_bf16 v[116:119], v[174:177], v[182:185], v[116:119]
	v_mfma_f32_16x16x32_bf16 v[100:103], v[170:173], v[186:189], v[100:103]
	v_mfma_f32_16x16x32_bf16 v[100:103], v[174:177], v[190:193], v[100:103]
	v_mfma_f32_16x16x32_bf16 v[104:107], v[162:165], v[186:189], v[104:107]
	v_mfma_f32_16x16x32_bf16 v[104:107], v[166:169], v[190:193], v[104:107]
	v_mfma_f32_16x16x32_bf16 v[88:91], v[162:165], v[194:197], v[88:91]
	v_mfma_f32_16x16x32_bf16 v[88:91], v[166:169], v[198:201], v[88:91]
	v_mfma_f32_16x16x32_bf16 v[84:87], v[170:173], v[194:197], v[84:87]
	v_mfma_f32_16x16x32_bf16 v[84:87], v[174:177], v[198:201], v[84:87]
	v_mfma_f32_16x16x32_bf16 v[68:71], v[170:173], v[202:205], v[68:71]
	v_mfma_f32_16x16x32_bf16 v[68:71], v[174:177], v[206:209], v[68:71]
	v_mfma_f32_16x16x32_bf16 v[72:75], v[162:165], v[202:205], v[72:75]
	v_mfma_f32_16x16x32_bf16 v[72:75], v[166:169], v[206:209], v[72:75]
	s_barrier
	s_setprio 0
	ds_read_b128 v[178:181], v149 offset:49152
	ds_read_b128 v[182:185], v149 offset:50176
	ds_read_b128 v[186:189], v149 offset:51200
	ds_read_b128 v[190:193], v149 offset:52224
	ds_read_b128 v[194:197], v149 offset:53248
	ds_read_b128 v[198:201], v149 offset:54272
	ds_read_b128 v[202:205], v149 offset:55296
	ds_read_b128 v[206:209], v149 offset:56320
	s_add_i32 s26, s63, s9
	s_mov_b32 m0, s26
	s_add_u32 s0, s0, 0x80
	s_addc_u32 s1, s1, 0
	global_load_lds_dwordx4 v2, s[0:1]
	s_add_i32 m0, s26, 0x2000
	s_add_i32 s26, s64, s9
	global_load_lds_dwordx4 v136, s[0:1]
	s_add_u32 s0, s0, 0x100000
	s_addc_u32 s1, s1, 0
	s_mov_b32 m0, s26
	s_nop 0
	global_load_lds_dwordx4 v2, s[0:1]
	s_add_i32 m0, s26, 0x2000
	s_nop 0
	global_load_lds_dwordx4 v136, s[0:1]
	s_setprio 1
	s_waitcnt vmcnt(6)
	s_waitcnt lgkmcnt(0)
	s_barrier
	v_mfma_f32_16x16x32_bf16 v[64:67], v[142:145], v[178:181], v[64:67]
	v_mfma_f32_16x16x32_bf16 v[64:67], v[150:153], v[182:185], v[64:67]
	v_mfma_f32_16x16x32_bf16 v[60:63], v[154:157], v[178:181], v[60:63]
	v_mfma_f32_16x16x32_bf16 v[60:63], v[158:161], v[182:185], v[60:63]
	v_mfma_f32_16x16x32_bf16 v[44:47], v[154:157], v[186:189], v[44:47]
	v_mfma_f32_16x16x32_bf16 v[44:47], v[158:161], v[190:193], v[44:47]
	v_mfma_f32_16x16x32_bf16 v[48:51], v[142:145], v[186:189], v[48:51]
	v_mfma_f32_16x16x32_bf16 v[48:51], v[150:153], v[190:193], v[48:51]
	v_mfma_f32_16x16x32_bf16 v[32:35], v[142:145], v[194:197], v[32:35]
	v_mfma_f32_16x16x32_bf16 v[32:35], v[150:153], v[198:201], v[32:35]
	v_mfma_f32_16x16x32_bf16 v[28:31], v[154:157], v[194:197], v[28:31]
	v_mfma_f32_16x16x32_bf16 v[28:31], v[158:161], v[198:201], v[28:31]
	v_mfma_f32_16x16x32_bf16 v[12:15], v[154:157], v[202:205], v[12:15]
	v_mfma_f32_16x16x32_bf16 v[12:15], v[158:161], v[206:209], v[12:15]
	v_mfma_f32_16x16x32_bf16 v[16:19], v[142:145], v[202:205], v[16:19]
	v_mfma_f32_16x16x32_bf16 v[16:19], v[150:153], v[206:209], v[16:19]
	s_setprio 0
	s_setprio 1
	s_add_i32 s62, s62, 2
	s_add_u32 s56, s56, 0x100
	s_addc_u32 s57, s57, 0
	s_add_u32 s47, s47, 0x100
	s_addc_u32 s49, s49, 0
	s_nop 0
	v_mfma_f32_16x16x32_bf16 v[56:59], v[162:165], v[178:181], v[56:59]
	v_mfma_f32_16x16x32_bf16 v[56:59], v[166:169], v[182:185], v[56:59]
	v_mfma_f32_16x16x32_bf16 v[52:55], v[170:173], v[178:181], v[52:55]
	v_mfma_f32_16x16x32_bf16 v[52:55], v[174:177], v[182:185], v[52:55]
	v_mfma_f32_16x16x32_bf16 v[36:39], v[170:173], v[186:189], v[36:39]
	v_mfma_f32_16x16x32_bf16 v[36:39], v[174:177], v[190:193], v[36:39]
	v_mfma_f32_16x16x32_bf16 v[40:43], v[162:165], v[186:189], v[40:43]
	v_mfma_f32_16x16x32_bf16 v[40:43], v[166:169], v[190:193], v[40:43]
	v_mfma_f32_16x16x32_bf16 v[24:27], v[162:165], v[194:197], v[24:27]
	v_mfma_f32_16x16x32_bf16 v[24:27], v[166:169], v[198:201], v[24:27]
	v_mfma_f32_16x16x32_bf16 v[20:23], v[170:173], v[194:197], v[20:23]
	v_mfma_f32_16x16x32_bf16 v[20:23], v[174:177], v[198:201], v[20:23]
	v_mfma_f32_16x16x32_bf16 v[4:7], v[170:173], v[202:205], v[4:7]
	v_mfma_f32_16x16x32_bf16 v[4:7], v[174:177], v[206:209], v[4:7]
	v_mfma_f32_16x16x32_bf16 v[8:11], v[162:165], v[202:205], v[8:11]
	v_mfma_f32_16x16x32_bf16 v[8:11], v[166:169], v[206:209], v[8:11]
	s_barrier
	s_cmp_gt_u32 s62, 61
	s_cbranch_scc0 .LBB0_1624
	s_setprio 0
	s_and_b64 vcc, exec, s[44:45]
	s_cbranch_vccz .LBB0_1627
	s_barrier

; #define PG8_STAGE(bufoff, gbase, voff) do { _Pragma("unroll") for (int _i = 0; _i < 2; ++_i) \
;         __builtin_amdgcn_global_load_lds((const unsigned*)((const char*)(gbase) + (voff)[_i]), (PG8_LAS unsigned*)(lds + (bufoff) + ldsw + _i * 8192), 16, 0, 0); } while (0)
; #define PG8_LDA(dst, b, h) do { _Pragma("unroll") for (int m = 0; m < 4; ++m) _Pragma("unroll") for (int k = 0; k < 2; ++k) dst[m][k] = *(const PG8_LAS bf16x8*)(lds + PG8_SA(b, h) + aoff + m * 2048 + k * 1024); } while (0)
; #define PG8_LDB(dst, b, h) do { _Pragma("unroll") for (int n = 0; n < 2; ++n) _Pragma("unroll") for (int k = 0; k < 2; ++k) dst[n][k] = *(const PG8_LAS bf16x8*)(lds + PG8_SB(b, h) + boff + n * 2048 + k * 1024); } while (0)
; #define PG8_MMA(ai, bj, At, Bt) do { __builtin_amdgcn_s_setprio(1); _Pragma("unroll") for (int m = 0; m < 4; ++m) _Pragma("unroll") for (int n = 0; n < 2; ++n) _Pragma("unroll") for (int k = 0; k < 2; ++k) \
;         acc[ai][bj][m][n] = __builtin_amdgcn_mfma_f32_16x16x32_bf16(Bt[n][k], At[m][k], acc[ai][bj][m][n], 0, 0, 0); __builtin_amdgcn_s_setprio(0); } while (0)
; #define PG8_WAIT_V(n) asm volatile("s_waitcnt vmcnt(" #n ")" ::: "memory")
; #define PG8_WAIT_L(n) asm volatile("s_waitcnt lgkmcnt(" #n ")" ::: "memory")
; #define PG8_BAR __builtin_amdgcn_s_barrier()
; #define PG8_SCHED __builtin_amdgcn_sched_barrier(0)
; template <class Epi, class Sched, bool ALIGN_EPI = false, bool SP2 = false>
; __device__ __forceinline__ void gemm_phase(PG8_LAS unsigned char* lds, const Gemm g, const Sched& S, const Epi& E) {
;     ...
;             PG8_LDB(B0, 0, 0); PG8_LDB(B1, 0, 1); PG8_SCHED; PG8_LDA(At, 0, 0); PG8_STAGE(PG8_SA(1, 1), a1 + hstep, voffA);
;             PG8_WAIT_V(8); PG8_WAIT_L(0); PG8_BAR; PG8_MMA(0, 0, At, B0); PG8_MMA(0, 1, At, B1); PG8_BAR; PG8_SCHED;
;             PG8_LDA(At, 0, 1); PG8_STAGE(PG8_SB(0, 0), b2, voffB); PG8_STAGE(PG8_SB(0, 1), b2 + hstep, voffB); PG8_STAGE(PG8_SA(0, 0), a2, voffA);
;             PG8_WAIT_V(8); PG8_WAIT_L(0); PG8_BAR; PG8_MMA(1, 0, At, B0); PG8_MMA(1, 1, At, B1); PG8_BAR; PG8_SCHED;
.LBB0_2089:
	s_setprio 0
	ds_read_b128 v[142:145], v210
	ds_read_b128 v[146:149], v210 offset:1024
	ds_read_b128 v[154:157], v210 offset:2048
	ds_read_b128 v[158:161], v210 offset:3072
	ds_read_b128 v[162:165], v210 offset:16384
	ds_read_b128 v[166:169], v210 offset:17408
	ds_read_b128 v[170:173], v210 offset:18432
	ds_read_b128 v[174:177], v210 offset:19456
	ds_read_b128 v[178:181], v153
	ds_read_b128 v[182:185], v153 offset:1024
	ds_read_b128 v[186:189], v153 offset:2048
	ds_read_b128 v[190:193], v153 offset:3072
	ds_read_b128 v[194:197], v153 offset:4096
	ds_read_b128 v[198:201], v153 offset:5120
	ds_read_b128 v[202:205], v153 offset:6144
	ds_read_b128 v[206:209], v153 offset:7168
	s_add_u32 s0, s50, 0xfff00080
	s_addc_u32 s1, s51, -1
	s_add_i32 s61, 0, 0x10000
	s_cmp_eq_u32 s60, 60
	s_cselect_b32 s27, s47, s1
	s_cselect_b32 s26, s46, s0
	s_cselect_b32 s1, s49, s45
	s_cselect_b32 s0, s48, s43
	s_add_i32 s64, 0, 0x14000
	s_add_u32 s100, s50, 0xfff00000
	s_addc_u32 s101, s51, -1
	s_mov_b32 m0, s54
	s_nop 0
	global_load_lds_dwordx4 v136, s[100:101]
	s_mov_b32 m0, s55
	s_nop 0
	global_load_lds_dwordx4 v134, s[100:101]
	s_add_i32 m0, s10, 0xc000
	s_nop 0
	global_load_lds_dwordx4 v138, s[50:51]
	s_add_i32 m0, s10, 0xe000
	s_nop 0
	global_load_lds_dwordx4 v140, s[50:51]
	s_setprio 1
	s_waitcnt vmcnt(8)
	s_waitcnt lgkmcnt(0)
	s_barrier
	v_mfma_f32_16x16x32_bf16 v[128:131], v[142:145], v[178:181], v[128:131]
	v_mfma_f32_16x16x32_bf16 v[128:131], v[146:149], v[182:185], v[128:131]
	v_mfma_f32_16x16x32_bf16 v[124:127], v[154:157], v[178:181], v[124:127]
	v_mfma_f32_16x16x32_bf16 v[124:127], v[158:161], v[182:185], v[124:127]
	v_mfma_f32_16x16x32_bf16 v[108:111], v[154:157], v[186:189], v[108:111]
	v_mfma_f32_16x16x32_bf16 v[108:111], v[158:161], v[190:193], v[108:111]
	v_mfma_f32_16x16x32_bf16 v[112:115], v[142:145], v[186:189], v[112:115]
	v_mfma_f32_16x16x32_bf16 v[112:115], v[146:149], v[190:193], v[112:115]
	v_mfma_f32_16x16x32_bf16 v[96:99], v[142:145], v[194:197], v[96:99]
	v_mfma_f32_16x16x32_bf16 v[96:99], v[146:149], v[198:201], v[96:99]
	v_mfma_f32_16x16x32_bf16 v[92:95], v[154:157], v[194:197], v[92:95]
	v_mfma_f32_16x16x32_bf16 v[92:95], v[158:161], v[198:201], v[92:95]
	v_mfma_f32_16x16x32_bf16 v[76:79], v[154:157], v[202:205], v[76:79]
	v_mfma_f32_16x16x32_bf16 v[76:79], v[158:161], v[206:209], v[76:79]
	v_mfma_f32_16x16x32_bf16 v[80:83], v[142:145], v[202:205], v[80:83]
	v_mfma_f32_16x16x32_bf16 v[80:83], v[146:149], v[206:209], v[80:83]
	s_setprio 0
	s_setprio 1
	v_mfma_f32_16x16x32_bf16 v[120:123], v[162:165], v[178:181], v[120:123]
	v_mfma_f32_16x16x32_bf16 v[120:123], v[166:169], v[182:185], v[120:123]
	v_mfma_f32_16x16x32_bf16 v[116:119], v[170:173], v[178:181], v[116:119]
	v_mfma_f32_16x16x32_bf16 v[116:119], v[174:177], v[182:185], v[116:119]
	v_mfma_f32_16x16x32_bf16 v[100:103], v[170:173], v[186:189], v[100:103]
	v_mfma_f32_16x16x32_bf16 v[100:103], v[174:177], v[190:193], v[100:103]
	v_mfma_f32_16x16x32_bf16 v[104:107], v[162:165], v[186:189], v[104:107]
	v_mfma_f32_16x16x32_bf16 v[104:107], v[166:169], v[190:193], v[104:107]
	v_mfma_f32_16x16x32_bf16 v[88:91], v[162:165], v[194:197], v[88:91]
	v_mfma_f32_16x16x32_bf16 v[88:91], v[166:169], v[198:201], v[88:91]
	v_mfma_f32_16x16x32_bf16 v[84:87], v[170:173], v[194:197], v[84:87]
	v_mfma_f32_16x16x32_bf16 v[84:87], v[174:177], v[198:201], v[84:87]
	v_mfma_f32_16x16x32_bf16 v[68:71], v[170:173], v[202:205], v[68:71]
	v_mfma_f32_16x16x32_bf16 v[68:71], v[174:177], v[206:209], v[68:71]
	v_mfma_f32_16x16x32_bf16 v[72:75], v[162:165], v[202:205], v[72:75]
	v_mfma_f32_16x16x32_bf16 v[72:75], v[166:169], v[206:209], v[72:75]
	s_barrier
	s_setprio 0
	ds_read_b128 v[178:181], v153 offset:16384
	ds_read_b128 v[182:185], v153 offset:17408
	ds_read_b128 v[186:189], v153 offset:18432
	ds_read_b128 v[190:193], v153 offset:19456
	ds_read_b128 v[194:197], v153 offset:20480
	ds_read_b128 v[198:201], v153 offset:21504
	ds_read_b128 v[202:205], v153 offset:22528
	ds_read_b128 v[206:209], v153 offset:23552
	s_add_i32 s61, s61, s9
	s_mov_b32 m0, s61
	s_nop 0
	global_load_lds_dwordx4 v2, s[0:1]
	s_add_i32 m0, s61, 0x2000
	s_add_u32 s62, s0, 0x100000
	s_addc_u32 s63, s1, 0
	s_add_i32 s61, s64, s9
	global_load_lds_dwordx4 v132, s[0:1]
	s_mov_b32 m0, s61
	s_nop 0
	global_load_lds_dwordx4 v2, s[62:63]
	s_add_i32 m0, s61, 0x2000
	s_nop 0
	global_load_lds_dwordx4 v132, s[62:63]
	s_setprio 1
	s_waitcnt vmcnt(6)
	s_waitcnt lgkmcnt(0)
	s_barrier
	v_mfma_f32_16x16x32_bf16 v[64:67], v[142:145], v[178:181], v[64:67]
	v_mfma_f32_16x16x32_bf16 v[64:67], v[146:149], v[182:185], v[64:67]
	v_mfma_f32_16x16x32_bf16 v[60:63], v[154:157], v[178:181], v[60:63]
	v_mfma_f32_16x16x32_bf16 v[60:63], v[158:161], v[182:185], v[60:63]
	v_mfma_f32_16x16x32_bf16 v[44:47], v[154:157], v[186:189], v[44:47]
	v_mfma_f32_16x16x32_bf16 v[44:47], v[158:161], v[190:193], v[44:47]
	v_mfma_f32_16x16x32_bf16 v[48:51], v[142:145], v[186:189], v[48:51]
	v_mfma_f32_16x16x32_bf16 v[48:51], v[146:149], v[190:193], v[48:51]
	v_mfma_f32_16x16x32_bf16 v[32:35], v[142:145], v[194:197], v[32:35]
	v_mfma_f32_16x16x32_bf16 v[32:35], v[146:149], v[198:201], v[32:35]
	v_mfma_f32_16x16x32_bf16 v[28:31], v[154:157], v[194:197], v[28:31]
	v_mfma_f32_16x16x32_bf16 v[28:31], v[158:161], v[198:201], v[28:31]
	v_mfma_f32_16x16x32_bf16 v[12:15], v[154:157], v[202:205], v[12:15]
	v_mfma_f32_16x16x32_bf16 v[12:15], v[158:161], v[206:209], v[12:15]
	v_mfma_f32_16x16x32_bf16 v[16:19], v[142:145], v[202:205], v[16:19]
	v_mfma_f32_16x16x32_bf16 v[16:19], v[146:149], v[206:209], v[16:19]
	s_setprio 0
	s_setprio 1
	v_mfma_f32_16x16x32_bf16 v[56:59], v[162:165], v[178:181], v[56:59]
	v_mfma_f32_16x16x32_bf16 v[56:59], v[166:169], v[182:185], v[56:59]
	v_mfma_f32_16x16x32_bf16 v[52:55], v[170:173], v[178:181], v[52:55]
	v_mfma_f32_16x16x32_bf16 v[52:55], v[174:177], v[182:185], v[52:55]
	v_mfma_f32_16x16x32_bf16 v[36:39], v[170:173], v[186:189], v[36:39]
	v_mfma_f32_16x16x32_bf16 v[36:39], v[174:177], v[190:193], v[36:39]
	v_mfma_f32_16x16x32_bf16 v[40:43], v[162:165], v[186:189], v[40:43]
	v_mfma_f32_16x16x32_bf16 v[40:43], v[166:169], v[190:193], v[40:43]
	v_mfma_f32_16x16x32_bf16 v[24:27], v[162:165], v[194:197], v[24:27]
	v_mfma_f32_16x16x32_bf16 v[24:27], v[166:169], v[198:201], v[24:27]
	v_mfma_f32_16x16x32_bf16 v[20:23], v[170:173], v[194:197], v[20:23]
	v_mfma_f32_16x16x32_bf16 v[20:23], v[174:177], v[198:201], v[20:23]
	v_mfma_f32_16x16x32_bf16 v[4:7], v[170:173], v[202:205], v[4:7]
	v_mfma_f32_16x16x32_bf16 v[4:7], v[174:177], v[206:209], v[4:7]
	v_mfma_f32_16x16x32_bf16 v[8:11], v[162:165], v[202:205], v[8:11]
	v_mfma_f32_16x16x32_bf16 v[8:11], v[166:169], v[206:209], v[8:11]
	s_barrier
; #define PG8_STAGE(bufoff, gbase, voff) do { _Pragma("unroll") for (int _i = 0; _i < 2; ++_i) \
;         __builtin_amdgcn_global_load_lds((const unsigned*)((const char*)(gbase) + (voff)[_i]), (PG8_LAS unsigned*)(lds + (bufoff) + ldsw + _i * 8192), 16, 0, 0); } while (0)
; #define PG8_LDA(dst, b, h) do { _Pragma("unroll") for (int m = 0; m < 4; ++m) _Pragma("unroll") for (int k = 0; k < 2; ++k) dst[m][k] = *(const PG8_LAS bf16x8*)(lds + PG8_SA(b, h) + aoff + m * 2048 + k * 1024); } while (0)
; #define PG8_LDB(dst, b, h) do { _Pragma("unroll") for (int n = 0; n < 2; ++n) _Pragma("unroll") for (int k = 0; k < 2; ++k) dst[n][k] = *(const PG8_LAS bf16x8*)(lds + PG8_SB(b, h) + boff + n * 2048 + k * 1024); } while (0)
; #define PG8_MMA(ai, bj, At, Bt) do { __builtin_amdgcn_s_setprio(1); _Pragma("unroll") for (int m = 0; m < 4; ++m) _Pragma("unroll") for (int n = 0; n < 2; ++n) _Pragma("unroll") for (int k = 0; k < 2; ++k) \
;         acc[ai][bj][m][n] = __builtin_amdgcn_mfma_f32_16x16x32_bf16(Bt[n][k], At[m][k], acc[ai][bj][m][n], 0, 0, 0); __builtin_amdgcn_s_setprio(0); } while (0)
; #define PG8_WAIT_V(n) asm volatile("s_waitcnt vmcnt(" #n ")" ::: "memory")
; #define PG8_WAIT_L(n) asm volatile("s_waitcnt lgkmcnt(" #n ")" ::: "memory")
; #define PG8_BAR __builtin_amdgcn_s_barrier()
; #define PG8_SCHED __builtin_amdgcn_sched_barrier(0)
; template <class Epi, class Sched, bool ALIGN_EPI = false, bool SP2 = false>
; __device__ __forceinline__ void gemm_phase(PG8_LAS unsigned char* lds, const Gemm g, const Sched& S, const Epi& E) {
;     ...
;             PG8_LDB(B0, 1, 0); PG8_LDB(B1, 1, 1); PG8_SCHED; PG8_LDA(At, 1, 0); PG8_STAGE(PG8_SA(0, 1), a2 + hstep, voffA);
;             PG8_WAIT_V(8); PG8_WAIT_L(0); PG8_BAR; PG8_MMA(0, 0, At, B0); PG8_MMA(0, 1, At, B1); PG8_BAR; PG8_SCHED;
;             PG8_LDA(At, 1, 1); PG8_STAGE(PG8_SB(1, 0), b3, voffB); PG8_STAGE(PG8_SB(1, 1), b3 + hstep, voffB); PG8_STAGE(PG8_SA(1, 0), a3, voffA);
;             PG8_WAIT_V(8); PG8_WAIT_L(0); PG8_BAR; PG8_MMA(1, 0, At, B0); PG8_MMA(1, 1, At, B1); PG8_BAR; PG8_SCHED;
	s_setprio 0
	ds_read_b128 v[142:145], v210 offset:32768
	ds_read_b128 v[146:149], v210 offset:33792
	ds_read_b128 v[154:157], v210 offset:34816
	ds_read_b128 v[158:161], v210 offset:35840
	ds_read_b128 v[162:165], v210 offset:49152
	ds_read_b128 v[166:169], v210 offset:50176
	ds_read_b128 v[170:173], v210 offset:51200
	ds_read_b128 v[174:177], v210 offset:52224
	ds_read_b128 v[178:181], v153 offset:32768
	ds_read_b128 v[182:185], v153 offset:33792
	ds_read_b128 v[186:189], v153 offset:34816
	ds_read_b128 v[190:193], v153 offset:35840
	ds_read_b128 v[194:197], v153 offset:36864
	ds_read_b128 v[198:201], v153 offset:37888
	ds_read_b128 v[202:205], v153 offset:38912
	ds_read_b128 v[206:209], v153 offset:39936
	s_add_i32 s61, 0, 0x18000
	s_add_i32 s62, 0, 0x1c000
	s_mov_b32 m0, s10
	s_nop 0
	global_load_lds_dwordx4 v136, s[26:27]
	s_mov_b32 m0, s11
	s_nop 0
	global_load_lds_dwordx4 v134, s[26:27]
	s_add_u32 s26, s26, 0x100000
	s_addc_u32 s27, s27, 0
	s_mov_b32 m0, s52
	s_nop 0
	global_load_lds_dwordx4 v136, s[26:27]
	s_mov_b32 m0, s53
	s_nop 0
	global_load_lds_dwordx4 v134, s[26:27]
	s_nop 0
	s_setprio 1
	s_waitcnt vmcnt(8)
	s_waitcnt lgkmcnt(0)
	s_barrier
	v_mfma_f32_16x16x32_bf16 v[128:131], v[142:145], v[178:181], v[128:131]
	v_mfma_f32_16x16x32_bf16 v[128:131], v[146:149], v[182:185], v[128:131]
	v_mfma_f32_16x16x32_bf16 v[124:127], v[154:157], v[178:181], v[124:127]
	v_mfma_f32_16x16x32_bf16 v[124:127], v[158:161], v[182:185], v[124:127]
	v_mfma_f32_16x16x32_bf16 v[108:111], v[154:157], v[186:189], v[108:111]
	v_mfma_f32_16x16x32_bf16 v[108:111], v[158:161], v[190:193], v[108:111]
	v_mfma_f32_16x16x32_bf16 v[112:115], v[142:145], v[186:189], v[112:115]
	v_mfma_f32_16x16x32_bf16 v[112:115], v[146:149], v[190:193], v[112:115]
	v_mfma_f32_16x16x32_bf16 v[96:99], v[142:145], v[194:197], v[96:99]
	v_mfma_f32_16x16x32_bf16 v[96:99], v[146:149], v[198:201], v[96:99]
	v_mfma_f32_16x16x32_bf16 v[92:95], v[154:157], v[194:197], v[92:95]
	v_mfma_f32_16x16x32_bf16 v[92:95], v[158:161], v[198:201], v[92:95]
	v_mfma_f32_16x16x32_bf16 v[76:79], v[154:157], v[202:205], v[76:79]
	v_mfma_f32_16x16x32_bf16 v[76:79], v[158:161], v[206:209], v[76:79]
	v_mfma_f32_16x16x32_bf16 v[80:83], v[142:145], v[202:205], v[80:83]
	v_mfma_f32_16x16x32_bf16 v[80:83], v[146:149], v[206:209], v[80:83]
	s_setprio 0
	s_setprio 1
	v_mfma_f32_16x16x32_bf16 v[120:123], v[162:165], v[178:181], v[120:123]
	v_mfma_f32_16x16x32_bf16 v[120:123], v[166:169], v[182:185], v[120:123]
	v_mfma_f32_16x16x32_bf16 v[116:119], v[170:173], v[178:181], v[116:119]
	v_mfma_f32_16x16x32_bf16 v[116:119], v[174:177], v[182:185], v[116:119]
	v_mfma_f32_16x16x32_bf16 v[100:103], v[170:173], v[186:189], v[100:103]
	v_mfma_f32_16x16x32_bf16 v[100:103], v[174:177], v[190:193], v[100:103]
	v_mfma_f32_16x16x32_bf16 v[104:107], v[162:165], v[186:189], v[104:107]
	v_mfma_f32_16x16x32_bf16 v[104:107], v[166:169], v[190:193], v[104:107]
	v_mfma_f32_16x16x32_bf16 v[88:91], v[162:165], v[194:197], v[88:91]
	v_mfma_f32_16x16x32_bf16 v[88:91], v[166:169], v[198:201], v[88:91]
	v_mfma_f32_16x16x32_bf16 v[84:87], v[170:173], v[194:197], v[84:87]
	v_mfma_f32_16x16x32_bf16 v[84:87], v[174:177], v[198:201], v[84:87]
	v_mfma_f32_16x16x32_bf16 v[68:71], v[170:173], v[202:205], v[68:71]
	v_mfma_f32_16x16x32_bf16 v[68:71], v[174:177], v[206:209], v[68:71]
	v_mfma_f32_16x16x32_bf16 v[72:75], v[162:165], v[202:205], v[72:75]
	v_mfma_f32_16x16x32_bf16 v[72:75], v[166:169], v[206:209], v[72:75]
	s_barrier
	s_setprio 0
	ds_read_b128 v[178:181], v153 offset:49152
	ds_read_b128 v[182:185], v153 offset:50176
	ds_read_b128 v[186:189], v153 offset:51200
	ds_read_b128 v[190:193], v153 offset:52224
	ds_read_b128 v[194:197], v153 offset:53248
	ds_read_b128 v[198:201], v153 offset:54272
	ds_read_b128 v[202:205], v153 offset:55296
	ds_read_b128 v[206:209], v153 offset:56320
	s_add_i32 s26, s61, s9
	s_mov_b32 m0, s26
	s_add_u32 s0, s0, 0x80
	s_addc_u32 s1, s1, 0
	global_load_lds_dwordx4 v2, s[0:1]
	s_add_i32 m0, s26, 0x2000
	s_add_i32 s26, s62, s9
	global_load_lds_dwordx4 v132, s[0:1]
	s_add_u32 s0, s0, 0x100000
	s_addc_u32 s1, s1, 0
	s_mov_b32 m0, s26
	s_nop 0
	global_load_lds_dwordx4 v2, s[0:1]
	s_add_i32 m0, s26, 0x2000
	s_nop 0
	global_load_lds_dwordx4 v132, s[0:1]
	s_setprio 1
	s_waitcnt vmcnt(6)
	s_waitcnt lgkmcnt(0)
	s_barrier
	v_mfma_f32_16x16x32_bf16 v[64:67], v[142:145], v[178:181], v[64:67]
	v_mfma_f32_16x16x32_bf16 v[64:67], v[146:149], v[182:185], v[64:67]
	v_mfma_f32_16x16x32_bf16 v[60:63], v[154:157], v[178:181], v[60:63]
	v_mfma_f32_16x16x32_bf16 v[60:63], v[158:161], v[182:185], v[60:63]
	v_mfma_f32_16x16x32_bf16 v[44:47], v[154:157], v[186:189], v[44:47]
	v_mfma_f32_16x16x32_bf16 v[44:47], v[158:161], v[190:193], v[44:47]
	v_mfma_f32_16x16x32_bf16 v[48:51], v[142:145], v[186:189], v[48:51]
	v_mfma_f32_16x16x32_bf16 v[48:51], v[146:149], v[190:193], v[48:51]
	v_mfma_f32_16x16x32_bf16 v[32:35], v[142:145], v[194:197], v[32:35]
	v_mfma_f32_16x16x32_bf16 v[32:35], v[146:149], v[198:201], v[32:35]
	v_mfma_f32_16x16x32_bf16 v[28:31], v[154:157], v[194:197], v[28:31]
	v_mfma_f32_16x16x32_bf16 v[28:31], v[158:161], v[198:201], v[28:31]
	v_mfma_f32_16x16x32_bf16 v[12:15], v[154:157], v[202:205], v[12:15]
	v_mfma_f32_16x16x32_bf16 v[12:15], v[158:161], v[206:209], v[12:15]
	v_mfma_f32_16x16x32_bf16 v[16:19], v[142:145], v[202:205], v[16:19]
	v_mfma_f32_16x16x32_bf16 v[16:19], v[146:149], v[206:209], v[16:19]
	s_setprio 0
	s_setprio 1
	s_add_i32 s60, s60, 2
	s_add_u32 s50, s50, 0x100
	s_addc_u32 s51, s51, 0
	s_add_u32 s43, s43, 0x100
	s_addc_u32 s45, s45, 0
	s_nop 0
	v_mfma_f32_16x16x32_bf16 v[56:59], v[162:165], v[178:181], v[56:59]
	v_mfma_f32_16x16x32_bf16 v[56:59], v[166:169], v[182:185], v[56:59]
	v_mfma_f32_16x16x32_bf16 v[52:55], v[170:173], v[178:181], v[52:55]
	v_mfma_f32_16x16x32_bf16 v[52:55], v[174:177], v[182:185], v[52:55]
	v_mfma_f32_16x16x32_bf16 v[36:39], v[170:173], v[186:189], v[36:39]
	v_mfma_f32_16x16x32_bf16 v[36:39], v[174:177], v[190:193], v[36:39]
	v_mfma_f32_16x16x32_bf16 v[40:43], v[162:165], v[186:189], v[40:43]
	v_mfma_f32_16x16x32_bf16 v[40:43], v[166:169], v[190:193], v[40:43]
	v_mfma_f32_16x16x32_bf16 v[24:27], v[162:165], v[194:197], v[24:27]
	v_mfma_f32_16x16x32_bf16 v[24:27], v[166:169], v[198:201], v[24:27]
	v_mfma_f32_16x16x32_bf16 v[20:23], v[170:173], v[194:197], v[20:23]
	v_mfma_f32_16x16x32_bf16 v[20:23], v[174:177], v[198:201], v[20:23]
	v_mfma_f32_16x16x32_bf16 v[4:7], v[170:173], v[202:205], v[4:7]
	v_mfma_f32_16x16x32_bf16 v[4:7], v[174:177], v[206:209], v[4:7]
	v_mfma_f32_16x16x32_bf16 v[8:11], v[162:165], v[202:205], v[8:11]
	v_mfma_f32_16x16x32_bf16 v[8:11], v[166:169], v[206:209], v[8:11]
	s_barrier
	s_cmp_gt_u32 s60, 61
	s_cbranch_scc0 .LBB0_2089
	s_setprio 0
	s_and_b64 vcc, exec, s[40:41]
	s_cbranch_vccz .LBB0_2092
	s_barrier

; #define PG8_STAGE(bufoff, gbase, voff) do { _Pragma("unroll") for (int _i = 0; _i < 2; ++_i) \
;         __builtin_amdgcn_global_load_lds((const unsigned*)((const char*)(gbase) + (voff)[_i]), (PG8_LAS unsigned*)(lds + (bufoff) + ldsw + _i * 8192), 16, 0, 0); } while (0)
; #define PG8_LDA(dst, b, h) do { _Pragma("unroll") for (int m = 0; m < 4; ++m) _Pragma("unroll") for (int k = 0; k < 2; ++k) dst[m][k] = *(const PG8_LAS bf16x8*)(lds + PG8_SA(b, h) + aoff + m * 2048 + k * 1024); } while (0)
; #define PG8_LDB(dst, b, h) do { _Pragma("unroll") for (int n = 0; n < 2; ++n) _Pragma("unroll") for (int k = 0; k < 2; ++k) dst[n][k] = *(const PG8_LAS bf16x8*)(lds + PG8_SB(b, h) + boff + n * 2048 + k * 1024); } while (0)
; #define PG8_MMA(ai, bj, At, Bt) do { __builtin_amdgcn_s_setprio(1); _Pragma("unroll") for (int m = 0; m < 4; ++m) _Pragma("unroll") for (int n = 0; n < 2; ++n) _Pragma("unroll") for (int k = 0; k < 2; ++k) \
;         acc[ai][bj][m][n] = __builtin_amdgcn_mfma_f32_16x16x32_bf16(Bt[n][k], At[m][k], acc[ai][bj][m][n], 0, 0, 0); __builtin_amdgcn_s_setprio(0); } while (0)
; #define PG8_WAIT_V(n) asm volatile("s_waitcnt vmcnt(" #n ")" ::: "memory")
; #define PG8_WAIT_L(n) asm volatile("s_waitcnt lgkmcnt(" #n ")" ::: "memory")
; #define PG8_BAR __builtin_amdgcn_s_barrier()
; #define PG8_SCHED __builtin_amdgcn_sched_barrier(0)
; template <class Epi, class Sched, bool ALIGN_EPI = false, bool SP2 = false>
; __device__ __forceinline__ void gemm_phase(PG8_LAS unsigned char* lds, const Gemm g, const Sched& S, const Epi& E) {
;     ...
;             PG8_LDB(B0, 0, 0); PG8_LDB(B1, 0, 1); PG8_SCHED; PG8_LDA(At, 0, 0); PG8_STAGE(PG8_SA(1, 1), a1 + hstep, voffA);
;             PG8_WAIT_V(8); PG8_WAIT_L(0); PG8_BAR; PG8_MMA(0, 0, At, B0); PG8_MMA(0, 1, At, B1); PG8_BAR; PG8_SCHED;
;             PG8_LDA(At, 0, 1); PG8_STAGE(PG8_SB(0, 0), b2, voffB); PG8_STAGE(PG8_SB(0, 1), b2 + hstep, voffB); PG8_STAGE(PG8_SA(0, 0), a2, voffA);
;             PG8_WAIT_V(8); PG8_WAIT_L(0); PG8_BAR; PG8_MMA(1, 0, At, B0); PG8_MMA(1, 1, At, B1); PG8_BAR; PG8_SCHED;
.LBB0_2115:
	s_setprio 0
	s_waitcnt vmcnt(0)
	ds_read_b128 v[132:135], v188
	ds_read_b128 v[136:139], v188 offset:1024
	ds_read_b128 v[152:155], v188 offset:2048
	ds_read_b128 v[156:159], v188 offset:3072
	ds_read_b128 v[160:163], v188 offset:16384
	ds_read_b128 v[164:167], v188 offset:17408
	ds_read_b128 v[168:171], v188 offset:18432
	ds_read_b128 v[172:175], v188 offset:19456
	ds_read_b128 v[176:179], v194
	ds_read_b128 v[180:183], v194 offset:1024
	ds_read_b128 v[184:187], v194 offset:2048
	ds_read_b128 v[196:199], v194 offset:3072
	ds_read_b128 v[200:203], v194 offset:4096
	ds_read_b128 v[204:207], v194 offset:5120
	ds_read_b128 v[208:211], v194 offset:6144
	ds_read_b128 v[212:215], v194 offset:7168
	s_add_u32 s0, s40, 0xfff00080
	s_addc_u32 s1, s41, -1
	s_add_i32 s77, 0, 0x10000
	s_cmp_eq_u32 s76, 60
	s_cselect_b32 s27, s49, s1
	s_cselect_b32 s26, s57, s0
	s_cselect_b32 s1, s47, s59
	s_cselect_b32 s0, s73, s58
	s_add_i32 s80, 0, 0x14000
	s_add_u32 s100, s40, 0xfff00000
	s_addc_u32 s101, s41, -1
	s_mov_b32 m0, s62
	s_nop 0
	global_load_lds_dwordx4 v140, s[100:101]
	s_mov_b32 m0, s63
	s_nop 0
	global_load_lds_dwordx4 v142, s[100:101]
	s_add_i32 m0, s11, 0xc000
	s_nop 0
	global_load_lds_dwordx4 v148, s[40:41]
	s_add_i32 m0, s11, 0xe000
	s_nop 0
	global_load_lds_dwordx4 v150, s[40:41]
	s_nop 0
	s_setprio 1
	s_waitcnt vmcnt(8)
	s_waitcnt lgkmcnt(0)
	s_barrier
	v_mfma_f32_16x16x32_bf16 v[128:131], v[132:135], v[176:179], v[128:131]
	v_mfma_f32_16x16x32_bf16 v[128:131], v[136:139], v[180:183], v[128:131]
	v_mfma_f32_16x16x32_bf16 v[124:127], v[152:155], v[176:179], v[124:127]
	v_mfma_f32_16x16x32_bf16 v[124:127], v[156:159], v[180:183], v[124:127]
	v_mfma_f32_16x16x32_bf16 v[108:111], v[152:155], v[184:187], v[108:111]
	v_mfma_f32_16x16x32_bf16 v[108:111], v[156:159], v[196:199], v[108:111]
	v_mfma_f32_16x16x32_bf16 v[112:115], v[132:135], v[184:187], v[112:115]
	v_mfma_f32_16x16x32_bf16 v[112:115], v[136:139], v[196:199], v[112:115]
	v_mfma_f32_16x16x32_bf16 v[96:99], v[132:135], v[200:203], v[96:99]
	v_mfma_f32_16x16x32_bf16 v[96:99], v[136:139], v[204:207], v[96:99]
	v_mfma_f32_16x16x32_bf16 v[92:95], v[152:155], v[200:203], v[92:95]
	v_mfma_f32_16x16x32_bf16 v[92:95], v[156:159], v[204:207], v[92:95]
	v_mfma_f32_16x16x32_bf16 v[76:79], v[152:155], v[208:211], v[76:79]
	v_mfma_f32_16x16x32_bf16 v[76:79], v[156:159], v[212:215], v[76:79]
	v_mfma_f32_16x16x32_bf16 v[80:83], v[132:135], v[208:211], v[80:83]
	v_mfma_f32_16x16x32_bf16 v[80:83], v[136:139], v[212:215], v[80:83]
	s_setprio 0
	s_setprio 1
	v_mfma_f32_16x16x32_bf16 v[120:123], v[160:163], v[176:179], v[120:123]
	v_mfma_f32_16x16x32_bf16 v[120:123], v[164:167], v[180:183], v[120:123]
	v_mfma_f32_16x16x32_bf16 v[116:119], v[168:171], v[176:179], v[116:119]
	v_mfma_f32_16x16x32_bf16 v[116:119], v[172:175], v[180:183], v[116:119]
	v_mfma_f32_16x16x32_bf16 v[100:103], v[168:171], v[184:187], v[100:103]
	v_mfma_f32_16x16x32_bf16 v[100:103], v[172:175], v[196:199], v[100:103]
	v_mfma_f32_16x16x32_bf16 v[104:107], v[160:163], v[184:187], v[104:107]
	v_mfma_f32_16x16x32_bf16 v[104:107], v[164:167], v[196:199], v[104:107]
	v_mfma_f32_16x16x32_bf16 v[88:91], v[160:163], v[200:203], v[88:91]
	v_mfma_f32_16x16x32_bf16 v[88:91], v[164:167], v[204:207], v[88:91]
	v_mfma_f32_16x16x32_bf16 v[84:87], v[168:171], v[200:203], v[84:87]
	v_mfma_f32_16x16x32_bf16 v[84:87], v[172:175], v[204:207], v[84:87]
	v_mfma_f32_16x16x32_bf16 v[68:71], v[168:171], v[208:211], v[68:71]
	v_mfma_f32_16x16x32_bf16 v[68:71], v[172:175], v[212:215], v[68:71]
	v_mfma_f32_16x16x32_bf16 v[72:75], v[160:163], v[208:211], v[72:75]
	v_mfma_f32_16x16x32_bf16 v[72:75], v[164:167], v[212:215], v[72:75]
	s_barrier
	s_setprio 0
	ds_read_b128 v[176:179], v194 offset:16384
	ds_read_b128 v[180:183], v194 offset:17408
	ds_read_b128 v[184:187], v194 offset:18432
	ds_read_b128 v[196:199], v194 offset:19456
	ds_read_b128 v[200:203], v194 offset:20480
	ds_read_b128 v[204:207], v194 offset:21504
	ds_read_b128 v[208:211], v194 offset:22528
	ds_read_b128 v[212:215], v194 offset:23552
	s_add_i32 s77, s77, s10
	s_mov_b32 m0, s77
	s_nop 0
	global_load_lds_dwordx4 v2, s[0:1]
	s_add_i32 m0, s77, 0x2000
	s_add_u32 s78, s0, 0x100000
	s_addc_u32 s79, s1, 0
	s_add_i32 s77, s80, s10
	global_load_lds_dwordx4 v144, s[0:1]
	s_mov_b32 m0, s77
	s_nop 0
	global_load_lds_dwordx4 v2, s[78:79]
	s_add_i32 m0, s77, 0x2000
	s_nop 0
	global_load_lds_dwordx4 v144, s[78:79]
	s_setprio 1
	s_waitcnt vmcnt(6)
	s_waitcnt lgkmcnt(0)
	s_barrier
	v_mfma_f32_16x16x32_bf16 v[64:67], v[132:135], v[176:179], v[64:67]
	v_mfma_f32_16x16x32_bf16 v[64:67], v[136:139], v[180:183], v[64:67]
	v_mfma_f32_16x16x32_bf16 v[60:63], v[152:155], v[176:179], v[60:63]
	v_mfma_f32_16x16x32_bf16 v[60:63], v[156:159], v[180:183], v[60:63]
	v_mfma_f32_16x16x32_bf16 v[44:47], v[152:155], v[184:187], v[44:47]
	v_mfma_f32_16x16x32_bf16 v[44:47], v[156:159], v[196:199], v[44:47]
	v_mfma_f32_16x16x32_bf16 v[48:51], v[132:135], v[184:187], v[48:51]
	v_mfma_f32_16x16x32_bf16 v[48:51], v[136:139], v[196:199], v[48:51]
	v_mfma_f32_16x16x32_bf16 v[32:35], v[132:135], v[200:203], v[32:35]
	v_mfma_f32_16x16x32_bf16 v[32:35], v[136:139], v[204:207], v[32:35]
	v_mfma_f32_16x16x32_bf16 v[28:31], v[152:155], v[200:203], v[28:31]
	v_mfma_f32_16x16x32_bf16 v[28:31], v[156:159], v[204:207], v[28:31]
	v_mfma_f32_16x16x32_bf16 v[12:15], v[152:155], v[208:211], v[12:15]
	v_mfma_f32_16x16x32_bf16 v[12:15], v[156:159], v[212:215], v[12:15]
	v_mfma_f32_16x16x32_bf16 v[16:19], v[132:135], v[208:211], v[16:19]
	v_mfma_f32_16x16x32_bf16 v[16:19], v[136:139], v[212:215], v[16:19]
	s_setprio 0
	s_setprio 1
	v_mfma_f32_16x16x32_bf16 v[56:59], v[160:163], v[176:179], v[56:59]
	v_mfma_f32_16x16x32_bf16 v[56:59], v[164:167], v[180:183], v[56:59]
	v_mfma_f32_16x16x32_bf16 v[52:55], v[168:171], v[176:179], v[52:55]
	v_mfma_f32_16x16x32_bf16 v[52:55], v[172:175], v[180:183], v[52:55]
	v_mfma_f32_16x16x32_bf16 v[36:39], v[168:171], v[184:187], v[36:39]
	v_mfma_f32_16x16x32_bf16 v[36:39], v[172:175], v[196:199], v[36:39]
	v_mfma_f32_16x16x32_bf16 v[40:43], v[160:163], v[184:187], v[40:43]
	v_mfma_f32_16x16x32_bf16 v[40:43], v[164:167], v[196:199], v[40:43]
	v_mfma_f32_16x16x32_bf16 v[24:27], v[160:163], v[200:203], v[24:27]
	v_mfma_f32_16x16x32_bf16 v[24:27], v[164:167], v[204:207], v[24:27]
	v_mfma_f32_16x16x32_bf16 v[20:23], v[168:171], v[200:203], v[20:23]
	v_mfma_f32_16x16x32_bf16 v[20:23], v[172:175], v[204:207], v[20:23]
	v_mfma_f32_16x16x32_bf16 v[4:7], v[168:171], v[208:211], v[4:7]
	v_mfma_f32_16x16x32_bf16 v[4:7], v[172:175], v[212:215], v[4:7]
	v_mfma_f32_16x16x32_bf16 v[8:11], v[160:163], v[208:211], v[8:11]
	v_mfma_f32_16x16x32_bf16 v[8:11], v[164:167], v[212:215], v[8:11]
	s_barrier
; #define PG8_STAGE(bufoff, gbase, voff) do { _Pragma("unroll") for (int _i = 0; _i < 2; ++_i) \
;         __builtin_amdgcn_global_load_lds((const unsigned*)((const char*)(gbase) + (voff)[_i]), (PG8_LAS unsigned*)(lds + (bufoff) + ldsw + _i * 8192), 16, 0, 0); } while (0)
; #define PG8_LDA(dst, b, h) do { _Pragma("unroll") for (int m = 0; m < 4; ++m) _Pragma("unroll") for (int k = 0; k < 2; ++k) dst[m][k] = *(const PG8_LAS bf16x8*)(lds + PG8_SA(b, h) + aoff + m * 2048 + k * 1024); } while (0)
; #define PG8_LDB(dst, b, h) do { _Pragma("unroll") for (int n = 0; n < 2; ++n) _Pragma("unroll") for (int k = 0; k < 2; ++k) dst[n][k] = *(const PG8_LAS bf16x8*)(lds + PG8_SB(b, h) + boff + n * 2048 + k * 1024); } while (0)
; #define PG8_MMA(ai, bj, At, Bt) do { __builtin_amdgcn_s_setprio(1); _Pragma("unroll") for (int m = 0; m < 4; ++m) _Pragma("unroll") for (int n = 0; n < 2; ++n) _Pragma("unroll") for (int k = 0; k < 2; ++k) \
;         acc[ai][bj][m][n] = __builtin_amdgcn_mfma_f32_16x16x32_bf16(Bt[n][k], At[m][k], acc[ai][bj][m][n], 0, 0, 0); __builtin_amdgcn_s_setprio(0); } while (0)
; #define PG8_WAIT_V(n) asm volatile("s_waitcnt vmcnt(" #n ")" ::: "memory")
; #define PG8_WAIT_L(n) asm volatile("s_waitcnt lgkmcnt(" #n ")" ::: "memory")
; #define PG8_BAR __builtin_amdgcn_s_barrier()
; #define PG8_SCHED __builtin_amdgcn_sched_barrier(0)
; template <class Epi, class Sched, bool ALIGN_EPI = false, bool SP2 = false>
; __device__ __forceinline__ void gemm_phase(PG8_LAS unsigned char* lds, const Gemm g, const Sched& S, const Epi& E) {
;     ...
;             PG8_LDB(B0, 1, 0); PG8_LDB(B1, 1, 1); PG8_SCHED; PG8_LDA(At, 1, 0); PG8_STAGE(PG8_SA(0, 1), a2 + hstep, voffA);
;             PG8_WAIT_V(8); PG8_WAIT_L(0); PG8_BAR; PG8_MMA(0, 0, At, B0); PG8_MMA(0, 1, At, B1); PG8_BAR; PG8_SCHED;
;             PG8_LDA(At, 1, 1); PG8_STAGE(PG8_SB(1, 0), b3, voffB); PG8_STAGE(PG8_SB(1, 1), b3 + hstep, voffB); PG8_STAGE(PG8_SA(1, 0), a3, voffA);
;             PG8_WAIT_V(8); PG8_WAIT_L(0); PG8_BAR; PG8_MMA(1, 0, At, B0); PG8_MMA(1, 1, At, B1); PG8_BAR; PG8_SCHED;
	s_setprio 0
	ds_read_b128 v[132:135], v188 offset:32768
	ds_read_b128 v[136:139], v188 offset:33792
	ds_read_b128 v[152:155], v188 offset:34816
	ds_read_b128 v[156:159], v188 offset:35840
	ds_read_b128 v[160:163], v188 offset:49152
	ds_read_b128 v[164:167], v188 offset:50176
	ds_read_b128 v[168:171], v188 offset:51200
	ds_read_b128 v[172:175], v188 offset:52224
	ds_read_b128 v[176:179], v194 offset:32768
	ds_read_b128 v[180:183], v194 offset:33792
	ds_read_b128 v[184:187], v194 offset:34816
	ds_read_b128 v[196:199], v194 offset:35840
	ds_read_b128 v[200:203], v194 offset:36864
	ds_read_b128 v[204:207], v194 offset:37888
	ds_read_b128 v[208:211], v194 offset:38912
	ds_read_b128 v[212:215], v194 offset:39936
	s_add_i32 s77, 0, 0x18000
	s_add_i32 s78, 0, 0x1c000
	s_mov_b32 m0, s11
	s_nop 0
	global_load_lds_dwordx4 v140, s[26:27]
	s_mov_b32 m0, s55
	s_nop 0
	global_load_lds_dwordx4 v142, s[26:27]
	s_add_u32 s26, s26, 0x100000
	s_addc_u32 s27, s27, 0
	s_mov_b32 m0, s60
	s_nop 0
	global_load_lds_dwordx4 v140, s[26:27]
	s_mov_b32 m0, s61
	s_nop 0
	global_load_lds_dwordx4 v142, s[26:27]
	s_nop 0
	s_setprio 1
	s_waitcnt vmcnt(8)
	s_waitcnt lgkmcnt(0)
	s_barrier
	v_mfma_f32_16x16x32_bf16 v[128:131], v[132:135], v[176:179], v[128:131]
	v_mfma_f32_16x16x32_bf16 v[128:131], v[136:139], v[180:183], v[128:131]
	v_mfma_f32_16x16x32_bf16 v[124:127], v[152:155], v[176:179], v[124:127]
	v_mfma_f32_16x16x32_bf16 v[124:127], v[156:159], v[180:183], v[124:127]
	v_mfma_f32_16x16x32_bf16 v[108:111], v[152:155], v[184:187], v[108:111]
	v_mfma_f32_16x16x32_bf16 v[108:111], v[156:159], v[196:199], v[108:111]
	v_mfma_f32_16x16x32_bf16 v[112:115], v[132:135], v[184:187], v[112:115]
	v_mfma_f32_16x16x32_bf16 v[112:115], v[136:139], v[196:199], v[112:115]
	v_mfma_f32_16x16x32_bf16 v[96:99], v[132:135], v[200:203], v[96:99]
	v_mfma_f32_16x16x32_bf16 v[96:99], v[136:139], v[204:207], v[96:99]
	v_mfma_f32_16x16x32_bf16 v[92:95], v[152:155], v[200:203], v[92:95]
	v_mfma_f32_16x16x32_bf16 v[92:95], v[156:159], v[204:207], v[92:95]
	v_mfma_f32_16x16x32_bf16 v[76:79], v[152:155], v[208:211], v[76:79]
	v_mfma_f32_16x16x32_bf16 v[76:79], v[156:159], v[212:215], v[76:79]
	v_mfma_f32_16x16x32_bf16 v[80:83], v[132:135], v[208:211], v[80:83]
	v_mfma_f32_16x16x32_bf16 v[80:83], v[136:139], v[212:215], v[80:83]
	s_setprio 0
	s_setprio 1
	v_mfma_f32_16x16x32_bf16 v[120:123], v[160:163], v[176:179], v[120:123]
	v_mfma_f32_16x16x32_bf16 v[120:123], v[164:167], v[180:183], v[120:123]
	v_mfma_f32_16x16x32_bf16 v[116:119], v[168:171], v[176:179], v[116:119]
	v_mfma_f32_16x16x32_bf16 v[116:119], v[172:175], v[180:183], v[116:119]
	v_mfma_f32_16x16x32_bf16 v[100:103], v[168:171], v[184:187], v[100:103]
	v_mfma_f32_16x16x32_bf16 v[100:103], v[172:175], v[196:199], v[100:103]
	v_mfma_f32_16x16x32_bf16 v[104:107], v[160:163], v[184:187], v[104:107]
	v_mfma_f32_16x16x32_bf16 v[104:107], v[164:167], v[196:199], v[104:107]
	v_mfma_f32_16x16x32_bf16 v[88:91], v[160:163], v[200:203], v[88:91]
	v_mfma_f32_16x16x32_bf16 v[88:91], v[164:167], v[204:207], v[88:91]
	v_mfma_f32_16x16x32_bf16 v[84:87], v[168:171], v[200:203], v[84:87]
	v_mfma_f32_16x16x32_bf16 v[84:87], v[172:175], v[204:207], v[84:87]
	v_mfma_f32_16x16x32_bf16 v[68:71], v[168:171], v[208:211], v[68:71]
	v_mfma_f32_16x16x32_bf16 v[68:71], v[172:175], v[212:215], v[68:71]
	v_mfma_f32_16x16x32_bf16 v[72:75], v[160:163], v[208:211], v[72:75]
	v_mfma_f32_16x16x32_bf16 v[72:75], v[164:167], v[212:215], v[72:75]
	s_barrier
	s_setprio 0
	ds_read_b128 v[176:179], v194 offset:49152
	ds_read_b128 v[180:183], v194 offset:50176
	ds_read_b128 v[184:187], v194 offset:51200
	ds_read_b128 v[196:199], v194 offset:52224
	ds_read_b128 v[200:203], v194 offset:53248
	ds_read_b128 v[204:207], v194 offset:54272
	ds_read_b128 v[208:211], v194 offset:55296
	ds_read_b128 v[212:215], v194 offset:56320
	s_add_i32 s26, s77, s10
	s_mov_b32 m0, s26
	s_add_u32 s0, s0, 0x80
	s_addc_u32 s1, s1, 0
	global_load_lds_dwordx4 v2, s[0:1]
	s_add_i32 m0, s26, 0x2000
	s_add_i32 s26, s78, s10
	global_load_lds_dwordx4 v144, s[0:1]
	s_add_u32 s0, s0, 0x100000
	s_addc_u32 s1, s1, 0
	s_mov_b32 m0, s26
	s_nop 0
	global_load_lds_dwordx4 v2, s[0:1]
	s_add_i32 m0, s26, 0x2000
	s_nop 0
	global_load_lds_dwordx4 v144, s[0:1]
	s_setprio 1
	s_waitcnt vmcnt(6)
	s_waitcnt lgkmcnt(0)
	s_barrier
	v_mfma_f32_16x16x32_bf16 v[64:67], v[132:135], v[176:179], v[64:67]
	v_mfma_f32_16x16x32_bf16 v[64:67], v[136:139], v[180:183], v[64:67]
	v_mfma_f32_16x16x32_bf16 v[60:63], v[152:155], v[176:179], v[60:63]
	v_mfma_f32_16x16x32_bf16 v[60:63], v[156:159], v[180:183], v[60:63]
	v_mfma_f32_16x16x32_bf16 v[44:47], v[152:155], v[184:187], v[44:47]
	v_mfma_f32_16x16x32_bf16 v[44:47], v[156:159], v[196:199], v[44:47]
	v_mfma_f32_16x16x32_bf16 v[48:51], v[132:135], v[184:187], v[48:51]
	v_mfma_f32_16x16x32_bf16 v[48:51], v[136:139], v[196:199], v[48:51]
	v_mfma_f32_16x16x32_bf16 v[32:35], v[132:135], v[200:203], v[32:35]
	v_mfma_f32_16x16x32_bf16 v[32:35], v[136:139], v[204:207], v[32:35]
	v_mfma_f32_16x16x32_bf16 v[28:31], v[152:155], v[200:203], v[28:31]
	v_mfma_f32_16x16x32_bf16 v[28:31], v[156:159], v[204:207], v[28:31]
	v_mfma_f32_16x16x32_bf16 v[12:15], v[152:155], v[208:211], v[12:15]
	v_mfma_f32_16x16x32_bf16 v[12:15], v[156:159], v[212:215], v[12:15]
	v_mfma_f32_16x16x32_bf16 v[16:19], v[132:135], v[208:211], v[16:19]
	v_mfma_f32_16x16x32_bf16 v[16:19], v[136:139], v[212:215], v[16:19]
	s_setprio 0
	s_setprio 1
	s_add_i32 s76, s76, 2
	s_add_u32 s40, s40, 0x100
	s_addc_u32 s41, s41, 0
	s_add_u32 s58, s58, 0x100
	s_addc_u32 s59, s59, 0
	s_nop 0
	v_mfma_f32_16x16x32_bf16 v[56:59], v[160:163], v[176:179], v[56:59]
	v_mfma_f32_16x16x32_bf16 v[56:59], v[164:167], v[180:183], v[56:59]
	v_mfma_f32_16x16x32_bf16 v[52:55], v[168:171], v[176:179], v[52:55]
	v_mfma_f32_16x16x32_bf16 v[52:55], v[172:175], v[180:183], v[52:55]
	v_mfma_f32_16x16x32_bf16 v[36:39], v[168:171], v[184:187], v[36:39]
	v_mfma_f32_16x16x32_bf16 v[36:39], v[172:175], v[196:199], v[36:39]
	v_mfma_f32_16x16x32_bf16 v[40:43], v[160:163], v[184:187], v[40:43]
	v_mfma_f32_16x16x32_bf16 v[40:43], v[164:167], v[196:199], v[40:43]
	v_mfma_f32_16x16x32_bf16 v[24:27], v[160:163], v[200:203], v[24:27]
	v_mfma_f32_16x16x32_bf16 v[24:27], v[164:167], v[204:207], v[24:27]
	v_mfma_f32_16x16x32_bf16 v[20:23], v[168:171], v[200:203], v[20:23]
	v_mfma_f32_16x16x32_bf16 v[20:23], v[172:175], v[204:207], v[20:23]
	v_mfma_f32_16x16x32_bf16 v[4:7], v[168:171], v[208:211], v[4:7]
	v_mfma_f32_16x16x32_bf16 v[4:7], v[172:175], v[212:215], v[4:7]
	v_mfma_f32_16x16x32_bf16 v[8:11], v[160:163], v[208:211], v[8:11]
	v_mfma_f32_16x16x32_bf16 v[8:11], v[164:167], v[212:215], v[8:11]
	s_barrier
	s_cmp_gt_u32 s76, 61
	s_cbranch_scc0 .LBB0_2115
	s_setprio 0
	s_and_b64 vcc, exec, s[36:37]
	s_cbranch_vccz .LBB0_2118
	s_barrier

; #define PG8_STAGE(bufoff, gbase, voff) do { _Pragma("unroll") for (int _i = 0; _i < 2; ++_i) \
;         __builtin_amdgcn_global_load_lds((const unsigned*)((const char*)(gbase) + (voff)[_i]), (PG8_LAS unsigned*)(lds + (bufoff) + ldsw + _i * 8192), 16, 0, 0); } while (0)
; #define PG8_LDA(dst, b, h) do { _Pragma("unroll") for (int m = 0; m < 4; ++m) _Pragma("unroll") for (int k = 0; k < 2; ++k) dst[m][k] = *(const PG8_LAS bf16x8*)(lds + PG8_SA(b, h) + aoff + m * 2048 + k * 1024); } while (0)
; #define PG8_LDB(dst, b, h) do { _Pragma("unroll") for (int n = 0; n < 2; ++n) _Pragma("unroll") for (int k = 0; k < 2; ++k) dst[n][k] = *(const PG8_LAS bf16x8*)(lds + PG8_SB(b, h) + boff + n * 2048 + k * 1024); } while (0)
; #define PG8_MMA(ai, bj, At, Bt) do { __builtin_amdgcn_s_setprio(1); _Pragma("unroll") for (int m = 0; m < 4; ++m) _Pragma("unroll") for (int n = 0; n < 2; ++n) _Pragma("unroll") for (int k = 0; k < 2; ++k) \
;         acc[ai][bj][m][n] = __builtin_amdgcn_mfma_f32_16x16x32_bf16(Bt[n][k], At[m][k], acc[ai][bj][m][n], 0, 0, 0); __builtin_amdgcn_s_setprio(0); } while (0)
; #define PG8_WAIT_V(n) asm volatile("s_waitcnt vmcnt(" #n ")" ::: "memory")
; #define PG8_WAIT_L(n) asm volatile("s_waitcnt lgkmcnt(" #n ")" ::: "memory")
; #define PG8_BAR __builtin_amdgcn_s_barrier()
; #define PG8_SCHED __builtin_amdgcn_sched_barrier(0)
; template <class Epi, class Sched, bool ALIGN_EPI = false, bool SP2 = false>
; __device__ __forceinline__ void gemm_phase(PG8_LAS unsigned char* lds, const Gemm g, const Sched& S, const Epi& E) {
;     ...
;             PG8_LDB(B0, 0, 0); PG8_LDB(B1, 0, 1); PG8_SCHED; PG8_LDA(At, 0, 0); PG8_STAGE(PG8_SA(1, 1), a1 + hstep, voffA);
;             PG8_WAIT_V(8); PG8_WAIT_L(0); PG8_BAR; PG8_MMA(0, 0, At, B0); PG8_MMA(0, 1, At, B1); PG8_BAR; PG8_SCHED;
;             PG8_LDA(At, 0, 1); PG8_STAGE(PG8_SB(0, 0), b2, voffB); PG8_STAGE(PG8_SB(0, 1), b2 + hstep, voffB); PG8_STAGE(PG8_SA(0, 0), a2, voffA);
;             PG8_WAIT_V(8); PG8_WAIT_L(0); PG8_BAR; PG8_MMA(1, 0, At, B0); PG8_MMA(1, 1, At, B1); PG8_BAR; PG8_SCHED;
.LBB0_2692:
	s_setprio 0
	ds_read_b128 v[142:145], v210
	ds_read_b128 v[150:153], v210 offset:1024
	ds_read_b128 v[154:157], v210 offset:2048
	ds_read_b128 v[158:161], v210 offset:3072
	ds_read_b128 v[162:165], v210 offset:16384
	ds_read_b128 v[166:169], v210 offset:17408
	ds_read_b128 v[170:173], v210 offset:18432
	ds_read_b128 v[174:177], v210 offset:19456
	ds_read_b128 v[178:181], v149
	ds_read_b128 v[182:185], v149 offset:1024
	ds_read_b128 v[186:189], v149 offset:2048
	ds_read_b128 v[190:193], v149 offset:3072
	ds_read_b128 v[194:197], v149 offset:4096
	ds_read_b128 v[198:201], v149 offset:5120
	ds_read_b128 v[202:205], v149 offset:6144
	ds_read_b128 v[206:209], v149 offset:7168
	s_add_u32 s0, s56, 0xfffe0080
	s_addc_u32 s1, s57, -1
	s_add_i32 s63, 0, 0x10000
	s_cmp_eq_u32 s62, 4
	s_cselect_b32 s27, s51, s1
	s_cselect_b32 s26, s50, s0
	s_cselect_b32 s1, s53, s49
	s_cselect_b32 s0, s52, s47
	s_add_i32 s66, 0, 0x14000
	s_add_u32 s100, s56, 0xfffe0000
	s_addc_u32 s101, s57, -1
	s_mov_b32 m0, s58
	s_nop 0
	global_load_lds_dwordx4 v132, s[100:101]
	s_mov_b32 m0, s59
	s_nop 0
	global_load_lds_dwordx4 v134, s[100:101]
	s_add_i32 m0, s10, 0xc000
	s_nop 0
	global_load_lds_dwordx4 v138, s[56:57]
	s_add_i32 m0, s10, 0xe000
	s_nop 0
	global_load_lds_dwordx4 v140, s[56:57]
	s_setprio 1
	s_waitcnt vmcnt(8)
	s_waitcnt lgkmcnt(0)
	s_barrier
	v_mfma_f32_16x16x32_bf16 v[128:131], v[142:145], v[178:181], v[128:131]
	v_mfma_f32_16x16x32_bf16 v[128:131], v[150:153], v[182:185], v[128:131]
	v_mfma_f32_16x16x32_bf16 v[124:127], v[154:157], v[178:181], v[124:127]
	v_mfma_f32_16x16x32_bf16 v[124:127], v[158:161], v[182:185], v[124:127]
	v_mfma_f32_16x16x32_bf16 v[108:111], v[154:157], v[186:189], v[108:111]
	v_mfma_f32_16x16x32_bf16 v[108:111], v[158:161], v[190:193], v[108:111]
	v_mfma_f32_16x16x32_bf16 v[112:115], v[142:145], v[186:189], v[112:115]
	v_mfma_f32_16x16x32_bf16 v[112:115], v[150:153], v[190:193], v[112:115]
	v_mfma_f32_16x16x32_bf16 v[96:99], v[142:145], v[194:197], v[96:99]
	v_mfma_f32_16x16x32_bf16 v[96:99], v[150:153], v[198:201], v[96:99]
	v_mfma_f32_16x16x32_bf16 v[92:95], v[154:157], v[194:197], v[92:95]
	v_mfma_f32_16x16x32_bf16 v[92:95], v[158:161], v[198:201], v[92:95]
	v_mfma_f32_16x16x32_bf16 v[76:79], v[154:157], v[202:205], v[76:79]
	v_mfma_f32_16x16x32_bf16 v[76:79], v[158:161], v[206:209], v[76:79]
	v_mfma_f32_16x16x32_bf16 v[80:83], v[142:145], v[202:205], v[80:83]
	v_mfma_f32_16x16x32_bf16 v[80:83], v[150:153], v[206:209], v[80:83]
	s_setprio 0
	s_setprio 1
	v_mfma_f32_16x16x32_bf16 v[120:123], v[162:165], v[178:181], v[120:123]
	v_mfma_f32_16x16x32_bf16 v[120:123], v[166:169], v[182:185], v[120:123]
	v_mfma_f32_16x16x32_bf16 v[116:119], v[170:173], v[178:181], v[116:119]
	v_mfma_f32_16x16x32_bf16 v[116:119], v[174:177], v[182:185], v[116:119]
	v_mfma_f32_16x16x32_bf16 v[100:103], v[170:173], v[186:189], v[100:103]
	v_mfma_f32_16x16x32_bf16 v[100:103], v[174:177], v[190:193], v[100:103]
	v_mfma_f32_16x16x32_bf16 v[104:107], v[162:165], v[186:189], v[104:107]
	v_mfma_f32_16x16x32_bf16 v[104:107], v[166:169], v[190:193], v[104:107]
	v_mfma_f32_16x16x32_bf16 v[88:91], v[162:165], v[194:197], v[88:91]
	v_mfma_f32_16x16x32_bf16 v[88:91], v[166:169], v[198:201], v[88:91]
	v_mfma_f32_16x16x32_bf16 v[84:87], v[170:173], v[194:197], v[84:87]
	v_mfma_f32_16x16x32_bf16 v[84:87], v[174:177], v[198:201], v[84:87]
	v_mfma_f32_16x16x32_bf16 v[68:71], v[170:173], v[202:205], v[68:71]
	v_mfma_f32_16x16x32_bf16 v[68:71], v[174:177], v[206:209], v[68:71]
	v_mfma_f32_16x16x32_bf16 v[72:75], v[162:165], v[202:205], v[72:75]
	v_mfma_f32_16x16x32_bf16 v[72:75], v[166:169], v[206:209], v[72:75]
	s_barrier
	s_setprio 0
	ds_read_b128 v[178:181], v149 offset:16384
	ds_read_b128 v[182:185], v149 offset:17408
	ds_read_b128 v[186:189], v149 offset:18432
	ds_read_b128 v[190:193], v149 offset:19456
	ds_read_b128 v[194:197], v149 offset:20480
	ds_read_b128 v[198:201], v149 offset:21504
	ds_read_b128 v[202:205], v149 offset:22528
	ds_read_b128 v[206:209], v149 offset:23552
	s_add_i32 s63, s63, s9
	s_mov_b32 m0, s63
	s_nop 0
	global_load_lds_dwordx4 v2, s[0:1]
	s_add_i32 m0, s63, 0x2000
	s_add_u32 s64, s0, 0x20000
	s_addc_u32 s65, s1, 0
	s_add_i32 s63, s66, s9
	global_load_lds_dwordx4 v136, s[0:1]
	s_mov_b32 m0, s63
	s_nop 0
	global_load_lds_dwordx4 v2, s[64:65]
	s_add_i32 m0, s63, 0x2000
	s_nop 0
	global_load_lds_dwordx4 v136, s[64:65]
	s_setprio 1
	s_waitcnt vmcnt(6)
	s_waitcnt lgkmcnt(0)
	s_barrier
	v_mfma_f32_16x16x32_bf16 v[64:67], v[142:145], v[178:181], v[64:67]
	v_mfma_f32_16x16x32_bf16 v[64:67], v[150:153], v[182:185], v[64:67]
	v_mfma_f32_16x16x32_bf16 v[60:63], v[154:157], v[178:181], v[60:63]
	v_mfma_f32_16x16x32_bf16 v[60:63], v[158:161], v[182:185], v[60:63]
	v_mfma_f32_16x16x32_bf16 v[44:47], v[154:157], v[186:189], v[44:47]
	v_mfma_f32_16x16x32_bf16 v[44:47], v[158:161], v[190:193], v[44:47]
	v_mfma_f32_16x16x32_bf16 v[48:51], v[142:145], v[186:189], v[48:51]
	v_mfma_f32_16x16x32_bf16 v[48:51], v[150:153], v[190:193], v[48:51]
	v_mfma_f32_16x16x32_bf16 v[32:35], v[142:145], v[194:197], v[32:35]
	v_mfma_f32_16x16x32_bf16 v[32:35], v[150:153], v[198:201], v[32:35]
	v_mfma_f32_16x16x32_bf16 v[28:31], v[154:157], v[194:197], v[28:31]
	v_mfma_f32_16x16x32_bf16 v[28:31], v[158:161], v[198:201], v[28:31]
	v_mfma_f32_16x16x32_bf16 v[12:15], v[154:157], v[202:205], v[12:15]
	v_mfma_f32_16x16x32_bf16 v[12:15], v[158:161], v[206:209], v[12:15]
	v_mfma_f32_16x16x32_bf16 v[16:19], v[142:145], v[202:205], v[16:19]
	v_mfma_f32_16x16x32_bf16 v[16:19], v[150:153], v[206:209], v[16:19]
	s_setprio 0
	s_setprio 1
	v_mfma_f32_16x16x32_bf16 v[56:59], v[162:165], v[178:181], v[56:59]
	v_mfma_f32_16x16x32_bf16 v[56:59], v[166:169], v[182:185], v[56:59]
	v_mfma_f32_16x16x32_bf16 v[52:55], v[170:173], v[178:181], v[52:55]
	v_mfma_f32_16x16x32_bf16 v[52:55], v[174:177], v[182:185], v[52:55]
	v_mfma_f32_16x16x32_bf16 v[36:39], v[170:173], v[186:189], v[36:39]
	v_mfma_f32_16x16x32_bf16 v[36:39], v[174:177], v[190:193], v[36:39]
	v_mfma_f32_16x16x32_bf16 v[40:43], v[162:165], v[186:189], v[40:43]
	v_mfma_f32_16x16x32_bf16 v[40:43], v[166:169], v[190:193], v[40:43]
	v_mfma_f32_16x16x32_bf16 v[24:27], v[162:165], v[194:197], v[24:27]
	v_mfma_f32_16x16x32_bf16 v[24:27], v[166:169], v[198:201], v[24:27]
	v_mfma_f32_16x16x32_bf16 v[20:23], v[170:173], v[194:197], v[20:23]
	v_mfma_f32_16x16x32_bf16 v[20:23], v[174:177], v[198:201], v[20:23]
	v_mfma_f32_16x16x32_bf16 v[4:7], v[170:173], v[202:205], v[4:7]
	v_mfma_f32_16x16x32_bf16 v[4:7], v[174:177], v[206:209], v[4:7]
	v_mfma_f32_16x16x32_bf16 v[8:11], v[162:165], v[202:205], v[8:11]
	v_mfma_f32_16x16x32_bf16 v[8:11], v[166:169], v[206:209], v[8:11]
	s_barrier
; #define PG8_STAGE(bufoff, gbase, voff) do { _Pragma("unroll") for (int _i = 0; _i < 2; ++_i) \
;         __builtin_amdgcn_global_load_lds((const unsigned*)((const char*)(gbase) + (voff)[_i]), (PG8_LAS unsigned*)(lds + (bufoff) + ldsw + _i * 8192), 16, 0, 0); } while (0)
; #define PG8_LDA(dst, b, h) do { _Pragma("unroll") for (int m = 0; m < 4; ++m) _Pragma("unroll") for (int k = 0; k < 2; ++k) dst[m][k] = *(const PG8_LAS bf16x8*)(lds + PG8_SA(b, h) + aoff + m * 2048 + k * 1024); } while (0)
; #define PG8_LDB(dst, b, h) do { _Pragma("unroll") for (int n = 0; n < 2; ++n) _Pragma("unroll") for (int k = 0; k < 2; ++k) dst[n][k] = *(const PG8_LAS bf16x8*)(lds + PG8_SB(b, h) + boff + n * 2048 + k * 1024); } while (0)
; #define PG8_MMA(ai, bj, At, Bt) do { __builtin_amdgcn_s_setprio(1); _Pragma("unroll") for (int m = 0; m < 4; ++m) _Pragma("unroll") for (int n = 0; n < 2; ++n) _Pragma("unroll") for (int k = 0; k < 2; ++k) \
;         acc[ai][bj][m][n] = __builtin_amdgcn_mfma_f32_16x16x32_bf16(Bt[n][k], At[m][k], acc[ai][bj][m][n], 0, 0, 0); __builtin_amdgcn_s_setprio(0); } while (0)
; #define PG8_WAIT_V(n) asm volatile("s_waitcnt vmcnt(" #n ")" ::: "memory")
; #define PG8_WAIT_L(n) asm volatile("s_waitcnt lgkmcnt(" #n ")" ::: "memory")
; #define PG8_BAR __builtin_amdgcn_s_barrier()
; #define PG8_SCHED __builtin_amdgcn_sched_barrier(0)
; template <class Epi, class Sched, bool ALIGN_EPI = false, bool SP2 = false>
; __device__ __forceinline__ void gemm_phase(PG8_LAS unsigned char* lds, const Gemm g, const Sched& S, const Epi& E) {
;     ...
;             PG8_LDB(B0, 1, 0); PG8_LDB(B1, 1, 1); PG8_SCHED; PG8_LDA(At, 1, 0); PG8_STAGE(PG8_SA(0, 1), a2 + hstep, voffA);
;             PG8_WAIT_V(8); PG8_WAIT_L(0); PG8_BAR; PG8_MMA(0, 0, At, B0); PG8_MMA(0, 1, At, B1); PG8_BAR; PG8_SCHED;
;             PG8_LDA(At, 1, 1); PG8_STAGE(PG8_SB(1, 0), b3, voffB); PG8_STAGE(PG8_SB(1, 1), b3 + hstep, voffB); PG8_STAGE(PG8_SA(1, 0), a3, voffA);
;             PG8_WAIT_V(8); PG8_WAIT_L(0); PG8_BAR; PG8_MMA(1, 0, At, B0); PG8_MMA(1, 1, At, B1); PG8_BAR; PG8_SCHED;
	s_setprio 0
	ds_read_b128 v[142:145], v210 offset:32768
	ds_read_b128 v[150:153], v210 offset:33792
	ds_read_b128 v[154:157], v210 offset:34816
	ds_read_b128 v[158:161], v210 offset:35840
	ds_read_b128 v[162:165], v210 offset:49152
	ds_read_b128 v[166:169], v210 offset:50176
	ds_read_b128 v[170:173], v210 offset:51200
	ds_read_b128 v[174:177], v210 offset:52224
	ds_read_b128 v[178:181], v149 offset:32768
	ds_read_b128 v[182:185], v149 offset:33792
	ds_read_b128 v[186:189], v149 offset:34816
	ds_read_b128 v[190:193], v149 offset:35840
	ds_read_b128 v[194:197], v149 offset:36864
	ds_read_b128 v[198:201], v149 offset:37888
	ds_read_b128 v[202:205], v149 offset:38912
	ds_read_b128 v[206:209], v149 offset:39936
	s_add_i32 s63, 0, 0x18000
	s_add_i32 s64, 0, 0x1c000
	s_mov_b32 m0, s10
	s_nop 0
	global_load_lds_dwordx4 v132, s[26:27]
	s_mov_b32 m0, s11
	s_nop 0
	global_load_lds_dwordx4 v134, s[26:27]
	s_add_u32 s26, s26, 0x20000
	s_addc_u32 s27, s27, 0
	s_mov_b32 m0, s25
	s_nop 0
	global_load_lds_dwordx4 v132, s[26:27]
	s_mov_b32 m0, s55
	s_nop 0
	global_load_lds_dwordx4 v134, s[26:27]
	s_nop 0
	s_setprio 1
	s_waitcnt vmcnt(8)
	s_waitcnt lgkmcnt(0)
	s_barrier
	v_mfma_f32_16x16x32_bf16 v[128:131], v[142:145], v[178:181], v[128:131]
	v_mfma_f32_16x16x32_bf16 v[128:131], v[150:153], v[182:185], v[128:131]
	v_mfma_f32_16x16x32_bf16 v[124:127], v[154:157], v[178:181], v[124:127]
	v_mfma_f32_16x16x32_bf16 v[124:127], v[158:161], v[182:185], v[124:127]
	v_mfma_f32_16x16x32_bf16 v[108:111], v[154:157], v[186:189], v[108:111]
	v_mfma_f32_16x16x32_bf16 v[108:111], v[158:161], v[190:193], v[108:111]
	v_mfma_f32_16x16x32_bf16 v[112:115], v[142:145], v[186:189], v[112:115]
	v_mfma_f32_16x16x32_bf16 v[112:115], v[150:153], v[190:193], v[112:115]
	v_mfma_f32_16x16x32_bf16 v[96:99], v[142:145], v[194:197], v[96:99]
	v_mfma_f32_16x16x32_bf16 v[96:99], v[150:153], v[198:201], v[96:99]
	v_mfma_f32_16x16x32_bf16 v[92:95], v[154:157], v[194:197], v[92:95]
	v_mfma_f32_16x16x32_bf16 v[92:95], v[158:161], v[198:201], v[92:95]
	v_mfma_f32_16x16x32_bf16 v[76:79], v[154:157], v[202:205], v[76:79]
	v_mfma_f32_16x16x32_bf16 v[76:79], v[158:161], v[206:209], v[76:79]
	v_mfma_f32_16x16x32_bf16 v[80:83], v[142:145], v[202:205], v[80:83]
	v_mfma_f32_16x16x32_bf16 v[80:83], v[150:153], v[206:209], v[80:83]
	s_setprio 0
	s_setprio 1
	v_mfma_f32_16x16x32_bf16 v[120:123], v[162:165], v[178:181], v[120:123]
	v_mfma_f32_16x16x32_bf16 v[120:123], v[166:169], v[182:185], v[120:123]
	v_mfma_f32_16x16x32_bf16 v[116:119], v[170:173], v[178:181], v[116:119]
	v_mfma_f32_16x16x32_bf16 v[116:119], v[174:177], v[182:185], v[116:119]
	v_mfma_f32_16x16x32_bf16 v[100:103], v[170:173], v[186:189], v[100:103]
	v_mfma_f32_16x16x32_bf16 v[100:103], v[174:177], v[190:193], v[100:103]
	v_mfma_f32_16x16x32_bf16 v[104:107], v[162:165], v[186:189], v[104:107]
	v_mfma_f32_16x16x32_bf16 v[104:107], v[166:169], v[190:193], v[104:107]
	v_mfma_f32_16x16x32_bf16 v[88:91], v[162:165], v[194:197], v[88:91]
	v_mfma_f32_16x16x32_bf16 v[88:91], v[166:169], v[198:201], v[88:91]
	v_mfma_f32_16x16x32_bf16 v[84:87], v[170:173], v[194:197], v[84:87]
	v_mfma_f32_16x16x32_bf16 v[84:87], v[174:177], v[198:201], v[84:87]
	v_mfma_f32_16x16x32_bf16 v[68:71], v[170:173], v[202:205], v[68:71]
	v_mfma_f32_16x16x32_bf16 v[68:71], v[174:177], v[206:209], v[68:71]
	v_mfma_f32_16x16x32_bf16 v[72:75], v[162:165], v[202:205], v[72:75]
	v_mfma_f32_16x16x32_bf16 v[72:75], v[166:169], v[206:209], v[72:75]
	s_barrier
	s_setprio 0
	ds_read_b128 v[178:181], v149 offset:49152
	ds_read_b128 v[182:185], v149 offset:50176
	ds_read_b128 v[186:189], v149 offset:51200
	ds_read_b128 v[190:193], v149 offset:52224
	ds_read_b128 v[194:197], v149 offset:53248
	ds_read_b128 v[198:201], v149 offset:54272
	ds_read_b128 v[202:205], v149 offset:55296
	ds_read_b128 v[206:209], v149 offset:56320
	s_add_i32 s26, s63, s9
	s_mov_b32 m0, s26
	s_add_u32 s0, s0, 0x80
	s_addc_u32 s1, s1, 0
	global_load_lds_dwordx4 v2, s[0:1]
	s_add_i32 m0, s26, 0x2000
	s_add_i32 s26, s64, s9
	global_load_lds_dwordx4 v136, s[0:1]
	s_add_u32 s0, s0, 0x20000
	s_addc_u32 s1, s1, 0
	s_mov_b32 m0, s26
	s_nop 0
	global_load_lds_dwordx4 v2, s[0:1]
	s_add_i32 m0, s26, 0x2000
	s_nop 0
	global_load_lds_dwordx4 v136, s[0:1]
	s_setprio 1
	s_waitcnt vmcnt(6)
	s_waitcnt lgkmcnt(0)
	s_barrier
	v_mfma_f32_16x16x32_bf16 v[64:67], v[142:145], v[178:181], v[64:67]
	v_mfma_f32_16x16x32_bf16 v[64:67], v[150:153], v[182:185], v[64:67]
	v_mfma_f32_16x16x32_bf16 v[60:63], v[154:157], v[178:181], v[60:63]
	v_mfma_f32_16x16x32_bf16 v[60:63], v[158:161], v[182:185], v[60:63]
	v_mfma_f32_16x16x32_bf16 v[44:47], v[154:157], v[186:189], v[44:47]
	v_mfma_f32_16x16x32_bf16 v[44:47], v[158:161], v[190:193], v[44:47]
	v_mfma_f32_16x16x32_bf16 v[48:51], v[142:145], v[186:189], v[48:51]
	v_mfma_f32_16x16x32_bf16 v[48:51], v[150:153], v[190:193], v[48:51]
	v_mfma_f32_16x16x32_bf16 v[32:35], v[142:145], v[194:197], v[32:35]
	v_mfma_f32_16x16x32_bf16 v[32:35], v[150:153], v[198:201], v[32:35]
	v_mfma_f32_16x16x32_bf16 v[28:31], v[154:157], v[194:197], v[28:31]
	v_mfma_f32_16x16x32_bf16 v[28:31], v[158:161], v[198:201], v[28:31]
	v_mfma_f32_16x16x32_bf16 v[12:15], v[154:157], v[202:205], v[12:15]
	v_mfma_f32_16x16x32_bf16 v[12:15], v[158:161], v[206:209], v[12:15]
	v_mfma_f32_16x16x32_bf16 v[16:19], v[142:145], v[202:205], v[16:19]
	v_mfma_f32_16x16x32_bf16 v[16:19], v[150:153], v[206:209], v[16:19]
	s_setprio 0
	s_setprio 1
	s_add_i32 s62, s62, 2
	s_add_u32 s56, s56, 0x100
	s_addc_u32 s57, s57, 0
	s_add_u32 s47, s47, 0x100
	s_addc_u32 s49, s49, 0
	s_nop 0
	v_mfma_f32_16x16x32_bf16 v[56:59], v[162:165], v[178:181], v[56:59]
	v_mfma_f32_16x16x32_bf16 v[56:59], v[166:169], v[182:185], v[56:59]
	v_mfma_f32_16x16x32_bf16 v[52:55], v[170:173], v[178:181], v[52:55]
	v_mfma_f32_16x16x32_bf16 v[52:55], v[174:177], v[182:185], v[52:55]
	v_mfma_f32_16x16x32_bf16 v[36:39], v[170:173], v[186:189], v[36:39]
	v_mfma_f32_16x16x32_bf16 v[36:39], v[174:177], v[190:193], v[36:39]
	v_mfma_f32_16x16x32_bf16 v[40:43], v[162:165], v[186:189], v[40:43]
	v_mfma_f32_16x16x32_bf16 v[40:43], v[166:169], v[190:193], v[40:43]
	v_mfma_f32_16x16x32_bf16 v[24:27], v[162:165], v[194:197], v[24:27]
	v_mfma_f32_16x16x32_bf16 v[24:27], v[166:169], v[198:201], v[24:27]
	v_mfma_f32_16x16x32_bf16 v[20:23], v[170:173], v[194:197], v[20:23]
	v_mfma_f32_16x16x32_bf16 v[20:23], v[174:177], v[198:201], v[20:23]
	v_mfma_f32_16x16x32_bf16 v[4:7], v[170:173], v[202:205], v[4:7]
	v_mfma_f32_16x16x32_bf16 v[4:7], v[174:177], v[206:209], v[4:7]
	v_mfma_f32_16x16x32_bf16 v[8:11], v[162:165], v[202:205], v[8:11]
	v_mfma_f32_16x16x32_bf16 v[8:11], v[166:169], v[206:209], v[8:11]
	s_barrier
	s_cmp_gt_u32 s62, 5
	s_cbranch_scc0 .LBB0_2692
	s_setprio 0
	s_and_b64 vcc, exec, s[44:45]
	s_cbranch_vccz .LBB0_2695
	s_barrier

; #define PG8_STAGE(bufoff, gbase, voff) do { _Pragma("unroll") for (int _i = 0; _i < 2; ++_i) \
;         __builtin_amdgcn_global_load_lds((const unsigned*)((const char*)(gbase) + (voff)[_i]), (PG8_LAS unsigned*)(lds + (bufoff) + ldsw + _i * 8192), 16, 0, 0); } while (0)
; #define PG8_LDA(dst, b, h) do { _Pragma("unroll") for (int m = 0; m < 4; ++m) _Pragma("unroll") for (int k = 0; k < 2; ++k) dst[m][k] = *(const PG8_LAS bf16x8*)(lds + PG8_SA(b, h) + aoff + m * 2048 + k * 1024); } while (0)
; #define PG8_LDB(dst, b, h) do { _Pragma("unroll") for (int n = 0; n < 2; ++n) _Pragma("unroll") for (int k = 0; k < 2; ++k) dst[n][k] = *(const PG8_LAS bf16x8*)(lds + PG8_SB(b, h) + boff + n * 2048 + k * 1024); } while (0)
; #define PG8_MMA(ai, bj, At, Bt) do { __builtin_amdgcn_s_setprio(1); _Pragma("unroll") for (int m = 0; m < 4; ++m) _Pragma("unroll") for (int n = 0; n < 2; ++n) _Pragma("unroll") for (int k = 0; k < 2; ++k) \
;         acc[ai][bj][m][n] = __builtin_amdgcn_mfma_f32_16x16x32_bf16(Bt[n][k], At[m][k], acc[ai][bj][m][n], 0, 0, 0); __builtin_amdgcn_s_setprio(0); } while (0)
; #define PG8_WAIT_V(n) asm volatile("s_waitcnt vmcnt(" #n ")" ::: "memory")
; #define PG8_WAIT_L(n) asm volatile("s_waitcnt lgkmcnt(" #n ")" ::: "memory")
; #define PG8_BAR __builtin_amdgcn_s_barrier()
; #define PG8_SCHED __builtin_amdgcn_sched_barrier(0)
; template <class Epi, class Sched, bool ALIGN_EPI = false, bool SP2 = false>
; __device__ __forceinline__ void gemm_phase(PG8_LAS unsigned char* lds, const Gemm g, const Sched& S, const Epi& E) {
;     ...
;             PG8_LDB(B0, 0, 0); PG8_LDB(B1, 0, 1); PG8_SCHED; PG8_LDA(At, 0, 0); PG8_STAGE(PG8_SA(1, 1), a1 + hstep, voffA);
;             PG8_WAIT_V(8); PG8_WAIT_L(0); PG8_BAR; PG8_MMA(0, 0, At, B0); PG8_MMA(0, 1, At, B1); PG8_BAR; PG8_SCHED;
;             PG8_LDA(At, 0, 1); PG8_STAGE(PG8_SB(0, 0), b2, voffB); PG8_STAGE(PG8_SB(0, 1), b2 + hstep, voffB); PG8_STAGE(PG8_SA(0, 0), a2, voffA);
;             PG8_WAIT_V(8); PG8_WAIT_L(0); PG8_BAR; PG8_MMA(1, 0, At, B0); PG8_MMA(1, 1, At, B1); PG8_BAR; PG8_SCHED;
.LBB0_3159:
	s_setprio 0
	ds_read_b128 v[142:145], v146
	ds_read_b128 v[152:155], v146 offset:1024
	ds_read_b128 v[156:159], v146 offset:2048
	ds_read_b128 v[160:163], v146 offset:3072
	ds_read_b128 v[164:167], v146 offset:16384
	ds_read_b128 v[168:171], v146 offset:17408
	ds_read_b128 v[172:175], v146 offset:18432
	ds_read_b128 v[176:179], v146 offset:19456
	ds_read_b128 v[180:183], v151
	ds_read_b128 v[184:187], v151 offset:1024
	ds_read_b128 v[188:191], v151 offset:2048
	ds_read_b128 v[192:195], v151 offset:3072
	ds_read_b128 v[196:199], v151 offset:4096
	ds_read_b128 v[200:203], v151 offset:5120
	ds_read_b128 v[204:207], v151 offset:6144
	ds_read_b128 v[208:211], v151 offset:7168
	s_add_u32 s0, s24, 0xfff00080
	s_addc_u32 s1, s25, -1
	s_add_i32 s65, 0, 0x10000
	s_cmp_eq_u32 s64, 60
	s_cselect_b32 s27, s51, s1
	s_cselect_b32 s26, s60, s0
	s_cselect_b32 s1, s49, s63
	s_cselect_b32 s0, s61, s62
	s_add_i32 s70, 0, 0x14000
	s_add_u32 s100, s24, 0xfff00000
	s_addc_u32 s101, s25, -1
	s_mov_b32 m0, s56
	s_nop 0
	global_load_lds_dwordx4 v136, s[100:101]
	s_mov_b32 m0, s57
	s_nop 0
	global_load_lds_dwordx4 v134, s[100:101]
	s_add_i32 m0, s34, 0xc000
	s_nop 0
	global_load_lds_dwordx4 v138, s[24:25]
	s_add_i32 m0, s34, 0xe000
	s_nop 0
	global_load_lds_dwordx4 v140, s[24:25]
	s_nop 0
	s_setprio 1
	s_waitcnt vmcnt(8)
	s_waitcnt lgkmcnt(0)
	s_barrier
	v_mfma_f32_16x16x32_bf16 v[128:131], v[142:145], v[180:183], v[128:131]
	v_mfma_f32_16x16x32_bf16 v[128:131], v[152:155], v[184:187], v[128:131]
	v_mfma_f32_16x16x32_bf16 v[124:127], v[156:159], v[180:183], v[124:127]
	v_mfma_f32_16x16x32_bf16 v[124:127], v[160:163], v[184:187], v[124:127]
	v_mfma_f32_16x16x32_bf16 v[108:111], v[156:159], v[188:191], v[108:111]
	v_mfma_f32_16x16x32_bf16 v[108:111], v[160:163], v[192:195], v[108:111]
	v_mfma_f32_16x16x32_bf16 v[112:115], v[142:145], v[188:191], v[112:115]
	v_mfma_f32_16x16x32_bf16 v[112:115], v[152:155], v[192:195], v[112:115]
	v_mfma_f32_16x16x32_bf16 v[96:99], v[142:145], v[196:199], v[96:99]
	v_mfma_f32_16x16x32_bf16 v[96:99], v[152:155], v[200:203], v[96:99]
	v_mfma_f32_16x16x32_bf16 v[92:95], v[156:159], v[196:199], v[92:95]
	v_mfma_f32_16x16x32_bf16 v[92:95], v[160:163], v[200:203], v[92:95]
	v_mfma_f32_16x16x32_bf16 v[76:79], v[156:159], v[204:207], v[76:79]
	v_mfma_f32_16x16x32_bf16 v[76:79], v[160:163], v[208:211], v[76:79]
	v_mfma_f32_16x16x32_bf16 v[80:83], v[142:145], v[204:207], v[80:83]
	v_mfma_f32_16x16x32_bf16 v[80:83], v[152:155], v[208:211], v[80:83]
	s_setprio 0
	s_setprio 1
	v_mfma_f32_16x16x32_bf16 v[120:123], v[164:167], v[180:183], v[120:123]
	v_mfma_f32_16x16x32_bf16 v[120:123], v[168:171], v[184:187], v[120:123]
	v_mfma_f32_16x16x32_bf16 v[116:119], v[172:175], v[180:183], v[116:119]
	v_mfma_f32_16x16x32_bf16 v[116:119], v[176:179], v[184:187], v[116:119]
	v_mfma_f32_16x16x32_bf16 v[100:103], v[172:175], v[188:191], v[100:103]
	v_mfma_f32_16x16x32_bf16 v[100:103], v[176:179], v[192:195], v[100:103]
	v_mfma_f32_16x16x32_bf16 v[104:107], v[164:167], v[188:191], v[104:107]
	v_mfma_f32_16x16x32_bf16 v[104:107], v[168:171], v[192:195], v[104:107]
	v_mfma_f32_16x16x32_bf16 v[88:91], v[164:167], v[196:199], v[88:91]
	v_mfma_f32_16x16x32_bf16 v[88:91], v[168:171], v[200:203], v[88:91]
	v_mfma_f32_16x16x32_bf16 v[84:87], v[172:175], v[196:199], v[84:87]
	v_mfma_f32_16x16x32_bf16 v[84:87], v[176:179], v[200:203], v[84:87]
	v_mfma_f32_16x16x32_bf16 v[68:71], v[172:175], v[204:207], v[68:71]
	v_mfma_f32_16x16x32_bf16 v[68:71], v[176:179], v[208:211], v[68:71]
	v_mfma_f32_16x16x32_bf16 v[72:75], v[164:167], v[204:207], v[72:75]
	v_mfma_f32_16x16x32_bf16 v[72:75], v[168:171], v[208:211], v[72:75]
	s_barrier
	s_setprio 0
	ds_read_b128 v[180:183], v151 offset:16384
	ds_read_b128 v[184:187], v151 offset:17408
	ds_read_b128 v[188:191], v151 offset:18432
	ds_read_b128 v[192:195], v151 offset:19456
	ds_read_b128 v[196:199], v151 offset:20480
	ds_read_b128 v[200:203], v151 offset:21504
	ds_read_b128 v[204:207], v151 offset:22528
	ds_read_b128 v[208:211], v151 offset:23552
	s_add_i32 s65, s65, s9
	s_mov_b32 m0, s65
	s_nop 0
	global_load_lds_dwordx4 v2, s[0:1]
	s_add_i32 m0, s65, 0x2000
	s_add_u32 s66, s0, 0x100000
	s_addc_u32 s67, s1, 0
	s_add_i32 s65, s70, s9
	global_load_lds_dwordx4 v132, s[0:1]
	s_mov_b32 m0, s65
	s_nop 0
	global_load_lds_dwordx4 v2, s[66:67]
	s_add_i32 m0, s65, 0x2000
	s_nop 0
	global_load_lds_dwordx4 v132, s[66:67]
	s_setprio 1
	s_waitcnt vmcnt(6)
	s_waitcnt lgkmcnt(0)
	s_barrier
	v_mfma_f32_16x16x32_bf16 v[64:67], v[142:145], v[180:183], v[64:67]
	v_mfma_f32_16x16x32_bf16 v[64:67], v[152:155], v[184:187], v[64:67]
	v_mfma_f32_16x16x32_bf16 v[60:63], v[156:159], v[180:183], v[60:63]
	v_mfma_f32_16x16x32_bf16 v[60:63], v[160:163], v[184:187], v[60:63]
	v_mfma_f32_16x16x32_bf16 v[44:47], v[156:159], v[188:191], v[44:47]
	v_mfma_f32_16x16x32_bf16 v[44:47], v[160:163], v[192:195], v[44:47]
	v_mfma_f32_16x16x32_bf16 v[48:51], v[142:145], v[188:191], v[48:51]
	v_mfma_f32_16x16x32_bf16 v[48:51], v[152:155], v[192:195], v[48:51]
	v_mfma_f32_16x16x32_bf16 v[32:35], v[142:145], v[196:199], v[32:35]
	v_mfma_f32_16x16x32_bf16 v[32:35], v[152:155], v[200:203], v[32:35]
	v_mfma_f32_16x16x32_bf16 v[28:31], v[156:159], v[196:199], v[28:31]
	v_mfma_f32_16x16x32_bf16 v[28:31], v[160:163], v[200:203], v[28:31]
	v_mfma_f32_16x16x32_bf16 v[12:15], v[156:159], v[204:207], v[12:15]
	v_mfma_f32_16x16x32_bf16 v[12:15], v[160:163], v[208:211], v[12:15]
	v_mfma_f32_16x16x32_bf16 v[16:19], v[142:145], v[204:207], v[16:19]
	v_mfma_f32_16x16x32_bf16 v[16:19], v[152:155], v[208:211], v[16:19]
	s_setprio 0
	s_setprio 1
	v_mfma_f32_16x16x32_bf16 v[56:59], v[164:167], v[180:183], v[56:59]
	v_mfma_f32_16x16x32_bf16 v[56:59], v[168:171], v[184:187], v[56:59]
	v_mfma_f32_16x16x32_bf16 v[52:55], v[172:175], v[180:183], v[52:55]
	v_mfma_f32_16x16x32_bf16 v[52:55], v[176:179], v[184:187], v[52:55]
	v_mfma_f32_16x16x32_bf16 v[36:39], v[172:175], v[188:191], v[36:39]
	v_mfma_f32_16x16x32_bf16 v[36:39], v[176:179], v[192:195], v[36:39]
	v_mfma_f32_16x16x32_bf16 v[40:43], v[164:167], v[188:191], v[40:43]
	v_mfma_f32_16x16x32_bf16 v[40:43], v[168:171], v[192:195], v[40:43]
	v_mfma_f32_16x16x32_bf16 v[24:27], v[164:167], v[196:199], v[24:27]
	v_mfma_f32_16x16x32_bf16 v[24:27], v[168:171], v[200:203], v[24:27]
	v_mfma_f32_16x16x32_bf16 v[20:23], v[172:175], v[196:199], v[20:23]
	v_mfma_f32_16x16x32_bf16 v[20:23], v[176:179], v[200:203], v[20:23]
	v_mfma_f32_16x16x32_bf16 v[4:7], v[172:175], v[204:207], v[4:7]
	v_mfma_f32_16x16x32_bf16 v[4:7], v[176:179], v[208:211], v[4:7]
	v_mfma_f32_16x16x32_bf16 v[8:11], v[164:167], v[204:207], v[8:11]
	v_mfma_f32_16x16x32_bf16 v[8:11], v[168:171], v[208:211], v[8:11]
	s_barrier
; #define PG8_STAGE(bufoff, gbase, voff) do { _Pragma("unroll") for (int _i = 0; _i < 2; ++_i) \
;         __builtin_amdgcn_global_load_lds((const unsigned*)((const char*)(gbase) + (voff)[_i]), (PG8_LAS unsigned*)(lds + (bufoff) + ldsw + _i * 8192), 16, 0, 0); } while (0)
; #define PG8_LDA(dst, b, h) do { _Pragma("unroll") for (int m = 0; m < 4; ++m) _Pragma("unroll") for (int k = 0; k < 2; ++k) dst[m][k] = *(const PG8_LAS bf16x8*)(lds + PG8_SA(b, h) + aoff + m * 2048 + k * 1024); } while (0)
; #define PG8_LDB(dst, b, h) do { _Pragma("unroll") for (int n = 0; n < 2; ++n) _Pragma("unroll") for (int k = 0; k < 2; ++k) dst[n][k] = *(const PG8_LAS bf16x8*)(lds + PG8_SB(b, h) + boff + n * 2048 + k * 1024); } while (0)
; #define PG8_MMA(ai, bj, At, Bt) do { __builtin_amdgcn_s_setprio(1); _Pragma("unroll") for (int m = 0; m < 4; ++m) _Pragma("unroll") for (int n = 0; n < 2; ++n) _Pragma("unroll") for (int k = 0; k < 2; ++k) \
;         acc[ai][bj][m][n] = __builtin_amdgcn_mfma_f32_16x16x32_bf16(Bt[n][k], At[m][k], acc[ai][bj][m][n], 0, 0, 0); __builtin_amdgcn_s_setprio(0); } while (0)
; #define PG8_WAIT_V(n) asm volatile("s_waitcnt vmcnt(" #n ")" ::: "memory")
; #define PG8_WAIT_L(n) asm volatile("s_waitcnt lgkmcnt(" #n ")" ::: "memory")
; #define PG8_BAR __builtin_amdgcn_s_barrier()
; #define PG8_SCHED __builtin_amdgcn_sched_barrier(0)
; template <class Epi, class Sched, bool ALIGN_EPI = false, bool SP2 = false>
; __device__ __forceinline__ void gemm_phase(PG8_LAS unsigned char* lds, const Gemm g, const Sched& S, const Epi& E) {
;     ...
;             PG8_LDB(B0, 1, 0); PG8_LDB(B1, 1, 1); PG8_SCHED; PG8_LDA(At, 1, 0); PG8_STAGE(PG8_SA(0, 1), a2 + hstep, voffA);
;             PG8_WAIT_V(8); PG8_WAIT_L(0); PG8_BAR; PG8_MMA(0, 0, At, B0); PG8_MMA(0, 1, At, B1); PG8_BAR; PG8_SCHED;
;             PG8_LDA(At, 1, 1); PG8_STAGE(PG8_SB(1, 0), b3, voffB); PG8_STAGE(PG8_SB(1, 1), b3 + hstep, voffB); PG8_STAGE(PG8_SA(1, 0), a3, voffA);
;             PG8_WAIT_V(8); PG8_WAIT_L(0); PG8_BAR; PG8_MMA(1, 0, At, B0); PG8_MMA(1, 1, At, B1); PG8_BAR; PG8_SCHED;
	s_setprio 0
	ds_read_b128 v[142:145], v146 offset:32768
	ds_read_b128 v[152:155], v146 offset:33792
	ds_read_b128 v[156:159], v146 offset:34816
	ds_read_b128 v[160:163], v146 offset:35840
	ds_read_b128 v[164:167], v146 offset:49152
	ds_read_b128 v[168:171], v146 offset:50176
	ds_read_b128 v[172:175], v146 offset:51200
	ds_read_b128 v[176:179], v146 offset:52224
	ds_read_b128 v[180:183], v151 offset:32768
	ds_read_b128 v[184:187], v151 offset:33792
	ds_read_b128 v[188:191], v151 offset:34816
	ds_read_b128 v[192:195], v151 offset:35840
	ds_read_b128 v[196:199], v151 offset:36864
	ds_read_b128 v[200:203], v151 offset:37888
	ds_read_b128 v[204:207], v151 offset:38912
	ds_read_b128 v[208:211], v151 offset:39936
	s_add_i32 s65, 0, 0x18000
	s_add_i32 s66, 0, 0x1c000
	s_mov_b32 m0, s34
	s_nop 0
	global_load_lds_dwordx4 v136, s[26:27]
	s_mov_b32 m0, s35
	s_nop 0
	global_load_lds_dwordx4 v134, s[26:27]
	s_add_u32 s26, s26, 0x100000
	s_addc_u32 s27, s27, 0
	s_mov_b32 m0, s54
	s_nop 0
	global_load_lds_dwordx4 v136, s[26:27]
	s_mov_b32 m0, s55
	s_nop 0
	global_load_lds_dwordx4 v134, s[26:27]
	s_nop 0
	s_setprio 1
	s_waitcnt vmcnt(8)
	s_waitcnt lgkmcnt(0)
	s_barrier
	v_mfma_f32_16x16x32_bf16 v[128:131], v[142:145], v[180:183], v[128:131]
	v_mfma_f32_16x16x32_bf16 v[128:131], v[152:155], v[184:187], v[128:131]
	v_mfma_f32_16x16x32_bf16 v[124:127], v[156:159], v[180:183], v[124:127]
	v_mfma_f32_16x16x32_bf16 v[124:127], v[160:163], v[184:187], v[124:127]
	v_mfma_f32_16x16x32_bf16 v[108:111], v[156:159], v[188:191], v[108:111]
	v_mfma_f32_16x16x32_bf16 v[108:111], v[160:163], v[192:195], v[108:111]
	v_mfma_f32_16x16x32_bf16 v[112:115], v[142:145], v[188:191], v[112:115]
	v_mfma_f32_16x16x32_bf16 v[112:115], v[152:155], v[192:195], v[112:115]
	v_mfma_f32_16x16x32_bf16 v[96:99], v[142:145], v[196:199], v[96:99]
	v_mfma_f32_16x16x32_bf16 v[96:99], v[152:155], v[200:203], v[96:99]
	v_mfma_f32_16x16x32_bf16 v[92:95], v[156:159], v[196:199], v[92:95]
	v_mfma_f32_16x16x32_bf16 v[92:95], v[160:163], v[200:203], v[92:95]
	v_mfma_f32_16x16x32_bf16 v[76:79], v[156:159], v[204:207], v[76:79]
	v_mfma_f32_16x16x32_bf16 v[76:79], v[160:163], v[208:211], v[76:79]
	v_mfma_f32_16x16x32_bf16 v[80:83], v[142:145], v[204:207], v[80:83]
	v_mfma_f32_16x16x32_bf16 v[80:83], v[152:155], v[208:211], v[80:83]
	s_setprio 0
	s_setprio 1
	v_mfma_f32_16x16x32_bf16 v[120:123], v[164:167], v[180:183], v[120:123]
	v_mfma_f32_16x16x32_bf16 v[120:123], v[168:171], v[184:187], v[120:123]
	v_mfma_f32_16x16x32_bf16 v[116:119], v[172:175], v[180:183], v[116:119]
	v_mfma_f32_16x16x32_bf16 v[116:119], v[176:179], v[184:187], v[116:119]
	v_mfma_f32_16x16x32_bf16 v[100:103], v[172:175], v[188:191], v[100:103]
	v_mfma_f32_16x16x32_bf16 v[100:103], v[176:179], v[192:195], v[100:103]
	v_mfma_f32_16x16x32_bf16 v[104:107], v[164:167], v[188:191], v[104:107]
	v_mfma_f32_16x16x32_bf16 v[104:107], v[168:171], v[192:195], v[104:107]
	v_mfma_f32_16x16x32_bf16 v[88:91], v[164:167], v[196:199], v[88:91]
	v_mfma_f32_16x16x32_bf16 v[88:91], v[168:171], v[200:203], v[88:91]
	v_mfma_f32_16x16x32_bf16 v[84:87], v[172:175], v[196:199], v[84:87]
	v_mfma_f32_16x16x32_bf16 v[84:87], v[176:179], v[200:203], v[84:87]
	v_mfma_f32_16x16x32_bf16 v[68:71], v[172:175], v[204:207], v[68:71]
	v_mfma_f32_16x16x32_bf16 v[68:71], v[176:179], v[208:211], v[68:71]
	v_mfma_f32_16x16x32_bf16 v[72:75], v[164:167], v[204:207], v[72:75]
	v_mfma_f32_16x16x32_bf16 v[72:75], v[168:171], v[208:211], v[72:75]
	s_barrier
	s_setprio 0
	ds_read_b128 v[180:183], v151 offset:49152
	ds_read_b128 v[184:187], v151 offset:50176
	ds_read_b128 v[188:191], v151 offset:51200
	ds_read_b128 v[192:195], v151 offset:52224
	ds_read_b128 v[196:199], v151 offset:53248
	ds_read_b128 v[200:203], v151 offset:54272
	ds_read_b128 v[204:207], v151 offset:55296
	ds_read_b128 v[208:211], v151 offset:56320
	s_add_i32 s26, s65, s9
	s_mov_b32 m0, s26
	s_add_u32 s0, s0, 0x80
	s_addc_u32 s1, s1, 0
	global_load_lds_dwordx4 v2, s[0:1]
	s_add_i32 m0, s26, 0x2000
	s_add_i32 s26, s66, s9
	global_load_lds_dwordx4 v132, s[0:1]
	s_add_u32 s0, s0, 0x100000
	s_addc_u32 s1, s1, 0
	s_mov_b32 m0, s26
	s_nop 0
	global_load_lds_dwordx4 v2, s[0:1]
	s_add_i32 m0, s26, 0x2000
	s_nop 0
	global_load_lds_dwordx4 v132, s[0:1]
	s_setprio 1
	s_waitcnt vmcnt(6)
	s_waitcnt lgkmcnt(0)
	s_barrier
	v_mfma_f32_16x16x32_bf16 v[64:67], v[142:145], v[180:183], v[64:67]
	v_mfma_f32_16x16x32_bf16 v[64:67], v[152:155], v[184:187], v[64:67]
	v_mfma_f32_16x16x32_bf16 v[60:63], v[156:159], v[180:183], v[60:63]
	v_mfma_f32_16x16x32_bf16 v[60:63], v[160:163], v[184:187], v[60:63]
	v_mfma_f32_16x16x32_bf16 v[44:47], v[156:159], v[188:191], v[44:47]
	v_mfma_f32_16x16x32_bf16 v[44:47], v[160:163], v[192:195], v[44:47]
	v_mfma_f32_16x16x32_bf16 v[48:51], v[142:145], v[188:191], v[48:51]
	v_mfma_f32_16x16x32_bf16 v[48:51], v[152:155], v[192:195], v[48:51]
	v_mfma_f32_16x16x32_bf16 v[32:35], v[142:145], v[196:199], v[32:35]
	v_mfma_f32_16x16x32_bf16 v[32:35], v[152:155], v[200:203], v[32:35]
	v_mfma_f32_16x16x32_bf16 v[28:31], v[156:159], v[196:199], v[28:31]
	v_mfma_f32_16x16x32_bf16 v[28:31], v[160:163], v[200:203], v[28:31]
	v_mfma_f32_16x16x32_bf16 v[12:15], v[156:159], v[204:207], v[12:15]
	v_mfma_f32_16x16x32_bf16 v[12:15], v[160:163], v[208:211], v[12:15]
	v_mfma_f32_16x16x32_bf16 v[16:19], v[142:145], v[204:207], v[16:19]
	v_mfma_f32_16x16x32_bf16 v[16:19], v[152:155], v[208:211], v[16:19]
	s_setprio 0
	s_setprio 1
	s_add_i32 s64, s64, 2
	s_add_u32 s24, s24, 0x100
	s_addc_u32 s25, s25, 0
	s_add_u32 s62, s62, 0x100
	s_addc_u32 s63, s63, 0
	s_nop 0
	v_mfma_f32_16x16x32_bf16 v[56:59], v[164:167], v[180:183], v[56:59]
	v_mfma_f32_16x16x32_bf16 v[56:59], v[168:171], v[184:187], v[56:59]
	v_mfma_f32_16x16x32_bf16 v[52:55], v[172:175], v[180:183], v[52:55]
	v_mfma_f32_16x16x32_bf16 v[52:55], v[176:179], v[184:187], v[52:55]
	v_mfma_f32_16x16x32_bf16 v[36:39], v[172:175], v[188:191], v[36:39]
	v_mfma_f32_16x16x32_bf16 v[36:39], v[176:179], v[192:195], v[36:39]
	v_mfma_f32_16x16x32_bf16 v[40:43], v[164:167], v[188:191], v[40:43]
	v_mfma_f32_16x16x32_bf16 v[40:43], v[168:171], v[192:195], v[40:43]
	v_mfma_f32_16x16x32_bf16 v[24:27], v[164:167], v[196:199], v[24:27]
	v_mfma_f32_16x16x32_bf16 v[24:27], v[168:171], v[200:203], v[24:27]
	v_mfma_f32_16x16x32_bf16 v[20:23], v[172:175], v[196:199], v[20:23]
	v_mfma_f32_16x16x32_bf16 v[20:23], v[176:179], v[200:203], v[20:23]
	v_mfma_f32_16x16x32_bf16 v[4:7], v[172:175], v[204:207], v[4:7]
	v_mfma_f32_16x16x32_bf16 v[4:7], v[176:179], v[208:211], v[4:7]
	v_mfma_f32_16x16x32_bf16 v[8:11], v[164:167], v[204:207], v[8:11]
	v_mfma_f32_16x16x32_bf16 v[8:11], v[168:171], v[208:211], v[8:11]
	s_barrier
	s_cmp_gt_u32 s64, 61
	s_cbranch_scc0 .LBB0_3159
	s_setprio 0
	s_and_b64 vcc, exec, s[46:47]
	s_cbranch_vccz .LBB0_3162
	s_barrier

; #define PG8_STAGE(bufoff, gbase, voff) do { _Pragma("unroll") for (int _i = 0; _i < 2; ++_i) \
;         __builtin_amdgcn_global_load_lds((const unsigned*)((const char*)(gbase) + (voff)[_i]), (PG8_LAS unsigned*)(lds + (bufoff) + ldsw + _i * 8192), 16, 0, 0); } while (0)
; #define PG8_LDA(dst, b, h) do { _Pragma("unroll") for (int m = 0; m < 4; ++m) _Pragma("unroll") for (int k = 0; k < 2; ++k) dst[m][k] = *(const PG8_LAS bf16x8*)(lds + PG8_SA(b, h) + aoff + m * 2048 + k * 1024); } while (0)
; #define PG8_LDB(dst, b, h) do { _Pragma("unroll") for (int n = 0; n < 2; ++n) _Pragma("unroll") for (int k = 0; k < 2; ++k) dst[n][k] = *(const PG8_LAS bf16x8*)(lds + PG8_SB(b, h) + boff + n * 2048 + k * 1024); } while (0)
; #define PG8_MMA(ai, bj, At, Bt) do { __builtin_amdgcn_s_setprio(1); _Pragma("unroll") for (int m = 0; m < 4; ++m) _Pragma("unroll") for (int n = 0; n < 2; ++n) _Pragma("unroll") for (int k = 0; k < 2; ++k) \
;         acc[ai][bj][m][n] = __builtin_amdgcn_mfma_f32_16x16x32_bf16(Bt[n][k], At[m][k], acc[ai][bj][m][n], 0, 0, 0); __builtin_amdgcn_s_setprio(0); } while (0)
; #define PG8_WAIT_V(n) asm volatile("s_waitcnt vmcnt(" #n ")" ::: "memory")
; #define PG8_WAIT_L(n) asm volatile("s_waitcnt lgkmcnt(" #n ")" ::: "memory")
; #define PG8_BAR __builtin_amdgcn_s_barrier()
; #define PG8_SCHED __builtin_amdgcn_sched_barrier(0)
; template <class Epi, class Sched, bool ALIGN_EPI = false, bool SP2 = false>
; __device__ __forceinline__ void gemm_phase(PG8_LAS unsigned char* lds, const Gemm g, const Sched& S, const Epi& E) {
;     ...
;             PG8_LDB(B0, 0, 0); PG8_LDB(B1, 0, 1); PG8_SCHED; PG8_LDA(At, 0, 0); PG8_STAGE(PG8_SA(1, 1), a1 + hstep, voffA);
;             PG8_WAIT_V(8); PG8_WAIT_L(0); PG8_BAR; PG8_MMA(0, 0, At, B0); PG8_MMA(0, 1, At, B1); PG8_BAR; PG8_SCHED;
;             PG8_LDA(At, 0, 1); PG8_STAGE(PG8_SB(0, 0), b2, voffB); PG8_STAGE(PG8_SB(0, 1), b2 + hstep, voffB); PG8_STAGE(PG8_SA(0, 0), a2, voffA);
;             PG8_WAIT_V(8); PG8_WAIT_L(0); PG8_BAR; PG8_MMA(1, 0, At, B0); PG8_MMA(1, 1, At, B1); PG8_BAR; PG8_SCHED;
.LBB0_3627:
	s_setprio 0
	s_waitcnt lgkmcnt(0)
	ds_read_b128 v[132:135], v162
	ds_read_b128 v[136:139], v162 offset:1024
	ds_read_b128 v[140:143], v162 offset:2048
	ds_read_b128 v[154:157], v162 offset:3072
	ds_read_b128 v[158:161], v162 offset:16384
	ds_read_b128 v[170:173], v162 offset:17408
	ds_read_b128 v[174:177], v162 offset:18432
	ds_read_b128 v[178:181], v162 offset:19456
	ds_read_b128 v[182:185], v169
	ds_read_b128 v[186:189], v169 offset:1024
	ds_read_b128 v[190:193], v169 offset:2048
	ds_read_b128 v[194:197], v169 offset:3072
	ds_read_b128 v[198:201], v169 offset:4096
	ds_read_b128 v[202:205], v169 offset:5120
	ds_read_b128 v[206:209], v169 offset:6144
	ds_read_b128 v[210:213], v169 offset:7168
	s_add_i32 s72, s26, 2
	s_add_u32 s0, s24, 0x100
	s_addc_u32 s1, s25, 0
	s_add_i32 s73, 0, 0x10000
	s_cmp_eq_u32 s44, s26
	s_cselect_b32 s35, s79, s1
	s_cselect_b32 s34, s78, s0
	s_cselect_b32 s27, s81, s47
	s_cselect_b32 s26, s80, s45
	s_add_i32 vcc_lo, 0, 0x14000
	s_add_u32 s100, s24, 0x80
	s_addc_u32 s101, s25, 0
	s_mov_b32 m0, s65
	s_nop 0
	global_load_lds_dwordx4 v144, s[100:101]
	s_mov_b32 m0, s4
	s_nop 0
	global_load_lds_dwordx4 v146, s[100:101]
	s_add_i32 m0, s92, 0xc000
	s_nop 0
	global_load_lds_dwordx4 v150, s[24:25]
	s_add_i32 m0, s92, 0xe000
	s_nop 0
	global_load_lds_dwordx4 v152, s[24:25]
	s_setprio 1
	s_waitcnt vmcnt(8)
	s_waitcnt lgkmcnt(0)
	s_barrier
	v_mfma_f32_16x16x32_bf16 v[128:131], v[132:135], v[182:185], v[128:131]
	v_mfma_f32_16x16x32_bf16 v[128:131], v[136:139], v[186:189], v[128:131]
	v_mfma_f32_16x16x32_bf16 v[124:127], v[140:143], v[182:185], v[124:127]
	v_mfma_f32_16x16x32_bf16 v[124:127], v[154:157], v[186:189], v[124:127]
	v_mfma_f32_16x16x32_bf16 v[116:119], v[140:143], v[190:193], v[116:119]
	v_mfma_f32_16x16x32_bf16 v[116:119], v[154:157], v[194:197], v[116:119]
	v_mfma_f32_16x16x32_bf16 v[120:123], v[132:135], v[190:193], v[120:123]
	v_mfma_f32_16x16x32_bf16 v[120:123], v[136:139], v[194:197], v[120:123]
	v_mfma_f32_16x16x32_bf16 v[112:115], v[132:135], v[198:201], v[112:115]
	v_mfma_f32_16x16x32_bf16 v[112:115], v[136:139], v[202:205], v[112:115]
	v_mfma_f32_16x16x32_bf16 v[108:111], v[140:143], v[198:201], v[108:111]
	v_mfma_f32_16x16x32_bf16 v[108:111], v[154:157], v[202:205], v[108:111]
	v_mfma_f32_16x16x32_bf16 v[100:103], v[140:143], v[206:209], v[100:103]
	v_mfma_f32_16x16x32_bf16 v[100:103], v[154:157], v[210:213], v[100:103]
	v_mfma_f32_16x16x32_bf16 v[104:107], v[132:135], v[206:209], v[104:107]
	v_mfma_f32_16x16x32_bf16 v[104:107], v[136:139], v[210:213], v[104:107]
	s_setprio 0
	s_setprio 1
	v_mfma_f32_16x16x32_bf16 v[96:99], v[158:161], v[182:185], v[96:99]
	v_mfma_f32_16x16x32_bf16 v[96:99], v[170:173], v[186:189], v[96:99]
	v_mfma_f32_16x16x32_bf16 v[92:95], v[174:177], v[182:185], v[92:95]
	v_mfma_f32_16x16x32_bf16 v[92:95], v[178:181], v[186:189], v[92:95]
	v_mfma_f32_16x16x32_bf16 v[84:87], v[174:177], v[190:193], v[84:87]
	v_mfma_f32_16x16x32_bf16 v[84:87], v[178:181], v[194:197], v[84:87]
	v_mfma_f32_16x16x32_bf16 v[88:91], v[158:161], v[190:193], v[88:91]
	v_mfma_f32_16x16x32_bf16 v[88:91], v[170:173], v[194:197], v[88:91]
	v_mfma_f32_16x16x32_bf16 v[80:83], v[158:161], v[198:201], v[80:83]
	v_mfma_f32_16x16x32_bf16 v[80:83], v[170:173], v[202:205], v[80:83]
	v_mfma_f32_16x16x32_bf16 v[76:79], v[174:177], v[198:201], v[76:79]
	v_mfma_f32_16x16x32_bf16 v[76:79], v[178:181], v[202:205], v[76:79]
	v_mfma_f32_16x16x32_bf16 v[68:71], v[174:177], v[206:209], v[68:71]
	v_mfma_f32_16x16x32_bf16 v[68:71], v[178:181], v[210:213], v[68:71]
	v_mfma_f32_16x16x32_bf16 v[72:75], v[158:161], v[206:209], v[72:75]
	v_mfma_f32_16x16x32_bf16 v[72:75], v[170:173], v[210:213], v[72:75]
	s_barrier
	s_setprio 0
	ds_read_b128 v[182:185], v169 offset:16384
	ds_read_b128 v[186:189], v169 offset:17408
	ds_read_b128 v[190:193], v169 offset:18432
	ds_read_b128 v[194:197], v169 offset:19456
	ds_read_b128 v[198:201], v169 offset:20480
	ds_read_b128 v[202:205], v169 offset:21504
	ds_read_b128 v[206:209], v169 offset:22528
	ds_read_b128 v[210:213], v169 offset:23552
	s_add_i32 s24, s73, s83
	s_mov_b32 m0, s24
	s_nop 0
	global_load_lds_dwordx4 v2, s[26:27]
	s_add_i32 m0, s24, 0x2000
	s_add_u32 s24, s26, 0x2b0000
	s_addc_u32 s25, s27, 0
	s_add_i32 s73, vcc_lo, s83
	global_load_lds_dwordx4 v148, s[26:27]
	s_mov_b32 m0, s73
	s_nop 0
	global_load_lds_dwordx4 v2, s[24:25]
	s_add_i32 m0, s73, 0x2000
	s_nop 0
	global_load_lds_dwordx4 v148, s[24:25]
	s_setprio 1
	s_waitcnt vmcnt(6)
	s_waitcnt lgkmcnt(0)
	s_barrier
	v_mfma_f32_16x16x32_bf16 v[64:67], v[132:135], v[182:185], v[64:67]
	v_mfma_f32_16x16x32_bf16 v[64:67], v[136:139], v[186:189], v[64:67]
	v_mfma_f32_16x16x32_bf16 v[60:63], v[140:143], v[182:185], v[60:63]
	v_mfma_f32_16x16x32_bf16 v[60:63], v[154:157], v[186:189], v[60:63]
	v_mfma_f32_16x16x32_bf16 v[52:55], v[140:143], v[190:193], v[52:55]
	v_mfma_f32_16x16x32_bf16 v[52:55], v[154:157], v[194:197], v[52:55]
	v_mfma_f32_16x16x32_bf16 v[56:59], v[132:135], v[190:193], v[56:59]
	v_mfma_f32_16x16x32_bf16 v[56:59], v[136:139], v[194:197], v[56:59]
	v_mfma_f32_16x16x32_bf16 v[48:51], v[132:135], v[198:201], v[48:51]
	v_mfma_f32_16x16x32_bf16 v[48:51], v[136:139], v[202:205], v[48:51]
	v_mfma_f32_16x16x32_bf16 v[44:47], v[140:143], v[198:201], v[44:47]
	v_mfma_f32_16x16x32_bf16 v[44:47], v[154:157], v[202:205], v[44:47]
	v_mfma_f32_16x16x32_bf16 v[36:39], v[140:143], v[206:209], v[36:39]
	v_mfma_f32_16x16x32_bf16 v[36:39], v[154:157], v[210:213], v[36:39]
	v_mfma_f32_16x16x32_bf16 v[40:43], v[132:135], v[206:209], v[40:43]
	v_mfma_f32_16x16x32_bf16 v[40:43], v[136:139], v[210:213], v[40:43]
	s_setprio 0
	s_setprio 1
	v_mfma_f32_16x16x32_bf16 v[32:35], v[158:161], v[182:185], v[32:35]
	v_mfma_f32_16x16x32_bf16 v[32:35], v[170:173], v[186:189], v[32:35]
	v_mfma_f32_16x16x32_bf16 v[28:31], v[174:177], v[182:185], v[28:31]
	v_mfma_f32_16x16x32_bf16 v[28:31], v[178:181], v[186:189], v[28:31]
	v_mfma_f32_16x16x32_bf16 v[20:23], v[174:177], v[190:193], v[20:23]
	v_mfma_f32_16x16x32_bf16 v[20:23], v[178:181], v[194:197], v[20:23]
	v_mfma_f32_16x16x32_bf16 v[24:27], v[158:161], v[190:193], v[24:27]
	v_mfma_f32_16x16x32_bf16 v[24:27], v[170:173], v[194:197], v[24:27]
	v_mfma_f32_16x16x32_bf16 v[16:19], v[158:161], v[198:201], v[16:19]
	v_mfma_f32_16x16x32_bf16 v[16:19], v[170:173], v[202:205], v[16:19]
	v_mfma_f32_16x16x32_bf16 v[12:15], v[174:177], v[198:201], v[12:15]
	v_mfma_f32_16x16x32_bf16 v[12:15], v[178:181], v[202:205], v[12:15]
	v_mfma_f32_16x16x32_bf16 v[4:7], v[174:177], v[206:209], v[4:7]
	v_mfma_f32_16x16x32_bf16 v[4:7], v[178:181], v[210:213], v[4:7]
	v_mfma_f32_16x16x32_bf16 v[8:11], v[158:161], v[206:209], v[8:11]
	v_mfma_f32_16x16x32_bf16 v[8:11], v[170:173], v[210:213], v[8:11]
	s_barrier
; #define PG8_STAGE(bufoff, gbase, voff) do { _Pragma("unroll") for (int _i = 0; _i < 2; ++_i) \
;         __builtin_amdgcn_global_load_lds((const unsigned*)((const char*)(gbase) + (voff)[_i]), (PG8_LAS unsigned*)(lds + (bufoff) + ldsw + _i * 8192), 16, 0, 0); } while (0)
; #define PG8_LDA(dst, b, h) do { _Pragma("unroll") for (int m = 0; m < 4; ++m) _Pragma("unroll") for (int k = 0; k < 2; ++k) dst[m][k] = *(const PG8_LAS bf16x8*)(lds + PG8_SA(b, h) + aoff + m * 2048 + k * 1024); } while (0)
; #define PG8_LDB(dst, b, h) do { _Pragma("unroll") for (int n = 0; n < 2; ++n) _Pragma("unroll") for (int k = 0; k < 2; ++k) dst[n][k] = *(const PG8_LAS bf16x8*)(lds + PG8_SB(b, h) + boff + n * 2048 + k * 1024); } while (0)
; #define PG8_MMA(ai, bj, At, Bt) do { __builtin_amdgcn_s_setprio(1); _Pragma("unroll") for (int m = 0; m < 4; ++m) _Pragma("unroll") for (int n = 0; n < 2; ++n) _Pragma("unroll") for (int k = 0; k < 2; ++k) \
;         acc[ai][bj][m][n] = __builtin_amdgcn_mfma_f32_16x16x32_bf16(Bt[n][k], At[m][k], acc[ai][bj][m][n], 0, 0, 0); __builtin_amdgcn_s_setprio(0); } while (0)
; #define PG8_WAIT_V(n) asm volatile("s_waitcnt vmcnt(" #n ")" ::: "memory")
; #define PG8_WAIT_L(n) asm volatile("s_waitcnt lgkmcnt(" #n ")" ::: "memory")
; #define PG8_BAR __builtin_amdgcn_s_barrier()
; #define PG8_SCHED __builtin_amdgcn_sched_barrier(0)
; template <class Epi, class Sched, bool ALIGN_EPI = false, bool SP2 = false>
; __device__ __forceinline__ void gemm_phase(PG8_LAS unsigned char* lds, const Gemm g, const Sched& S, const Epi& E) {
;     ...
;             PG8_LDB(B0, 1, 0); PG8_LDB(B1, 1, 1); PG8_SCHED; PG8_LDA(At, 1, 0); PG8_STAGE(PG8_SA(0, 1), a2 + hstep, voffA);
;             PG8_WAIT_V(8); PG8_WAIT_L(0); PG8_BAR; PG8_MMA(0, 0, At, B0); PG8_MMA(0, 1, At, B1); PG8_BAR; PG8_SCHED;
;             PG8_LDA(At, 1, 1); PG8_STAGE(PG8_SB(1, 0), b3, voffB); PG8_STAGE(PG8_SB(1, 1), b3 + hstep, voffB); PG8_STAGE(PG8_SA(1, 0), a3, voffA);
;             PG8_WAIT_V(8); PG8_WAIT_L(0); PG8_BAR; PG8_MMA(1, 0, At, B0); PG8_MMA(1, 1, At, B1); PG8_BAR; PG8_SCHED;
	s_setprio 0
	ds_read_b128 v[132:135], v162 offset:32768
	ds_read_b128 v[136:139], v162 offset:33792
	ds_read_b128 v[140:143], v162 offset:34816
	ds_read_b128 v[154:157], v162 offset:35840
	ds_read_b128 v[158:161], v162 offset:49152
	ds_read_b128 v[170:173], v162 offset:50176
	ds_read_b128 v[174:177], v162 offset:51200
	ds_read_b128 v[178:181], v162 offset:52224
	ds_read_b128 v[182:185], v169 offset:32768
	ds_read_b128 v[186:189], v169 offset:33792
	ds_read_b128 v[190:193], v169 offset:34816
	ds_read_b128 v[194:197], v169 offset:35840
	ds_read_b128 v[198:201], v169 offset:36864
	ds_read_b128 v[202:205], v169 offset:37888
	ds_read_b128 v[206:209], v169 offset:38912
	ds_read_b128 v[210:213], v169 offset:39936
	s_add_i32 s73, 0, 0x18000
	s_add_i32 vcc_lo, 0, 0x1c000
	s_mov_b32 m0, s92
	s_nop 0
	global_load_lds_dwordx4 v144, s[34:35]
	s_mov_b32 m0, s93
	s_nop 0
	global_load_lds_dwordx4 v146, s[34:35]
	s_add_u32 s24, s34, 0x2b0000
	s_addc_u32 s25, s35, 0
	s_mov_b32 m0, s94
	s_nop 0
	global_load_lds_dwordx4 v144, s[24:25]
	s_mov_b32 m0, s95
	s_nop 0
	global_load_lds_dwordx4 v146, s[24:25]
	s_nop 0
	s_setprio 1
	s_waitcnt vmcnt(8)
	s_waitcnt lgkmcnt(0)
	s_barrier
	v_mfma_f32_16x16x32_bf16 v[128:131], v[132:135], v[182:185], v[128:131]
	v_mfma_f32_16x16x32_bf16 v[128:131], v[136:139], v[186:189], v[128:131]
	v_mfma_f32_16x16x32_bf16 v[124:127], v[140:143], v[182:185], v[124:127]
	v_mfma_f32_16x16x32_bf16 v[124:127], v[154:157], v[186:189], v[124:127]
	v_mfma_f32_16x16x32_bf16 v[116:119], v[140:143], v[190:193], v[116:119]
	v_mfma_f32_16x16x32_bf16 v[116:119], v[154:157], v[194:197], v[116:119]
	v_mfma_f32_16x16x32_bf16 v[120:123], v[132:135], v[190:193], v[120:123]
	v_mfma_f32_16x16x32_bf16 v[120:123], v[136:139], v[194:197], v[120:123]
	v_mfma_f32_16x16x32_bf16 v[112:115], v[132:135], v[198:201], v[112:115]
	v_mfma_f32_16x16x32_bf16 v[112:115], v[136:139], v[202:205], v[112:115]
	v_mfma_f32_16x16x32_bf16 v[108:111], v[140:143], v[198:201], v[108:111]
	v_mfma_f32_16x16x32_bf16 v[108:111], v[154:157], v[202:205], v[108:111]
	v_mfma_f32_16x16x32_bf16 v[100:103], v[140:143], v[206:209], v[100:103]
	v_mfma_f32_16x16x32_bf16 v[100:103], v[154:157], v[210:213], v[100:103]
	v_mfma_f32_16x16x32_bf16 v[104:107], v[132:135], v[206:209], v[104:107]
	v_mfma_f32_16x16x32_bf16 v[104:107], v[136:139], v[210:213], v[104:107]
	s_setprio 0
	s_setprio 1
	v_mfma_f32_16x16x32_bf16 v[96:99], v[158:161], v[182:185], v[96:99]
	v_mfma_f32_16x16x32_bf16 v[96:99], v[170:173], v[186:189], v[96:99]
	v_mfma_f32_16x16x32_bf16 v[92:95], v[174:177], v[182:185], v[92:95]
	v_mfma_f32_16x16x32_bf16 v[92:95], v[178:181], v[186:189], v[92:95]
	v_mfma_f32_16x16x32_bf16 v[84:87], v[174:177], v[190:193], v[84:87]
	v_mfma_f32_16x16x32_bf16 v[84:87], v[178:181], v[194:197], v[84:87]
	v_mfma_f32_16x16x32_bf16 v[88:91], v[158:161], v[190:193], v[88:91]
	v_mfma_f32_16x16x32_bf16 v[88:91], v[170:173], v[194:197], v[88:91]
	v_mfma_f32_16x16x32_bf16 v[80:83], v[158:161], v[198:201], v[80:83]
	v_mfma_f32_16x16x32_bf16 v[80:83], v[170:173], v[202:205], v[80:83]
	v_mfma_f32_16x16x32_bf16 v[76:79], v[174:177], v[198:201], v[76:79]
	v_mfma_f32_16x16x32_bf16 v[76:79], v[178:181], v[202:205], v[76:79]
	v_mfma_f32_16x16x32_bf16 v[68:71], v[174:177], v[206:209], v[68:71]
	v_mfma_f32_16x16x32_bf16 v[68:71], v[178:181], v[210:213], v[68:71]
	v_mfma_f32_16x16x32_bf16 v[72:75], v[158:161], v[206:209], v[72:75]
	v_mfma_f32_16x16x32_bf16 v[72:75], v[170:173], v[210:213], v[72:75]
	s_barrier
	s_setprio 0
	ds_read_b128 v[182:185], v169 offset:49152
	ds_read_b128 v[186:189], v169 offset:50176
	ds_read_b128 v[190:193], v169 offset:51200
	ds_read_b128 v[194:197], v169 offset:52224
	ds_read_b128 v[198:201], v169 offset:53248
	ds_read_b128 v[202:205], v169 offset:54272
	ds_read_b128 v[206:209], v169 offset:55296
	ds_read_b128 v[210:213], v169 offset:56320
	s_add_i32 s24, s73, s83
	s_add_u32 s100, s26, 0x80
	s_addc_u32 s101, s27, 0
	s_mov_b32 m0, s24
	s_nop 0
	global_load_lds_dwordx4 v2, s[100:101]
	s_add_i32 m0, s24, 0x2000
	s_add_u32 s24, s26, 0x2b0080
	s_addc_u32 s25, s27, 0
	s_add_i32 s26, vcc_lo, s83
	global_load_lds_dwordx4 v148, s[100:101]
	s_mov_b32 m0, s26
	s_nop 0
	global_load_lds_dwordx4 v2, s[24:25]
	s_add_i32 m0, s26, 0x2000
	s_nop 0
	global_load_lds_dwordx4 v148, s[24:25]
	s_nop 0
	s_setprio 1
	s_waitcnt vmcnt(6)
	s_waitcnt lgkmcnt(0)
	s_barrier
	v_mfma_f32_16x16x32_bf16 v[64:67], v[132:135], v[182:185], v[64:67]
	v_mfma_f32_16x16x32_bf16 v[64:67], v[136:139], v[186:189], v[64:67]
	v_mfma_f32_16x16x32_bf16 v[60:63], v[140:143], v[182:185], v[60:63]
	v_mfma_f32_16x16x32_bf16 v[60:63], v[154:157], v[186:189], v[60:63]
	v_mfma_f32_16x16x32_bf16 v[52:55], v[140:143], v[190:193], v[52:55]
	v_mfma_f32_16x16x32_bf16 v[52:55], v[154:157], v[194:197], v[52:55]
	v_mfma_f32_16x16x32_bf16 v[56:59], v[132:135], v[190:193], v[56:59]
	v_mfma_f32_16x16x32_bf16 v[56:59], v[136:139], v[194:197], v[56:59]
	v_mfma_f32_16x16x32_bf16 v[48:51], v[132:135], v[198:201], v[48:51]
	v_mfma_f32_16x16x32_bf16 v[48:51], v[136:139], v[202:205], v[48:51]
	v_mfma_f32_16x16x32_bf16 v[44:47], v[140:143], v[198:201], v[44:47]
	v_mfma_f32_16x16x32_bf16 v[44:47], v[154:157], v[202:205], v[44:47]
	v_mfma_f32_16x16x32_bf16 v[36:39], v[140:143], v[206:209], v[36:39]
	v_mfma_f32_16x16x32_bf16 v[36:39], v[154:157], v[210:213], v[36:39]
	v_mfma_f32_16x16x32_bf16 v[40:43], v[132:135], v[206:209], v[40:43]
	v_mfma_f32_16x16x32_bf16 v[40:43], v[136:139], v[210:213], v[40:43]
	s_setprio 0
	s_setprio 1
	s_add_u32 s45, s45, 0x100
	s_addc_u32 s47, s47, 0
	s_mov_b64 s[24:25], s[0:1]
	s_mov_b32 s26, s72
	s_nop 0
	v_mfma_f32_16x16x32_bf16 v[32:35], v[158:161], v[182:185], v[32:35]
	v_mfma_f32_16x16x32_bf16 v[32:35], v[170:173], v[186:189], v[32:35]
	v_mfma_f32_16x16x32_bf16 v[28:31], v[174:177], v[182:185], v[28:31]
	v_mfma_f32_16x16x32_bf16 v[28:31], v[178:181], v[186:189], v[28:31]
	v_mfma_f32_16x16x32_bf16 v[20:23], v[174:177], v[190:193], v[20:23]
	v_mfma_f32_16x16x32_bf16 v[20:23], v[178:181], v[194:197], v[20:23]
	v_mfma_f32_16x16x32_bf16 v[24:27], v[158:161], v[190:193], v[24:27]
	v_mfma_f32_16x16x32_bf16 v[24:27], v[170:173], v[194:197], v[24:27]
	v_mfma_f32_16x16x32_bf16 v[16:19], v[158:161], v[198:201], v[16:19]
	v_mfma_f32_16x16x32_bf16 v[16:19], v[170:173], v[202:205], v[16:19]
	v_mfma_f32_16x16x32_bf16 v[12:15], v[174:177], v[198:201], v[12:15]
	v_mfma_f32_16x16x32_bf16 v[12:15], v[178:181], v[202:205], v[12:15]
	v_mfma_f32_16x16x32_bf16 v[4:7], v[174:177], v[206:209], v[4:7]
	v_mfma_f32_16x16x32_bf16 v[4:7], v[178:181], v[210:213], v[4:7]
	v_mfma_f32_16x16x32_bf16 v[8:11], v[158:161], v[206:209], v[8:11]
	v_mfma_f32_16x16x32_bf16 v[8:11], v[170:173], v[210:213], v[8:11]
	s_barrier
	s_cmp_ge_i32 s72, s46
	s_cbranch_scc0 .LBB0_3627
	s_setprio 0
	s_and_b64 vcc, exec, s[50:51]
	s_cbranch_vccz .LBB0_3630
	s_barrier
